# K-loop MFMA blocks: mid-block priority flips and the redundant post-barrier lgkmcnt(0) removed (block-level setprio kept)
# speedup vs baseline: 1.0056x; 1.0056x over previous
; #define PG8_STAGE(bufoff, gbase, voff) do { _Pragma("unroll") for (int _i = 0; _i < 2; ++_i) \
;         __builtin_amdgcn_global_load_lds((const unsigned*)((const char*)(gbase) + (voff)[_i]), (LAS unsigned*)(lds + (bufoff) + ldsw + _i * 8192), 16, 0, 0); } while (0)
; #define PG8_LDA(dst, b, h) do { _Pragma("unroll") for (int m = 0; m < 4; ++m) _Pragma("unroll") for (int k = 0; k < 2; ++k) dst[m][k] = *(const LAS bf16x8*)(lds + PG8_SA(b, h) + aoff + m * 2048 + k * 1024); } while (0)
; #define PG8_LDB(dst, b, h) do { _Pragma("unroll") for (int n = 0; n < 2; ++n) _Pragma("unroll") for (int k = 0; k < 2; ++k) dst[n][k] = *(const LAS bf16x8*)(lds + PG8_SB(b, h) + boff + n * 2048 + k * 1024); } while (0)
; #define PG8_WAIT_V(n) asm volatile("s_waitcnt vmcnt(" #n ")" ::: "memory")
; #define PG8_WAIT_L(n) asm volatile("s_waitcnt lgkmcnt(" #n ")" ::: "memory")
; #define PG8_BAR __builtin_amdgcn_s_barrier()
; #define PG8_SCHED __builtin_amdgcn_sched_barrier(0)
; template <class Epi>
; __device__ __forceinline__ void gemm_phase(LAS unsigned char* lds, const Gemm g, const StaticOrder& S, const Epi& E, const int tid) {
;     ...
;             const bool last = (t == ntt - 2);
;             const bool s1 = Epi::TWO && (t >= nt), s2 = Epi::TWO && (t + 2 >= nt);
;             const char* a1 = (s1 ? cA2 + (size_t)(t - nt + 1) * kstep : cA + (size_t)(t + 1) * kstep);
;             const char* a2 = last ? nA : (s2 ? cA2 + (size_t)(t + 2 - nt) * kstep : cA + (size_t)(t + 2) * kstep);
;             const char* b2 = last ? nB : (s2 ? cB2 + (size_t)(t + 2 - nt) * kstep : cB + (size_t)(t + 2) * kstep);
;             const char* a3 = a2 + kstep; const char* b3 = b2 + kstep;
;             if constexpr (Epi::TWO) { if (t == nt) E.mid(acc, cur, wr, wc, fr, fq); }
;             if constexpr (SP2) {
;             PG8_LDB(B0, 0, 0); PG8_LDB(B1, 0, 1); PG8_SCHED; PG8_LDA(At, 0, 0); PG8_STAGE(PG8_SA(1, 1), a1 + hstep, voffA);
;             PG8_WAIT_V(8); PG8_WAIT_L(0); PG8_BAR; PG8_MMA(0, 0, At, B0); PG8_MMA(0, 1, At, B1); PG8_BAR; PG8_SCHED;
;             PG8_LDA(At, 0, 1); PG8_STAGE(PG8_SB(0, 0), b2, voffB); PG8_STAGE(PG8_SB(0, 1), b2 + bhs, voffB); PG8_STAGE(PG8_SA(0, 0), a2, voffA);
;             PG8_WAIT_V(8); PG8_WAIT_L(0); PG8_BAR; PG8_MMA(1, 0, At, B0); PG8_MMA(1, 1, At, B1); PG8_BAR; PG8_SCHED;
.LBB0_126:
	s_add_u32 s30, s28, 0xffe00080
	s_addc_u32 s31, s29, -1
	s_add_i32 s52, 0, 0x10000
	s_cmpk_eq_i32 s51, 0x7c
	s_cselect_b32 s35, s17, s31
	s_cselect_b32 s34, s27, s30
	s_cselect_b32 s31, s15, s50
	s_cselect_b32 s30, s33, s49
	s_add_i32 s54, 0, 0x14000
	v_add_u32_e32 v30, s52, v193
	v_add_u32_e32 v54, s54, v193
	ds_read_b128 v[18:21], v30
	ds_read_b128 v[22:25], v30 offset:1024
	ds_read_b128 v[26:29], v30 offset:2048
	ds_read_b128 v[30:33], v30 offset:3072
	ds_read_b128 v[42:45], v54
	ds_read_b128 v[46:49], v54 offset:1024
	ds_read_b128 v[50:53], v54 offset:2048
	ds_read_b128 v[54:57], v54 offset:3072
	v_lshl_add_u64 v[172:173], s[28:29], 0, v[180:181]
	s_add_i32 m0, s37, 0xc000
	ds_read_b128 v[182:185], v199
	global_load_lds_dwordx4 v[172:173], off
	ds_read_b128 v[186:189], v199 offset:1024
	ds_read_b128 v[212:215], v199 offset:2048
	v_lshl_add_u64 v[172:173], s[28:29], 0, v[178:179]
	s_add_i32 m0, s37, 0xe000
	s_nop 0
	global_load_lds_dwordx4 v[172:173], off
	ds_read_b128 v[216:219], v199 offset:3072
	ds_read_b128 v[220:223], v199 offset:4096
	ds_read_b128 v[224:227], v199 offset:5120
	ds_read_b128 v[228:231], v199 offset:6144
	ds_read_b128 v[232:235], v199 offset:7168
	s_waitcnt vmcnt(8)
	s_waitcnt lgkmcnt(0)
	s_barrier
	s_setprio 1
	v_mfma_f32_16x16x32_bf16 v[158:161], v[18:21], v[182:185], v[158:161]
	v_mfma_f32_16x16x32_bf16 v[154:157], v[26:29], v[182:185], v[154:157]
	v_mfma_f32_16x16x32_bf16 v[142:145], v[18:21], v[212:215], v[142:145]
	v_mfma_f32_16x16x32_bf16 v[138:141], v[26:29], v[212:215], v[138:141]
	v_mfma_f32_16x16x32_bf16 v[126:129], v[18:21], v[220:223], v[126:129]
	v_mfma_f32_16x16x32_bf16 v[122:125], v[26:29], v[220:223], v[122:125]
	v_mfma_f32_16x16x32_bf16 v[110:113], v[18:21], v[228:231], v[110:113]
	v_mfma_f32_16x16x32_bf16 v[106:109], v[26:29], v[228:231], v[106:109]
	v_mfma_f32_16x16x32_bf16 v[158:161], v[22:25], v[186:189], v[158:161]
	v_mfma_f32_16x16x32_bf16 v[154:157], v[30:33], v[186:189], v[154:157]
	v_mfma_f32_16x16x32_bf16 v[142:145], v[22:25], v[216:219], v[142:145]
	v_mfma_f32_16x16x32_bf16 v[138:141], v[30:33], v[216:219], v[138:141]
	v_mfma_f32_16x16x32_bf16 v[126:129], v[22:25], v[224:227], v[126:129]
	v_mfma_f32_16x16x32_bf16 v[122:125], v[30:33], v[224:227], v[122:125]
	v_mfma_f32_16x16x32_bf16 v[110:113], v[22:25], v[232:235], v[110:113]
	v_mfma_f32_16x16x32_bf16 v[106:109], v[30:33], v[232:235], v[106:109]
	v_mfma_f32_16x16x32_bf16 v[150:153], v[42:45], v[182:185], v[150:153]
	v_mfma_f32_16x16x32_bf16 v[146:149], v[50:53], v[182:185], v[146:149]
	v_mfma_f32_16x16x32_bf16 v[134:137], v[42:45], v[212:215], v[134:137]
	v_mfma_f32_16x16x32_bf16 v[130:133], v[50:53], v[212:215], v[130:133]
	v_mfma_f32_16x16x32_bf16 v[118:121], v[42:45], v[220:223], v[118:121]
	v_mfma_f32_16x16x32_bf16 v[114:117], v[50:53], v[220:223], v[114:117]
	v_mfma_f32_16x16x32_bf16 v[102:105], v[42:45], v[228:231], v[102:105]
	v_mfma_f32_16x16x32_bf16 v[98:101], v[50:53], v[228:231], v[98:101]
	v_mfma_f32_16x16x32_bf16 v[150:153], v[46:49], v[186:189], v[150:153]
	v_mfma_f32_16x16x32_bf16 v[146:149], v[54:57], v[186:189], v[146:149]
	v_mfma_f32_16x16x32_bf16 v[134:137], v[46:49], v[216:219], v[134:137]
	v_mfma_f32_16x16x32_bf16 v[130:133], v[54:57], v[216:219], v[130:133]
	v_mfma_f32_16x16x32_bf16 v[118:121], v[46:49], v[224:227], v[118:121]
	v_mfma_f32_16x16x32_bf16 v[114:117], v[54:57], v[224:227], v[114:117]
	v_mfma_f32_16x16x32_bf16 v[102:105], v[46:49], v[232:235], v[102:105]
	v_mfma_f32_16x16x32_bf16 v[98:101], v[54:57], v[232:235], v[98:101]
	s_setprio 0
	s_barrier
	s_add_i32 s52, s52, s36
	v_lshl_add_u64 v[172:173], s[30:31], 0, v[0:1]
	s_mov_b32 m0, s52
	ds_read_b128 v[182:185], v199 offset:16384
	global_load_lds_dwordx4 v[172:173], off
	ds_read_b128 v[186:189], v199 offset:17408
	ds_read_b128 v[212:215], v199 offset:18432
	s_add_i32 m0, s52, 0x2000
	s_add_u32 s52, s30, 0x20000
	v_lshl_add_u64 v[174:175], s[30:31], 0, v[166:167]
	s_addc_u32 s53, s31, 0
	s_add_i32 s54, s54, s36
	global_load_lds_dwordx4 v[174:175], off
	ds_read_b128 v[216:219], v199 offset:19456
	ds_read_b128 v[220:223], v199 offset:20480
	v_lshl_add_u64 v[176:177], s[52:53], 0, v[0:1]
	s_mov_b32 m0, s54
	v_lshl_add_u64 v[200:201], s[34:35], 0, v[164:165]
	global_load_lds_dwordx4 v[176:177], off
	ds_read_b128 v[224:227], v199 offset:21504
	ds_read_b128 v[228:231], v199 offset:22528
	v_lshl_add_u64 v[176:177], s[52:53], 0, v[166:167]
	s_add_i32 m0, s54, 0x2000
	s_nop 0
	global_load_lds_dwordx4 v[176:177], off
	ds_read_b128 v[232:235], v199 offset:23552
	v_lshl_add_u64 v[176:177], s[34:35], 0, v[162:163]
	s_mov_b32 m0, s37
	s_nop 0
	global_load_lds_dwordx4 v[176:177], off
	s_mov_b32 m0, s38
	s_nop 0
	global_load_lds_dwordx4 v[200:201], off
	s_waitcnt vmcnt(8)
	s_waitcnt lgkmcnt(0)
	s_barrier
; #define PG8_STAGE(bufoff, gbase, voff) do { _Pragma("unroll") for (int _i = 0; _i < 2; ++_i) \
;         __builtin_amdgcn_global_load_lds((const unsigned*)((const char*)(gbase) + (voff)[_i]), (LAS unsigned*)(lds + (bufoff) + ldsw + _i * 8192), 16, 0, 0); } while (0)
; #define PG8_LDA(dst, b, h) do { _Pragma("unroll") for (int m = 0; m < 4; ++m) _Pragma("unroll") for (int k = 0; k < 2; ++k) dst[m][k] = *(const LAS bf16x8*)(lds + PG8_SA(b, h) + aoff + m * 2048 + k * 1024); } while (0)
; #define PG8_LDB(dst, b, h) do { _Pragma("unroll") for (int n = 0; n < 2; ++n) _Pragma("unroll") for (int k = 0; k < 2; ++k) dst[n][k] = *(const LAS bf16x8*)(lds + PG8_SB(b, h) + boff + n * 2048 + k * 1024); } while (0)
; #define PG8_MMA(ai, bj, At, Bt) do { __builtin_amdgcn_s_setprio(1); _Pragma("unroll") for (int m = 0; m < 4; ++m) _Pragma("unroll") for (int n = 0; n < 2; ++n) _Pragma("unroll") for (int k = 0; k < 2; ++k) \
;         acc[ai][bj][m][n] = __builtin_amdgcn_mfma_f32_16x16x32_bf16(Bt[n][k], At[m][k], acc[ai][bj][m][n], 0, 0, 0); __builtin_amdgcn_s_setprio(0); } while (0)
; #define PG8_WAIT_V(n) asm volatile("s_waitcnt vmcnt(" #n ")" ::: "memory")
; #define PG8_WAIT_L(n) asm volatile("s_waitcnt lgkmcnt(" #n ")" ::: "memory")
; #define PG8_BAR __builtin_amdgcn_s_barrier()
; #define PG8_SCHED __builtin_amdgcn_sched_barrier(0)
; template <class Epi>
; __device__ __forceinline__ void gemm_phase(LAS unsigned char* lds, const Gemm g, const StaticOrder& S, const Epi& E, const int tid) {
;     ...
;             PG8_WAIT_V(8); PG8_WAIT_L(0); PG8_BAR; PG8_MMA(1, 0, At, B0); PG8_MMA(1, 1, At, B1); PG8_BAR; PG8_SCHED;
;             PG8_LDB(B0, 1, 0); PG8_LDB(B1, 1, 1); PG8_SCHED; PG8_LDA(At, 1, 0); PG8_STAGE(PG8_SA(0, 1), a2 + hstep, voffA);
;             PG8_WAIT_V(8); PG8_WAIT_L(0); PG8_BAR; PG8_MMA(0, 0, At, B0); PG8_MMA(0, 1, At, B1); PG8_BAR; PG8_SCHED;
	s_setprio 1
	v_mfma_f32_16x16x32_bf16 v[94:97], v[18:21], v[182:185], v[94:97]
	v_mfma_f32_16x16x32_bf16 v[90:93], v[26:29], v[182:185], v[90:93]
	v_mfma_f32_16x16x32_bf16 v[78:81], v[18:21], v[212:215], v[78:81]
	v_mfma_f32_16x16x32_bf16 v[74:77], v[26:29], v[212:215], v[74:77]
	v_mfma_f32_16x16x32_bf16 v[62:65], v[18:21], v[220:223], v[62:65]
	v_mfma_f32_16x16x32_bf16 v[58:61], v[26:29], v[220:223], v[58:61]
	v_mfma_f32_16x16x32_bf16 v[14:17], v[18:21], v[228:231], v[14:17]
	v_mfma_f32_16x16x32_bf16 v[10:13], v[26:29], v[228:231], v[10:13]
	v_mfma_f32_16x16x32_bf16 v[94:97], v[22:25], v[186:189], v[94:97]
	v_mfma_f32_16x16x32_bf16 v[90:93], v[30:33], v[186:189], v[90:93]
	v_mfma_f32_16x16x32_bf16 v[78:81], v[22:25], v[216:219], v[78:81]
	v_mfma_f32_16x16x32_bf16 v[74:77], v[30:33], v[216:219], v[74:77]
	v_mfma_f32_16x16x32_bf16 v[62:65], v[22:25], v[224:227], v[62:65]
	v_mfma_f32_16x16x32_bf16 v[58:61], v[30:33], v[224:227], v[58:61]
	v_mfma_f32_16x16x32_bf16 v[14:17], v[22:25], v[232:235], v[14:17]
	v_mfma_f32_16x16x32_bf16 v[10:13], v[30:33], v[232:235], v[10:13]
	v_mfma_f32_16x16x32_bf16 v[38:41], v[42:45], v[220:223], v[38:41]
	v_mfma_f32_16x16x32_bf16 v[34:37], v[50:53], v[220:223], v[34:37]
	v_mfma_f32_16x16x32_bf16 v[6:9], v[42:45], v[228:231], v[6:9]
	v_mfma_f32_16x16x32_bf16 v[2:5], v[50:53], v[228:231], v[2:5]
	v_mfma_f32_16x16x32_bf16 v[18:21], v[42:45], v[182:185], v[86:89]
	v_mfma_f32_16x16x32_bf16 v[22:25], v[50:53], v[182:185], v[82:85]
	v_mfma_f32_16x16x32_bf16 v[26:29], v[42:45], v[212:215], v[70:73]
	v_mfma_f32_16x16x32_bf16 v[30:33], v[50:53], v[212:215], v[66:69]
	v_mfma_f32_16x16x32_bf16 v[38:41], v[46:49], v[224:227], v[38:41]
	v_mfma_f32_16x16x32_bf16 v[34:37], v[54:57], v[224:227], v[34:37]
	v_mfma_f32_16x16x32_bf16 v[6:9], v[46:49], v[232:235], v[6:9]
	v_mfma_f32_16x16x32_bf16 v[2:5], v[54:57], v[232:235], v[2:5]
	v_mfma_f32_16x16x32_bf16 v[18:21], v[46:49], v[186:189], v[18:21]
	v_mfma_f32_16x16x32_bf16 v[22:25], v[54:57], v[186:189], v[22:25]
	v_mfma_f32_16x16x32_bf16 v[26:29], v[46:49], v[216:219], v[26:29]
	v_mfma_f32_16x16x32_bf16 v[30:33], v[54:57], v[216:219], v[30:33]
	s_setprio 0
	s_barrier
	s_add_i32 s52, 0, 0x18000
	s_add_i32 s53, 0, 0x1c000
	v_add_u32_e32 v54, s52, v193
	v_add_u32_e32 v66, s53, v193
	ds_read_b128 v[42:45], v54
	ds_read_b128 v[46:49], v54 offset:1024
	ds_read_b128 v[50:53], v54 offset:2048
	ds_read_b128 v[54:57], v54 offset:3072
	ds_read_b128 v[182:185], v66
	ds_read_b128 v[186:189], v66 offset:1024
	ds_read_b128 v[212:215], v66 offset:2048
	ds_read_b128 v[216:219], v66 offset:3072
	s_add_u32 s34, s34, 0x200000
	s_addc_u32 s35, s35, 0
	s_mov_b32 m0, s39
	v_lshl_add_u64 v[236:237], s[34:35], 0, v[162:163]
	ds_read_b128 v[66:69], v199 offset:32768
	global_load_lds_dwordx4 v[236:237], off
	ds_read_b128 v[70:73], v199 offset:33792
	ds_read_b128 v[82:85], v199 offset:34816
	v_lshl_add_u64 v[236:237], s[34:35], 0, v[164:165]
	s_mov_b32 m0, s44
	s_nop 0
	global_load_lds_dwordx4 v[236:237], off
	ds_read_b128 v[86:89], v199 offset:35840
	ds_read_b128 v[220:223], v199 offset:36864
	ds_read_b128 v[224:227], v199 offset:37888
	ds_read_b128 v[228:231], v199 offset:38912
	ds_read_b128 v[232:235], v199 offset:39936
	s_waitcnt vmcnt(8)
	s_waitcnt lgkmcnt(0)
	s_barrier
	s_setprio 1
	v_mfma_f32_16x16x32_bf16 v[158:161], v[42:45], v[66:69], v[158:161]
	v_mfma_f32_16x16x32_bf16 v[154:157], v[50:53], v[66:69], v[154:157]
	v_mfma_f32_16x16x32_bf16 v[142:145], v[42:45], v[82:85], v[142:145]
	v_mfma_f32_16x16x32_bf16 v[138:141], v[50:53], v[82:85], v[138:141]
	v_mfma_f32_16x16x32_bf16 v[126:129], v[42:45], v[220:223], v[126:129]
	v_mfma_f32_16x16x32_bf16 v[122:125], v[50:53], v[220:223], v[122:125]
	v_mfma_f32_16x16x32_bf16 v[110:113], v[42:45], v[228:231], v[110:113]
	v_mfma_f32_16x16x32_bf16 v[106:109], v[50:53], v[228:231], v[106:109]
	v_mfma_f32_16x16x32_bf16 v[158:161], v[46:49], v[70:73], v[158:161]
	v_mfma_f32_16x16x32_bf16 v[154:157], v[54:57], v[70:73], v[154:157]
	v_mfma_f32_16x16x32_bf16 v[142:145], v[46:49], v[86:89], v[142:145]
	v_mfma_f32_16x16x32_bf16 v[138:141], v[54:57], v[86:89], v[138:141]
	v_mfma_f32_16x16x32_bf16 v[126:129], v[46:49], v[224:227], v[126:129]
	v_mfma_f32_16x16x32_bf16 v[122:125], v[54:57], v[224:227], v[122:125]
	v_mfma_f32_16x16x32_bf16 v[110:113], v[46:49], v[232:235], v[110:113]
	v_mfma_f32_16x16x32_bf16 v[106:109], v[54:57], v[232:235], v[106:109]
	v_mfma_f32_16x16x32_bf16 v[150:153], v[182:185], v[66:69], v[150:153]
	v_mfma_f32_16x16x32_bf16 v[66:69], v[212:215], v[66:69], v[146:149]
	v_mfma_f32_16x16x32_bf16 v[146:149], v[216:219], v[70:73], v[66:69]
	v_mfma_f32_16x16x32_bf16 v[66:69], v[182:185], v[82:85], v[134:137]
	v_mfma_f32_16x16x32_bf16 v[134:137], v[186:189], v[86:89], v[66:69]
	v_mfma_f32_16x16x32_bf16 v[66:69], v[212:215], v[82:85], v[130:133]
	v_mfma_f32_16x16x32_bf16 v[130:133], v[216:219], v[86:89], v[66:69]
	v_mfma_f32_16x16x32_bf16 v[66:69], v[182:185], v[220:223], v[118:121]
	v_mfma_f32_16x16x32_bf16 v[118:121], v[186:189], v[224:227], v[66:69]
	v_mfma_f32_16x16x32_bf16 v[66:69], v[212:215], v[220:223], v[114:117]
	v_mfma_f32_16x16x32_bf16 v[114:117], v[216:219], v[224:227], v[66:69]
	v_mfma_f32_16x16x32_bf16 v[66:69], v[182:185], v[228:231], v[102:105]
	v_mfma_f32_16x16x32_bf16 v[102:105], v[186:189], v[232:235], v[66:69]
	v_mfma_f32_16x16x32_bf16 v[66:69], v[212:215], v[228:231], v[98:101]
	v_mfma_f32_16x16x32_bf16 v[150:153], v[186:189], v[70:73], v[150:153]
	v_mfma_f32_16x16x32_bf16 v[98:101], v[216:219], v[232:235], v[66:69]
	s_setprio 0
	s_barrier
; #define PG8_STAGE(bufoff, gbase, voff) do { _Pragma("unroll") for (int _i = 0; _i < 2; ++_i) \
;         __builtin_amdgcn_global_load_lds((const unsigned*)((const char*)(gbase) + (voff)[_i]), (LAS unsigned*)(lds + (bufoff) + ldsw + _i * 8192), 16, 0, 0); } while (0)
; #define PG8_LDA(dst, b, h) do { _Pragma("unroll") for (int m = 0; m < 4; ++m) _Pragma("unroll") for (int k = 0; k < 2; ++k) dst[m][k] = *(const LAS bf16x8*)(lds + PG8_SA(b, h) + aoff + m * 2048 + k * 1024); } while (0)
; #define PG8_MMA(ai, bj, At, Bt) do { __builtin_amdgcn_s_setprio(1); _Pragma("unroll") for (int m = 0; m < 4; ++m) _Pragma("unroll") for (int n = 0; n < 2; ++n) _Pragma("unroll") for (int k = 0; k < 2; ++k) \
;         acc[ai][bj][m][n] = __builtin_amdgcn_mfma_f32_16x16x32_bf16(Bt[n][k], At[m][k], acc[ai][bj][m][n], 0, 0, 0); __builtin_amdgcn_s_setprio(0); } while (0)
; #define PG8_WAIT_V(n) asm volatile("s_waitcnt vmcnt(" #n ")" ::: "memory")
; #define PG8_WAIT_L(n) asm volatile("s_waitcnt lgkmcnt(" #n ")" ::: "memory")
; #define PG8_BAR __builtin_amdgcn_s_barrier()
; #define PG8_SCHED __builtin_amdgcn_sched_barrier(0)
; template <class Epi>
; __device__ __forceinline__ void gemm_phase(LAS unsigned char* lds, const Gemm g, const StaticOrder& S, const Epi& E, const int tid) {
;     ...
;         for (int t = 0; t < ntt; t += 2) {
;     ...
;             PG8_LDA(At, 1, 1); PG8_STAGE(PG8_SB(1, 0), b3, voffB); PG8_STAGE(PG8_SB(1, 1), b3 + bhs, voffB); PG8_STAGE(PG8_SA(1, 0), a3, voffA);
;             PG8_WAIT_V(8); PG8_WAIT_L(0); PG8_BAR; PG8_MMA(1, 0, At, B0); PG8_MMA(1, 1, At, B1); PG8_BAR; PG8_SCHED;
	s_add_i32 s34, s52, s36
	v_lshl_add_u64 v[82:83], v[172:173], 0, s[70:71]
	s_mov_b32 m0, s34
	s_nop 0
	ds_read_b128 v[66:69], v199 offset:49152
	global_load_lds_dwordx4 v[82:83], off
	ds_read_b128 v[70:73], v199 offset:50176
	ds_read_b128 v[220:223], v199 offset:51200
	s_add_i32 m0, s34, 0x2000
	s_add_u32 s30, s30, 0x20080
	v_lshl_add_u64 v[82:83], v[174:175], 0, s[70:71]
	s_addc_u32 s31, s31, 0
	s_add_i32 s34, s53, s36
	global_load_lds_dwordx4 v[82:83], off
	ds_read_b128 v[224:227], v199 offset:52224
	ds_read_b128 v[228:231], v199 offset:53248
	v_lshl_add_u64 v[82:83], s[30:31], 0, v[0:1]
	s_mov_b32 m0, s34
	s_nop 0
	global_load_lds_dwordx4 v[82:83], off
	ds_read_b128 v[232:235], v199 offset:54272
	ds_read_b128 v[236:239], v199 offset:55296
	v_lshl_add_u64 v[82:83], s[30:31], 0, v[166:167]
	s_add_i32 m0, s34, 0x2000
	s_nop 0
	global_load_lds_dwordx4 v[82:83], off
	ds_read_b128 v[240:243], v199 offset:56320
	v_lshl_add_u64 v[82:83], v[176:177], 0, s[70:71]
	s_mov_b32 m0, s45
	s_nop 0
	global_load_lds_dwordx4 v[82:83], off
	v_lshl_add_u64 v[82:83], v[200:201], 0, s[70:71]
	s_mov_b32 m0, s46
	s_nop 0
	global_load_lds_dwordx4 v[82:83], off
	s_waitcnt vmcnt(8)
	s_waitcnt lgkmcnt(0)
	s_barrier
	s_setprio 1
	v_mfma_f32_16x16x32_bf16 v[82:85], v[42:45], v[66:69], v[94:97]
	v_mfma_f32_16x16x32_bf16 v[94:97], v[46:49], v[70:73], v[82:85]
	v_mfma_f32_16x16x32_bf16 v[82:85], v[50:53], v[66:69], v[90:93]
	v_mfma_f32_16x16x32_bf16 v[78:81], v[42:45], v[220:223], v[78:81]
	v_mfma_f32_16x16x32_bf16 v[74:77], v[50:53], v[220:223], v[74:77]
	v_mfma_f32_16x16x32_bf16 v[62:65], v[42:45], v[228:231], v[62:65]
	v_mfma_f32_16x16x32_bf16 v[58:61], v[50:53], v[228:231], v[58:61]
	v_mfma_f32_16x16x32_bf16 v[14:17], v[42:45], v[236:239], v[14:17]
	v_mfma_f32_16x16x32_bf16 v[10:13], v[50:53], v[236:239], v[10:13]
	v_mfma_f32_16x16x32_bf16 v[90:93], v[54:57], v[70:73], v[82:85]
	v_mfma_f32_16x16x32_bf16 v[78:81], v[46:49], v[224:227], v[78:81]
	v_mfma_f32_16x16x32_bf16 v[74:77], v[54:57], v[224:227], v[74:77]
	v_mfma_f32_16x16x32_bf16 v[62:65], v[46:49], v[232:235], v[62:65]
	v_mfma_f32_16x16x32_bf16 v[58:61], v[54:57], v[232:235], v[58:61]
	v_mfma_f32_16x16x32_bf16 v[14:17], v[46:49], v[240:243], v[14:17]
	v_mfma_f32_16x16x32_bf16 v[10:13], v[54:57], v[240:243], v[10:13]
	v_mfma_f32_16x16x32_bf16 v[18:21], v[182:185], v[66:69], v[18:21]
	v_mfma_f32_16x16x32_bf16 v[86:89], v[186:189], v[70:73], v[18:21]
	v_mfma_f32_16x16x32_bf16 v[18:21], v[212:215], v[66:69], v[22:25]
	v_mfma_f32_16x16x32_bf16 v[82:85], v[216:219], v[70:73], v[18:21]
	v_mfma_f32_16x16x32_bf16 v[18:21], v[182:185], v[220:223], v[26:29]
	v_mfma_f32_16x16x32_bf16 v[70:73], v[186:189], v[224:227], v[18:21]
	v_mfma_f32_16x16x32_bf16 v[18:21], v[212:215], v[220:223], v[30:33]
	v_mfma_f32_16x16x32_bf16 v[66:69], v[216:219], v[224:227], v[18:21]
	v_mfma_f32_16x16x32_bf16 v[18:21], v[182:185], v[228:231], v[38:41]
	v_mfma_f32_16x16x32_bf16 v[38:41], v[186:189], v[232:235], v[18:21]
	v_mfma_f32_16x16x32_bf16 v[18:21], v[212:215], v[228:231], v[34:37]
	v_mfma_f32_16x16x32_bf16 v[6:9], v[182:185], v[236:239], v[6:9]
	v_mfma_f32_16x16x32_bf16 v[2:5], v[212:215], v[236:239], v[2:5]
	v_mfma_f32_16x16x32_bf16 v[34:37], v[216:219], v[232:235], v[18:21]
	v_mfma_f32_16x16x32_bf16 v[6:9], v[186:189], v[240:243], v[6:9]
	v_mfma_f32_16x16x32_bf16 v[2:5], v[216:219], v[240:243], v[2:5]
	s_setprio 0
	s_barrier
	s_add_i32 s51, s51, 2
	s_add_u32 s49, s49, 0x100
	s_addc_u32 s50, s50, 0
	s_add_u32 s28, s28, 0x100
	s_addc_u32 s29, s29, 0
	s_cmpk_gt_u32 s51, 0x7d
	s_cbranch_scc0 .LBB0_126
	s_and_b64 vcc, exec, s[12:13]
	s_cbranch_vccz .LBB0_129
	s_barrier

; #define PG8_STAGE(bufoff, gbase, voff) do { _Pragma("unroll") for (int _i = 0; _i < 2; ++_i) \
;         __builtin_amdgcn_global_load_lds((const unsigned*)((const char*)(gbase) + (voff)[_i]), (LAS unsigned*)(lds + (bufoff) + ldsw + _i * 8192), 16, 0, 0); } while (0)
; #define PG8_LDA(dst, b, h) do { _Pragma("unroll") for (int m = 0; m < 4; ++m) _Pragma("unroll") for (int k = 0; k < 2; ++k) dst[m][k] = *(const LAS bf16x8*)(lds + PG8_SA(b, h) + aoff + m * 2048 + k * 1024); } while (0)
; #define PG8_LDB(dst, b, h) do { _Pragma("unroll") for (int n = 0; n < 2; ++n) _Pragma("unroll") for (int k = 0; k < 2; ++k) dst[n][k] = *(const LAS bf16x8*)(lds + PG8_SB(b, h) + boff + n * 2048 + k * 1024); } while (0)
; #define PG8_WAIT_V(n) asm volatile("s_waitcnt vmcnt(" #n ")" ::: "memory")
; #define PG8_WAIT_L(n) asm volatile("s_waitcnt lgkmcnt(" #n ")" ::: "memory")
; #define PG8_BAR __builtin_amdgcn_s_barrier()
; #define PG8_SCHED __builtin_amdgcn_sched_barrier(0)
; template <class Epi>
; __device__ __forceinline__ void gemm_phase(LAS unsigned char* lds, const Gemm g, const StaticOrder& S, const Epi& E, const int tid) {
;     ...
;             const bool last = (t == ntt - 2);
;             const bool s1 = Epi::TWO && (t >= nt), s2 = Epi::TWO && (t + 2 >= nt);
;             const char* a1 = (s1 ? cA2 + (size_t)(t - nt + 1) * kstep : cA + (size_t)(t + 1) * kstep);
;             const char* a2 = last ? nA : (s2 ? cA2 + (size_t)(t + 2 - nt) * kstep : cA + (size_t)(t + 2) * kstep);
;             const char* b2 = last ? nB : (s2 ? cB2 + (size_t)(t + 2 - nt) * kstep : cB + (size_t)(t + 2) * kstep);
;             const char* a3 = a2 + kstep; const char* b3 = b2 + kstep;
;             if constexpr (Epi::TWO) { if (t == nt) E.mid(acc, cur, wr, wc, fr, fq); }
;             if constexpr (SP2) {
;             PG8_LDB(B0, 0, 0); PG8_LDB(B1, 0, 1); PG8_SCHED; PG8_LDA(At, 0, 0); PG8_STAGE(PG8_SA(1, 1), a1 + hstep, voffA);
;             PG8_WAIT_V(8); PG8_WAIT_L(0); PG8_BAR; PG8_MMA(0, 0, At, B0); PG8_MMA(0, 1, At, B1); PG8_BAR; PG8_SCHED;
;             PG8_LDA(At, 0, 1); PG8_STAGE(PG8_SB(0, 0), b2, voffB); PG8_STAGE(PG8_SB(0, 1), b2 + bhs, voffB); PG8_STAGE(PG8_SA(0, 0), a2, voffA);
;             PG8_WAIT_V(8); PG8_WAIT_L(0); PG8_BAR; PG8_MMA(1, 0, At, B0); PG8_MMA(1, 1, At, B1); PG8_BAR; PG8_SCHED;
.LBB0_173:
	s_add_u32 s28, s26, 0xfff80080
	s_addc_u32 s29, s27, -1
	s_add_i32 s47, 0, 0x10000
	s_cmp_eq_u32 s46, 28
	s_cselect_b32 s31, s17, s29
	s_cselect_b32 s30, s42, s28
	v_add_u32_e32 v142, s47, v149
	s_cselect_b32 s29, s15, s45
	s_cselect_b32 s28, s43, s44
	s_add_i32 s50, 0, 0x14000
	ds_read_b128 v[156:159], v142
	ds_read_b128 v[160:163], v142 offset:1024
	ds_read_b128 v[164:167], v142 offset:2048
	ds_read_b128 v[178:181], v142 offset:3072
	v_add_u32_e32 v142, s50, v149
	ds_read_b128 v[182:185], v142
	ds_read_b128 v[186:189], v142 offset:1024
	ds_read_b128 v[190:193], v142 offset:2048
	ds_read_b128 v[194:197], v142 offset:3072
	v_lshl_add_u64 v[142:143], s[26:27], 0, v[140:141]
	s_add_i32 m0, s2, 0xc000
	ds_read_b128 v[198:201], v154
	global_load_lds_dwordx4 v[142:143], off
	ds_read_b128 v[212:215], v154 offset:1024
	ds_read_b128 v[216:219], v154 offset:2048
	v_lshl_add_u64 v[142:143], s[26:27], 0, v[138:139]
	s_add_i32 m0, s2, 0xe000
	s_nop 0
	global_load_lds_dwordx4 v[142:143], off
	ds_read_b128 v[220:223], v154 offset:3072
	ds_read_b128 v[224:227], v154 offset:4096
	ds_read_b128 v[228:231], v154 offset:5120
	ds_read_b128 v[232:235], v154 offset:6144
	ds_read_b128 v[236:239], v154 offset:7168
	s_waitcnt vmcnt(8)
	s_waitcnt lgkmcnt(0)
	s_barrier
	s_setprio 1
	v_mfma_f32_16x16x32_bf16 v[126:129], v[156:159], v[198:201], v[126:129]
	v_mfma_f32_16x16x32_bf16 v[122:125], v[164:167], v[198:201], v[122:125]
	v_mfma_f32_16x16x32_bf16 v[110:113], v[156:159], v[216:219], v[110:113]
	v_mfma_f32_16x16x32_bf16 v[106:109], v[164:167], v[216:219], v[106:109]
	v_mfma_f32_16x16x32_bf16 v[94:97], v[156:159], v[224:227], v[94:97]
	v_mfma_f32_16x16x32_bf16 v[90:93], v[164:167], v[224:227], v[90:93]
	v_mfma_f32_16x16x32_bf16 v[78:81], v[156:159], v[232:235], v[78:81]
	v_mfma_f32_16x16x32_bf16 v[74:77], v[164:167], v[232:235], v[74:77]
	v_mfma_f32_16x16x32_bf16 v[126:129], v[160:163], v[212:215], v[126:129]
	v_mfma_f32_16x16x32_bf16 v[122:125], v[178:181], v[212:215], v[122:125]
	v_mfma_f32_16x16x32_bf16 v[110:113], v[160:163], v[220:223], v[110:113]
	v_mfma_f32_16x16x32_bf16 v[106:109], v[178:181], v[220:223], v[106:109]
	v_mfma_f32_16x16x32_bf16 v[94:97], v[160:163], v[228:231], v[94:97]
	v_mfma_f32_16x16x32_bf16 v[90:93], v[178:181], v[228:231], v[90:93]
	v_mfma_f32_16x16x32_bf16 v[78:81], v[160:163], v[236:239], v[78:81]
	v_mfma_f32_16x16x32_bf16 v[74:77], v[178:181], v[236:239], v[74:77]
	v_mfma_f32_16x16x32_bf16 v[118:121], v[182:185], v[198:201], v[118:121]
	v_mfma_f32_16x16x32_bf16 v[114:117], v[190:193], v[198:201], v[114:117]
	v_mfma_f32_16x16x32_bf16 v[102:105], v[182:185], v[216:219], v[102:105]
	v_mfma_f32_16x16x32_bf16 v[98:101], v[190:193], v[216:219], v[98:101]
	v_mfma_f32_16x16x32_bf16 v[86:89], v[182:185], v[224:227], v[86:89]
	v_mfma_f32_16x16x32_bf16 v[82:85], v[190:193], v[224:227], v[82:85]
	v_mfma_f32_16x16x32_bf16 v[70:73], v[182:185], v[232:235], v[70:73]
	v_mfma_f32_16x16x32_bf16 v[66:69], v[190:193], v[232:235], v[66:69]
	v_mfma_f32_16x16x32_bf16 v[118:121], v[186:189], v[212:215], v[118:121]
	v_mfma_f32_16x16x32_bf16 v[114:117], v[194:197], v[212:215], v[114:117]
	v_mfma_f32_16x16x32_bf16 v[102:105], v[186:189], v[220:223], v[102:105]
	v_mfma_f32_16x16x32_bf16 v[98:101], v[194:197], v[220:223], v[98:101]
	v_mfma_f32_16x16x32_bf16 v[86:89], v[186:189], v[228:231], v[86:89]
	v_mfma_f32_16x16x32_bf16 v[82:85], v[194:197], v[228:231], v[82:85]
	v_mfma_f32_16x16x32_bf16 v[70:73], v[186:189], v[236:239], v[70:73]
	v_mfma_f32_16x16x32_bf16 v[66:69], v[194:197], v[236:239], v[66:69]
	s_setprio 0
	s_barrier
	s_add_i32 s47, s47, s34
	v_lshl_add_u64 v[142:143], s[28:29], 0, v[0:1]
	s_mov_b32 m0, s47
	ds_read_b128 v[198:201], v154 offset:16384
	global_load_lds_dwordx4 v[142:143], off
	ds_read_b128 v[212:215], v154 offset:17408
	ds_read_b128 v[216:219], v154 offset:18432
	s_add_i32 m0, s47, 0x2000
	s_add_u32 s48, s28, 0x8000
	v_lshl_add_u64 v[168:169], s[28:29], 0, v[134:135]
	s_addc_u32 s49, s29, 0
	s_add_i32 s47, s50, s34
	global_load_lds_dwordx4 v[168:169], off
	ds_read_b128 v[220:223], v154 offset:19456
	ds_read_b128 v[224:227], v154 offset:20480
	v_lshl_add_u64 v[172:173], s[48:49], 0, v[0:1]
	s_mov_b32 m0, s47
	v_lshl_add_u64 v[174:175], s[30:31], 0, v[132:133]
	global_load_lds_dwordx4 v[172:173], off
	ds_read_b128 v[228:231], v154 offset:21504
	ds_read_b128 v[232:235], v154 offset:22528
	v_lshl_add_u64 v[172:173], s[48:49], 0, v[134:135]
	s_add_i32 m0, s47, 0x2000
	s_nop 0
	global_load_lds_dwordx4 v[172:173], off
	ds_read_b128 v[236:239], v154 offset:23552
	v_lshl_add_u64 v[172:173], s[30:31], 0, v[130:131]
	s_mov_b32 m0, s2
	s_nop 0
	global_load_lds_dwordx4 v[172:173], off
	s_mov_b32 m0, s25
	s_nop 0
	global_load_lds_dwordx4 v[174:175], off
	s_waitcnt vmcnt(8)
	s_waitcnt lgkmcnt(0)
	s_barrier
; #define PG8_STAGE(bufoff, gbase, voff) do { _Pragma("unroll") for (int _i = 0; _i < 2; ++_i) \
;         __builtin_amdgcn_global_load_lds((const unsigned*)((const char*)(gbase) + (voff)[_i]), (LAS unsigned*)(lds + (bufoff) + ldsw + _i * 8192), 16, 0, 0); } while (0)
; #define PG8_LDA(dst, b, h) do { _Pragma("unroll") for (int m = 0; m < 4; ++m) _Pragma("unroll") for (int k = 0; k < 2; ++k) dst[m][k] = *(const LAS bf16x8*)(lds + PG8_SA(b, h) + aoff + m * 2048 + k * 1024); } while (0)
; #define PG8_LDB(dst, b, h) do { _Pragma("unroll") for (int n = 0; n < 2; ++n) _Pragma("unroll") for (int k = 0; k < 2; ++k) dst[n][k] = *(const LAS bf16x8*)(lds + PG8_SB(b, h) + boff + n * 2048 + k * 1024); } while (0)
; #define PG8_MMA(ai, bj, At, Bt) do { __builtin_amdgcn_s_setprio(1); _Pragma("unroll") for (int m = 0; m < 4; ++m) _Pragma("unroll") for (int n = 0; n < 2; ++n) _Pragma("unroll") for (int k = 0; k < 2; ++k) \
;         acc[ai][bj][m][n] = __builtin_amdgcn_mfma_f32_16x16x32_bf16(Bt[n][k], At[m][k], acc[ai][bj][m][n], 0, 0, 0); __builtin_amdgcn_s_setprio(0); } while (0)
; #define PG8_WAIT_V(n) asm volatile("s_waitcnt vmcnt(" #n ")" ::: "memory")
; #define PG8_WAIT_L(n) asm volatile("s_waitcnt lgkmcnt(" #n ")" ::: "memory")
; #define PG8_BAR __builtin_amdgcn_s_barrier()
; #define PG8_SCHED __builtin_amdgcn_sched_barrier(0)
; template <class Epi>
; __device__ __forceinline__ void gemm_phase(LAS unsigned char* lds, const Gemm g, const StaticOrder& S, const Epi& E, const int tid) {
;     ...
;             PG8_WAIT_V(8); PG8_WAIT_L(0); PG8_BAR; PG8_MMA(1, 0, At, B0); PG8_MMA(1, 1, At, B1); PG8_BAR; PG8_SCHED;
;             PG8_LDB(B0, 1, 0); PG8_LDB(B1, 1, 1); PG8_SCHED; PG8_LDA(At, 1, 0); PG8_STAGE(PG8_SA(0, 1), a2 + hstep, voffA);
;             PG8_WAIT_V(8); PG8_WAIT_L(0); PG8_BAR; PG8_MMA(0, 0, At, B0); PG8_MMA(0, 1, At, B1); PG8_BAR; PG8_SCHED;
	s_setprio 1
	v_mfma_f32_16x16x32_bf16 v[62:65], v[156:159], v[198:201], v[62:65]
	v_mfma_f32_16x16x32_bf16 v[58:61], v[164:167], v[198:201], v[58:61]
	v_mfma_f32_16x16x32_bf16 v[46:49], v[156:159], v[216:219], v[46:49]
	v_mfma_f32_16x16x32_bf16 v[42:45], v[164:167], v[216:219], v[42:45]
	v_mfma_f32_16x16x32_bf16 v[30:33], v[156:159], v[224:227], v[30:33]
	v_mfma_f32_16x16x32_bf16 v[26:29], v[164:167], v[224:227], v[26:29]
	v_mfma_f32_16x16x32_bf16 v[14:17], v[156:159], v[232:235], v[14:17]
	v_mfma_f32_16x16x32_bf16 v[10:13], v[164:167], v[232:235], v[10:13]
	v_mfma_f32_16x16x32_bf16 v[62:65], v[160:163], v[212:215], v[62:65]
	v_mfma_f32_16x16x32_bf16 v[58:61], v[178:181], v[212:215], v[58:61]
	v_mfma_f32_16x16x32_bf16 v[46:49], v[160:163], v[220:223], v[46:49]
	v_mfma_f32_16x16x32_bf16 v[42:45], v[178:181], v[220:223], v[42:45]
	v_mfma_f32_16x16x32_bf16 v[30:33], v[160:163], v[228:231], v[30:33]
	v_mfma_f32_16x16x32_bf16 v[26:29], v[178:181], v[228:231], v[26:29]
	v_mfma_f32_16x16x32_bf16 v[14:17], v[160:163], v[236:239], v[14:17]
	v_mfma_f32_16x16x32_bf16 v[10:13], v[178:181], v[236:239], v[10:13]
	v_mfma_f32_16x16x32_bf16 v[54:57], v[182:185], v[198:201], v[54:57]
	v_mfma_f32_16x16x32_bf16 v[50:53], v[190:193], v[198:201], v[50:53]
	v_mfma_f32_16x16x32_bf16 v[38:41], v[182:185], v[216:219], v[38:41]
	v_mfma_f32_16x16x32_bf16 v[34:37], v[190:193], v[216:219], v[34:37]
	v_mfma_f32_16x16x32_bf16 v[22:25], v[182:185], v[224:227], v[22:25]
	v_mfma_f32_16x16x32_bf16 v[18:21], v[190:193], v[224:227], v[18:21]
	v_mfma_f32_16x16x32_bf16 v[6:9], v[182:185], v[232:235], v[6:9]
	v_mfma_f32_16x16x32_bf16 v[2:5], v[190:193], v[232:235], v[2:5]
	v_mfma_f32_16x16x32_bf16 v[54:57], v[186:189], v[212:215], v[54:57]
	v_mfma_f32_16x16x32_bf16 v[50:53], v[194:197], v[212:215], v[50:53]
	v_mfma_f32_16x16x32_bf16 v[38:41], v[186:189], v[220:223], v[38:41]
	v_mfma_f32_16x16x32_bf16 v[34:37], v[194:197], v[220:223], v[34:37]
	v_mfma_f32_16x16x32_bf16 v[22:25], v[186:189], v[228:231], v[22:25]
	v_mfma_f32_16x16x32_bf16 v[18:21], v[194:197], v[228:231], v[18:21]
	v_mfma_f32_16x16x32_bf16 v[6:9], v[186:189], v[236:239], v[6:9]
	v_mfma_f32_16x16x32_bf16 v[2:5], v[194:197], v[236:239], v[2:5]
	s_setprio 0
	s_barrier
	s_add_i32 s47, 0, 0x18000
	v_add_u32_e32 v155, s47, v149
	s_add_i32 s48, 0, 0x1c000
	ds_read_b128 v[156:159], v155
	ds_read_b128 v[160:163], v155 offset:1024
	ds_read_b128 v[164:167], v155 offset:2048
	ds_read_b128 v[178:181], v155 offset:3072
	v_add_u32_e32 v155, s48, v149
	ds_read_b128 v[182:185], v155
	ds_read_b128 v[186:189], v155 offset:1024
	ds_read_b128 v[190:193], v155 offset:2048
	ds_read_b128 v[194:197], v155 offset:3072
	s_add_u32 s30, s30, 0x80000
	s_addc_u32 s31, s31, 0
	s_mov_b32 m0, s35
	v_lshl_add_u64 v[176:177], s[30:31], 0, v[130:131]
	ds_read_b128 v[198:201], v154 offset:32768
	global_load_lds_dwordx4 v[176:177], off
	ds_read_b128 v[212:215], v154 offset:33792
	ds_read_b128 v[216:219], v154 offset:34816
	v_lshl_add_u64 v[176:177], s[30:31], 0, v[132:133]
	s_mov_b32 m0, s36
	s_nop 0
	global_load_lds_dwordx4 v[176:177], off
	ds_read_b128 v[220:223], v154 offset:35840
	ds_read_b128 v[224:227], v154 offset:36864
	ds_read_b128 v[228:231], v154 offset:37888
	ds_read_b128 v[232:235], v154 offset:38912
	ds_read_b128 v[236:239], v154 offset:39936
	s_waitcnt vmcnt(8)
	s_waitcnt lgkmcnt(0)
	s_barrier
	s_setprio 1
	v_mfma_f32_16x16x32_bf16 v[126:129], v[156:159], v[198:201], v[126:129]
	v_mfma_f32_16x16x32_bf16 v[122:125], v[164:167], v[198:201], v[122:125]
	v_mfma_f32_16x16x32_bf16 v[110:113], v[156:159], v[216:219], v[110:113]
	v_mfma_f32_16x16x32_bf16 v[106:109], v[164:167], v[216:219], v[106:109]
	v_mfma_f32_16x16x32_bf16 v[94:97], v[156:159], v[224:227], v[94:97]
	v_mfma_f32_16x16x32_bf16 v[90:93], v[164:167], v[224:227], v[90:93]
	v_mfma_f32_16x16x32_bf16 v[78:81], v[156:159], v[232:235], v[78:81]
	v_mfma_f32_16x16x32_bf16 v[74:77], v[164:167], v[232:235], v[74:77]
	v_mfma_f32_16x16x32_bf16 v[126:129], v[160:163], v[212:215], v[126:129]
	v_mfma_f32_16x16x32_bf16 v[122:125], v[178:181], v[212:215], v[122:125]
	v_mfma_f32_16x16x32_bf16 v[110:113], v[160:163], v[220:223], v[110:113]
	v_mfma_f32_16x16x32_bf16 v[106:109], v[178:181], v[220:223], v[106:109]
	v_mfma_f32_16x16x32_bf16 v[94:97], v[160:163], v[228:231], v[94:97]
	v_mfma_f32_16x16x32_bf16 v[90:93], v[178:181], v[228:231], v[90:93]
	v_mfma_f32_16x16x32_bf16 v[78:81], v[160:163], v[236:239], v[78:81]
	v_mfma_f32_16x16x32_bf16 v[74:77], v[178:181], v[236:239], v[74:77]
	v_mfma_f32_16x16x32_bf16 v[118:121], v[182:185], v[198:201], v[118:121]
	v_mfma_f32_16x16x32_bf16 v[114:117], v[190:193], v[198:201], v[114:117]
	v_mfma_f32_16x16x32_bf16 v[102:105], v[182:185], v[216:219], v[102:105]
	v_mfma_f32_16x16x32_bf16 v[98:101], v[190:193], v[216:219], v[98:101]
	v_mfma_f32_16x16x32_bf16 v[86:89], v[182:185], v[224:227], v[86:89]
	v_mfma_f32_16x16x32_bf16 v[82:85], v[190:193], v[224:227], v[82:85]
	v_mfma_f32_16x16x32_bf16 v[70:73], v[182:185], v[232:235], v[70:73]
	v_mfma_f32_16x16x32_bf16 v[66:69], v[190:193], v[232:235], v[66:69]
	v_mfma_f32_16x16x32_bf16 v[118:121], v[186:189], v[212:215], v[118:121]
	v_mfma_f32_16x16x32_bf16 v[114:117], v[194:197], v[212:215], v[114:117]
	v_mfma_f32_16x16x32_bf16 v[102:105], v[186:189], v[220:223], v[102:105]
	v_mfma_f32_16x16x32_bf16 v[98:101], v[194:197], v[220:223], v[98:101]
	v_mfma_f32_16x16x32_bf16 v[86:89], v[186:189], v[228:231], v[86:89]
	v_mfma_f32_16x16x32_bf16 v[82:85], v[194:197], v[228:231], v[82:85]
	v_mfma_f32_16x16x32_bf16 v[70:73], v[186:189], v[236:239], v[70:73]
	v_mfma_f32_16x16x32_bf16 v[66:69], v[194:197], v[236:239], v[66:69]
	s_setprio 0
	s_barrier
; #define PG8_STAGE(bufoff, gbase, voff) do { _Pragma("unroll") for (int _i = 0; _i < 2; ++_i) \
;         __builtin_amdgcn_global_load_lds((const unsigned*)((const char*)(gbase) + (voff)[_i]), (LAS unsigned*)(lds + (bufoff) + ldsw + _i * 8192), 16, 0, 0); } while (0)
; #define PG8_LDA(dst, b, h) do { _Pragma("unroll") for (int m = 0; m < 4; ++m) _Pragma("unroll") for (int k = 0; k < 2; ++k) dst[m][k] = *(const LAS bf16x8*)(lds + PG8_SA(b, h) + aoff + m * 2048 + k * 1024); } while (0)
; #define PG8_MMA(ai, bj, At, Bt) do { __builtin_amdgcn_s_setprio(1); _Pragma("unroll") for (int m = 0; m < 4; ++m) _Pragma("unroll") for (int n = 0; n < 2; ++n) _Pragma("unroll") for (int k = 0; k < 2; ++k) \
;         acc[ai][bj][m][n] = __builtin_amdgcn_mfma_f32_16x16x32_bf16(Bt[n][k], At[m][k], acc[ai][bj][m][n], 0, 0, 0); __builtin_amdgcn_s_setprio(0); } while (0)
; #define PG8_WAIT_V(n) asm volatile("s_waitcnt vmcnt(" #n ")" ::: "memory")
; #define PG8_WAIT_L(n) asm volatile("s_waitcnt lgkmcnt(" #n ")" ::: "memory")
; #define PG8_BAR __builtin_amdgcn_s_barrier()
; #define PG8_SCHED __builtin_amdgcn_sched_barrier(0)
; template <class Epi>
; __device__ __forceinline__ void gemm_phase(LAS unsigned char* lds, const Gemm g, const StaticOrder& S, const Epi& E, const int tid) {
;     ...
;             PG8_LDA(At, 1, 1); PG8_STAGE(PG8_SB(1, 0), b3, voffB); PG8_STAGE(PG8_SB(1, 1), b3 + bhs, voffB); PG8_STAGE(PG8_SA(1, 0), a3, voffA);
;             PG8_WAIT_V(8); PG8_WAIT_L(0); PG8_BAR; PG8_MMA(1, 0, At, B0); PG8_MMA(1, 1, At, B1); PG8_BAR; PG8_SCHED;
	s_add_i32 s30, s47, s34
	v_lshl_add_u64 v[142:143], v[142:143], 0, s[70:71]
	s_mov_b32 m0, s30
	ds_read_b128 v[198:201], v154 offset:49152
	global_load_lds_dwordx4 v[142:143], off
	ds_read_b128 v[212:215], v154 offset:50176
	ds_read_b128 v[216:219], v154 offset:51200
	s_add_i32 m0, s30, 0x2000
	s_add_u32 s28, s28, 0x8080
	v_lshl_add_u64 v[142:143], v[168:169], 0, s[70:71]
	s_addc_u32 s29, s29, 0
	s_add_i32 s30, s48, s34
	global_load_lds_dwordx4 v[142:143], off
	ds_read_b128 v[220:223], v154 offset:52224
	ds_read_b128 v[224:227], v154 offset:53248
	v_lshl_add_u64 v[142:143], s[28:29], 0, v[0:1]
	s_mov_b32 m0, s30
	s_nop 0
	global_load_lds_dwordx4 v[142:143], off
	ds_read_b128 v[228:231], v154 offset:54272
	ds_read_b128 v[232:235], v154 offset:55296
	v_lshl_add_u64 v[142:143], s[28:29], 0, v[134:135]
	s_add_i32 m0, s30, 0x2000
	s_nop 0
	global_load_lds_dwordx4 v[142:143], off
	ds_read_b128 v[236:239], v154 offset:56320
	v_lshl_add_u64 v[142:143], v[172:173], 0, s[70:71]
	s_mov_b32 m0, s37
	s_nop 0
	global_load_lds_dwordx4 v[142:143], off
	v_lshl_add_u64 v[142:143], v[174:175], 0, s[70:71]
	s_mov_b32 m0, s38
	s_nop 0
	global_load_lds_dwordx4 v[142:143], off
	s_waitcnt vmcnt(8)
	s_waitcnt lgkmcnt(0)
	s_barrier
	s_setprio 1
	v_mfma_f32_16x16x32_bf16 v[62:65], v[156:159], v[198:201], v[62:65]
	v_mfma_f32_16x16x32_bf16 v[58:61], v[164:167], v[198:201], v[58:61]
	v_mfma_f32_16x16x32_bf16 v[46:49], v[156:159], v[216:219], v[46:49]
	v_mfma_f32_16x16x32_bf16 v[42:45], v[164:167], v[216:219], v[42:45]
	v_mfma_f32_16x16x32_bf16 v[30:33], v[156:159], v[224:227], v[30:33]
	v_mfma_f32_16x16x32_bf16 v[26:29], v[164:167], v[224:227], v[26:29]
	v_mfma_f32_16x16x32_bf16 v[14:17], v[156:159], v[232:235], v[14:17]
	v_mfma_f32_16x16x32_bf16 v[10:13], v[164:167], v[232:235], v[10:13]
	v_mfma_f32_16x16x32_bf16 v[62:65], v[160:163], v[212:215], v[62:65]
	v_mfma_f32_16x16x32_bf16 v[58:61], v[178:181], v[212:215], v[58:61]
	v_mfma_f32_16x16x32_bf16 v[46:49], v[160:163], v[220:223], v[46:49]
	v_mfma_f32_16x16x32_bf16 v[42:45], v[178:181], v[220:223], v[42:45]
	v_mfma_f32_16x16x32_bf16 v[30:33], v[160:163], v[228:231], v[30:33]
	v_mfma_f32_16x16x32_bf16 v[26:29], v[178:181], v[228:231], v[26:29]
	v_mfma_f32_16x16x32_bf16 v[14:17], v[160:163], v[236:239], v[14:17]
	v_mfma_f32_16x16x32_bf16 v[10:13], v[178:181], v[236:239], v[10:13]
	v_mfma_f32_16x16x32_bf16 v[54:57], v[182:185], v[198:201], v[54:57]
	v_mfma_f32_16x16x32_bf16 v[50:53], v[190:193], v[198:201], v[50:53]
	v_mfma_f32_16x16x32_bf16 v[38:41], v[182:185], v[216:219], v[38:41]
	v_mfma_f32_16x16x32_bf16 v[34:37], v[190:193], v[216:219], v[34:37]
	v_mfma_f32_16x16x32_bf16 v[22:25], v[182:185], v[224:227], v[22:25]
	v_mfma_f32_16x16x32_bf16 v[18:21], v[190:193], v[224:227], v[18:21]
	v_mfma_f32_16x16x32_bf16 v[6:9], v[182:185], v[232:235], v[6:9]
	v_mfma_f32_16x16x32_bf16 v[2:5], v[190:193], v[232:235], v[2:5]
	v_mfma_f32_16x16x32_bf16 v[54:57], v[186:189], v[212:215], v[54:57]
	v_mfma_f32_16x16x32_bf16 v[50:53], v[194:197], v[212:215], v[50:53]
	v_mfma_f32_16x16x32_bf16 v[38:41], v[186:189], v[220:223], v[38:41]
	v_mfma_f32_16x16x32_bf16 v[34:37], v[194:197], v[220:223], v[34:37]
	v_mfma_f32_16x16x32_bf16 v[22:25], v[186:189], v[228:231], v[22:25]
	v_mfma_f32_16x16x32_bf16 v[18:21], v[194:197], v[228:231], v[18:21]
	v_mfma_f32_16x16x32_bf16 v[6:9], v[186:189], v[236:239], v[6:9]
	v_mfma_f32_16x16x32_bf16 v[2:5], v[194:197], v[236:239], v[2:5]
	s_setprio 0
	s_barrier
	s_add_i32 s46, s46, 2
	s_add_u32 s44, s44, 0x100
	s_addc_u32 s45, s45, 0
	s_add_u32 s26, s26, 0x100
	s_addc_u32 s27, s27, 0
	s_cmp_gt_u32 s46, 29
	s_cbranch_scc0 .LBB0_173
	v_readlane_b32 s42, v251, 53
	s_and_b64 vcc, exec, s[12:13]
	v_readlane_b32 s43, v251, 54
	s_cbranch_vccz .LBB0_176
	s_barrier

; #define PG8_STAGE(bufoff, gbase, voff) do { _Pragma("unroll") for (int _i = 0; _i < 2; ++_i) \
;         __builtin_amdgcn_global_load_lds((const unsigned*)((const char*)(gbase) + (voff)[_i]), (LAS unsigned*)(lds + (bufoff) + ldsw + _i * 8192), 16, 0, 0); } while (0)
; #define PG8_LDA(dst, b, h) do { _Pragma("unroll") for (int m = 0; m < 4; ++m) _Pragma("unroll") for (int k = 0; k < 2; ++k) dst[m][k] = *(const LAS bf16x8*)(lds + PG8_SA(b, h) + aoff + m * 2048 + k * 1024); } while (0)
; #define PG8_LDB(dst, b, h) do { _Pragma("unroll") for (int n = 0; n < 2; ++n) _Pragma("unroll") for (int k = 0; k < 2; ++k) dst[n][k] = *(const LAS bf16x8*)(lds + PG8_SB(b, h) + boff + n * 2048 + k * 1024); } while (0)
; #define PG8_WAIT_V(n) asm volatile("s_waitcnt vmcnt(" #n ")" ::: "memory")
; #define PG8_WAIT_L(n) asm volatile("s_waitcnt lgkmcnt(" #n ")" ::: "memory")
; #define PG8_BAR __builtin_amdgcn_s_barrier()
; #define PG8_SCHED __builtin_amdgcn_sched_barrier(0)
; template <class Epi>
; __device__ __forceinline__ void gemm_phase(LAS unsigned char* lds, const Gemm g, const StaticOrder& S, const Epi& E, const int tid) {
;     ...
;             const bool last = (t == ntt - 2);
;             const bool s1 = Epi::TWO && (t >= nt), s2 = Epi::TWO && (t + 2 >= nt);
;             const char* a1 = (s1 ? cA2 + (size_t)(t - nt + 1) * kstep : cA + (size_t)(t + 1) * kstep);
;             const char* a2 = last ? nA : (s2 ? cA2 + (size_t)(t + 2 - nt) * kstep : cA + (size_t)(t + 2) * kstep);
;             const char* b2 = last ? nB : (s2 ? cB2 + (size_t)(t + 2 - nt) * kstep : cB + (size_t)(t + 2) * kstep);
;             const char* a3 = a2 + kstep; const char* b3 = b2 + kstep;
;             if constexpr (Epi::TWO) { if (t == nt) E.mid(acc, cur, wr, wc, fr, fq); }
;             if constexpr (SP2) {
;             PG8_LDB(B0, 0, 0); PG8_LDB(B1, 0, 1); PG8_SCHED; PG8_LDA(At, 0, 0); PG8_STAGE(PG8_SA(1, 1), a1 + hstep, voffA);
;             PG8_WAIT_V(8); PG8_WAIT_L(0); PG8_BAR; PG8_MMA(0, 0, At, B0); PG8_MMA(0, 1, At, B1); PG8_BAR; PG8_SCHED;
;             PG8_LDA(At, 0, 1); PG8_STAGE(PG8_SB(0, 0), b2, voffB); PG8_STAGE(PG8_SB(0, 1), b2 + bhs, voffB); PG8_STAGE(PG8_SA(0, 0), a2, voffA);
;             PG8_WAIT_V(8); PG8_WAIT_L(0); PG8_BAR; PG8_MMA(1, 0, At, B0); PG8_MMA(1, 1, At, B1); PG8_BAR; PG8_SCHED;
.LBB0_206:
	s_add_u32 s30, s28, 0xfffe0080
	s_addc_u32 s31, s29, -1
	s_add_i32 s52, 0, 0x10000
	s_cmp_eq_u32 s51, 4
	s_cselect_b32 s35, s17, s31
	s_cselect_b32 s34, s27, s30
	s_cselect_b32 s31, s15, s50
	s_cselect_b32 s30, s33, s49
	s_add_i32 s54, 0, 0x14000
	v_add_u32_e32 v30, s52, v193
	v_add_u32_e32 v54, s54, v193
	ds_read_b128 v[18:21], v30
	ds_read_b128 v[22:25], v30 offset:1024
	ds_read_b128 v[26:29], v30 offset:2048
	ds_read_b128 v[30:33], v30 offset:3072
	ds_read_b128 v[42:45], v54
	ds_read_b128 v[46:49], v54 offset:1024
	ds_read_b128 v[50:53], v54 offset:2048
	ds_read_b128 v[54:57], v54 offset:3072
	v_lshl_add_u64 v[172:173], s[28:29], 0, v[180:181]
	s_add_i32 m0, s37, 0xc000
	ds_read_b128 v[182:185], v199
	global_load_lds_dwordx4 v[172:173], off
	ds_read_b128 v[186:189], v199 offset:1024
	ds_read_b128 v[212:215], v199 offset:2048
	v_lshl_add_u64 v[172:173], s[28:29], 0, v[178:179]
	s_add_i32 m0, s37, 0xe000
	s_nop 0
	global_load_lds_dwordx4 v[172:173], off
	ds_read_b128 v[216:219], v199 offset:3072
	ds_read_b128 v[220:223], v199 offset:4096
	ds_read_b128 v[224:227], v199 offset:5120
	ds_read_b128 v[228:231], v199 offset:6144
	ds_read_b128 v[232:235], v199 offset:7168
	s_waitcnt vmcnt(8)
	s_waitcnt lgkmcnt(0)
	s_barrier
	s_setprio 1
	v_mfma_f32_16x16x32_bf16 v[158:161], v[18:21], v[182:185], v[158:161]
	v_mfma_f32_16x16x32_bf16 v[154:157], v[26:29], v[182:185], v[154:157]
	v_mfma_f32_16x16x32_bf16 v[142:145], v[18:21], v[212:215], v[142:145]
	v_mfma_f32_16x16x32_bf16 v[138:141], v[26:29], v[212:215], v[138:141]
	v_mfma_f32_16x16x32_bf16 v[126:129], v[18:21], v[220:223], v[126:129]
	v_mfma_f32_16x16x32_bf16 v[122:125], v[26:29], v[220:223], v[122:125]
	v_mfma_f32_16x16x32_bf16 v[110:113], v[18:21], v[228:231], v[110:113]
	v_mfma_f32_16x16x32_bf16 v[106:109], v[26:29], v[228:231], v[106:109]
	v_mfma_f32_16x16x32_bf16 v[158:161], v[22:25], v[186:189], v[158:161]
	v_mfma_f32_16x16x32_bf16 v[154:157], v[30:33], v[186:189], v[154:157]
	v_mfma_f32_16x16x32_bf16 v[142:145], v[22:25], v[216:219], v[142:145]
	v_mfma_f32_16x16x32_bf16 v[138:141], v[30:33], v[216:219], v[138:141]
	v_mfma_f32_16x16x32_bf16 v[126:129], v[22:25], v[224:227], v[126:129]
	v_mfma_f32_16x16x32_bf16 v[122:125], v[30:33], v[224:227], v[122:125]
	v_mfma_f32_16x16x32_bf16 v[110:113], v[22:25], v[232:235], v[110:113]
	v_mfma_f32_16x16x32_bf16 v[106:109], v[30:33], v[232:235], v[106:109]
	v_mfma_f32_16x16x32_bf16 v[150:153], v[42:45], v[182:185], v[150:153]
	v_mfma_f32_16x16x32_bf16 v[146:149], v[50:53], v[182:185], v[146:149]
	v_mfma_f32_16x16x32_bf16 v[134:137], v[42:45], v[212:215], v[134:137]
	v_mfma_f32_16x16x32_bf16 v[130:133], v[50:53], v[212:215], v[130:133]
	v_mfma_f32_16x16x32_bf16 v[118:121], v[42:45], v[220:223], v[118:121]
	v_mfma_f32_16x16x32_bf16 v[114:117], v[50:53], v[220:223], v[114:117]
	v_mfma_f32_16x16x32_bf16 v[102:105], v[42:45], v[228:231], v[102:105]
	v_mfma_f32_16x16x32_bf16 v[98:101], v[50:53], v[228:231], v[98:101]
	v_mfma_f32_16x16x32_bf16 v[150:153], v[46:49], v[186:189], v[150:153]
	v_mfma_f32_16x16x32_bf16 v[146:149], v[54:57], v[186:189], v[146:149]
	v_mfma_f32_16x16x32_bf16 v[134:137], v[46:49], v[216:219], v[134:137]
	v_mfma_f32_16x16x32_bf16 v[130:133], v[54:57], v[216:219], v[130:133]
	v_mfma_f32_16x16x32_bf16 v[118:121], v[46:49], v[224:227], v[118:121]
	v_mfma_f32_16x16x32_bf16 v[114:117], v[54:57], v[224:227], v[114:117]
	v_mfma_f32_16x16x32_bf16 v[102:105], v[46:49], v[232:235], v[102:105]
	v_mfma_f32_16x16x32_bf16 v[98:101], v[54:57], v[232:235], v[98:101]
	s_setprio 0
	s_barrier
	s_add_i32 s52, s52, s36
	v_lshl_add_u64 v[172:173], s[30:31], 0, v[0:1]
	s_mov_b32 m0, s52
	ds_read_b128 v[182:185], v199 offset:16384
	global_load_lds_dwordx4 v[172:173], off
	ds_read_b128 v[186:189], v199 offset:17408
	ds_read_b128 v[212:215], v199 offset:18432
	s_add_i32 m0, s52, 0x2000
	s_add_u32 s52, s30, 0x2000
	v_lshl_add_u64 v[174:175], s[30:31], 0, v[166:167]
	s_addc_u32 s53, s31, 0
	s_add_i32 s54, s54, s36
	global_load_lds_dwordx4 v[174:175], off
	ds_read_b128 v[216:219], v199 offset:19456
	ds_read_b128 v[220:223], v199 offset:20480
	v_lshl_add_u64 v[176:177], s[52:53], 0, v[0:1]
	s_mov_b32 m0, s54
	v_lshl_add_u64 v[200:201], s[34:35], 0, v[164:165]
	global_load_lds_dwordx4 v[176:177], off
	ds_read_b128 v[224:227], v199 offset:21504
	ds_read_b128 v[228:231], v199 offset:22528
	v_lshl_add_u64 v[176:177], s[52:53], 0, v[166:167]
	s_add_i32 m0, s54, 0x2000
	s_nop 0
	global_load_lds_dwordx4 v[176:177], off
	ds_read_b128 v[232:235], v199 offset:23552
	v_lshl_add_u64 v[176:177], s[34:35], 0, v[162:163]
	s_mov_b32 m0, s37
	s_nop 0
	global_load_lds_dwordx4 v[176:177], off
	s_mov_b32 m0, s38
	s_nop 0
	global_load_lds_dwordx4 v[200:201], off
	s_waitcnt vmcnt(8)
	s_waitcnt lgkmcnt(0)
	s_barrier
; #define PG8_STAGE(bufoff, gbase, voff) do { _Pragma("unroll") for (int _i = 0; _i < 2; ++_i) \
;         __builtin_amdgcn_global_load_lds((const unsigned*)((const char*)(gbase) + (voff)[_i]), (LAS unsigned*)(lds + (bufoff) + ldsw + _i * 8192), 16, 0, 0); } while (0)
; #define PG8_LDA(dst, b, h) do { _Pragma("unroll") for (int m = 0; m < 4; ++m) _Pragma("unroll") for (int k = 0; k < 2; ++k) dst[m][k] = *(const LAS bf16x8*)(lds + PG8_SA(b, h) + aoff + m * 2048 + k * 1024); } while (0)
; #define PG8_LDB(dst, b, h) do { _Pragma("unroll") for (int n = 0; n < 2; ++n) _Pragma("unroll") for (int k = 0; k < 2; ++k) dst[n][k] = *(const LAS bf16x8*)(lds + PG8_SB(b, h) + boff + n * 2048 + k * 1024); } while (0)
; #define PG8_MMA(ai, bj, At, Bt) do { __builtin_amdgcn_s_setprio(1); _Pragma("unroll") for (int m = 0; m < 4; ++m) _Pragma("unroll") for (int n = 0; n < 2; ++n) _Pragma("unroll") for (int k = 0; k < 2; ++k) \
;         acc[ai][bj][m][n] = __builtin_amdgcn_mfma_f32_16x16x32_bf16(Bt[n][k], At[m][k], acc[ai][bj][m][n], 0, 0, 0); __builtin_amdgcn_s_setprio(0); } while (0)
; #define PG8_WAIT_V(n) asm volatile("s_waitcnt vmcnt(" #n ")" ::: "memory")
; #define PG8_WAIT_L(n) asm volatile("s_waitcnt lgkmcnt(" #n ")" ::: "memory")
; #define PG8_BAR __builtin_amdgcn_s_barrier()
; #define PG8_SCHED __builtin_amdgcn_sched_barrier(0)
; template <class Epi>
; __device__ __forceinline__ void gemm_phase(LAS unsigned char* lds, const Gemm g, const StaticOrder& S, const Epi& E, const int tid) {
;     ...
;             PG8_WAIT_V(8); PG8_WAIT_L(0); PG8_BAR; PG8_MMA(1, 0, At, B0); PG8_MMA(1, 1, At, B1); PG8_BAR; PG8_SCHED;
;             PG8_LDB(B0, 1, 0); PG8_LDB(B1, 1, 1); PG8_SCHED; PG8_LDA(At, 1, 0); PG8_STAGE(PG8_SA(0, 1), a2 + hstep, voffA);
;             PG8_WAIT_V(8); PG8_WAIT_L(0); PG8_BAR; PG8_MMA(0, 0, At, B0); PG8_MMA(0, 1, At, B1); PG8_BAR; PG8_SCHED;
	s_setprio 1
	v_mfma_f32_16x16x32_bf16 v[94:97], v[18:21], v[182:185], v[94:97]
	v_mfma_f32_16x16x32_bf16 v[90:93], v[26:29], v[182:185], v[90:93]
	v_mfma_f32_16x16x32_bf16 v[78:81], v[18:21], v[212:215], v[78:81]
	v_mfma_f32_16x16x32_bf16 v[74:77], v[26:29], v[212:215], v[74:77]
	v_mfma_f32_16x16x32_bf16 v[62:65], v[18:21], v[220:223], v[62:65]
	v_mfma_f32_16x16x32_bf16 v[58:61], v[26:29], v[220:223], v[58:61]
	v_mfma_f32_16x16x32_bf16 v[14:17], v[18:21], v[228:231], v[14:17]
	v_mfma_f32_16x16x32_bf16 v[10:13], v[26:29], v[228:231], v[10:13]
	v_mfma_f32_16x16x32_bf16 v[94:97], v[22:25], v[186:189], v[94:97]
	v_mfma_f32_16x16x32_bf16 v[90:93], v[30:33], v[186:189], v[90:93]
	v_mfma_f32_16x16x32_bf16 v[78:81], v[22:25], v[216:219], v[78:81]
	v_mfma_f32_16x16x32_bf16 v[74:77], v[30:33], v[216:219], v[74:77]
	v_mfma_f32_16x16x32_bf16 v[62:65], v[22:25], v[224:227], v[62:65]
	v_mfma_f32_16x16x32_bf16 v[58:61], v[30:33], v[224:227], v[58:61]
	v_mfma_f32_16x16x32_bf16 v[14:17], v[22:25], v[232:235], v[14:17]
	v_mfma_f32_16x16x32_bf16 v[10:13], v[30:33], v[232:235], v[10:13]
	v_mfma_f32_16x16x32_bf16 v[38:41], v[42:45], v[220:223], v[38:41]
	v_mfma_f32_16x16x32_bf16 v[34:37], v[50:53], v[220:223], v[34:37]
	v_mfma_f32_16x16x32_bf16 v[6:9], v[42:45], v[228:231], v[6:9]
	v_mfma_f32_16x16x32_bf16 v[2:5], v[50:53], v[228:231], v[2:5]
	v_mfma_f32_16x16x32_bf16 v[18:21], v[42:45], v[182:185], v[86:89]
	v_mfma_f32_16x16x32_bf16 v[22:25], v[50:53], v[182:185], v[82:85]
	v_mfma_f32_16x16x32_bf16 v[26:29], v[42:45], v[212:215], v[70:73]
	v_mfma_f32_16x16x32_bf16 v[30:33], v[50:53], v[212:215], v[66:69]
	v_mfma_f32_16x16x32_bf16 v[38:41], v[46:49], v[224:227], v[38:41]
	v_mfma_f32_16x16x32_bf16 v[34:37], v[54:57], v[224:227], v[34:37]
	v_mfma_f32_16x16x32_bf16 v[6:9], v[46:49], v[232:235], v[6:9]
	v_mfma_f32_16x16x32_bf16 v[2:5], v[54:57], v[232:235], v[2:5]
	v_mfma_f32_16x16x32_bf16 v[18:21], v[46:49], v[186:189], v[18:21]
	v_mfma_f32_16x16x32_bf16 v[22:25], v[54:57], v[186:189], v[22:25]
	v_mfma_f32_16x16x32_bf16 v[26:29], v[46:49], v[216:219], v[26:29]
	v_mfma_f32_16x16x32_bf16 v[30:33], v[54:57], v[216:219], v[30:33]
	s_setprio 0
	s_barrier
	s_add_i32 s52, 0, 0x18000
	s_add_i32 s53, 0, 0x1c000
	v_add_u32_e32 v54, s52, v193
	v_add_u32_e32 v66, s53, v193
	ds_read_b128 v[42:45], v54
	ds_read_b128 v[46:49], v54 offset:1024
	ds_read_b128 v[50:53], v54 offset:2048
	ds_read_b128 v[54:57], v54 offset:3072
	ds_read_b128 v[182:185], v66
	ds_read_b128 v[186:189], v66 offset:1024
	ds_read_b128 v[212:215], v66 offset:2048
	ds_read_b128 v[216:219], v66 offset:3072
	s_add_u32 s34, s34, 0x20000
	s_addc_u32 s35, s35, 0
	s_mov_b32 m0, s39
	v_lshl_add_u64 v[236:237], s[34:35], 0, v[162:163]
	ds_read_b128 v[66:69], v199 offset:32768
	global_load_lds_dwordx4 v[236:237], off
	ds_read_b128 v[70:73], v199 offset:33792
	ds_read_b128 v[82:85], v199 offset:34816
	v_lshl_add_u64 v[236:237], s[34:35], 0, v[164:165]
	s_mov_b32 m0, s44
	s_nop 0
	global_load_lds_dwordx4 v[236:237], off
	ds_read_b128 v[86:89], v199 offset:35840
	ds_read_b128 v[220:223], v199 offset:36864
	ds_read_b128 v[224:227], v199 offset:37888
	ds_read_b128 v[228:231], v199 offset:38912
	ds_read_b128 v[232:235], v199 offset:39936
	s_waitcnt vmcnt(8)
	s_waitcnt lgkmcnt(0)
	s_barrier
	s_setprio 1
	v_mfma_f32_16x16x32_bf16 v[158:161], v[42:45], v[66:69], v[158:161]
	v_mfma_f32_16x16x32_bf16 v[154:157], v[50:53], v[66:69], v[154:157]
	v_mfma_f32_16x16x32_bf16 v[142:145], v[42:45], v[82:85], v[142:145]
	v_mfma_f32_16x16x32_bf16 v[138:141], v[50:53], v[82:85], v[138:141]
	v_mfma_f32_16x16x32_bf16 v[126:129], v[42:45], v[220:223], v[126:129]
	v_mfma_f32_16x16x32_bf16 v[122:125], v[50:53], v[220:223], v[122:125]
	v_mfma_f32_16x16x32_bf16 v[110:113], v[42:45], v[228:231], v[110:113]
	v_mfma_f32_16x16x32_bf16 v[106:109], v[50:53], v[228:231], v[106:109]
	v_mfma_f32_16x16x32_bf16 v[158:161], v[46:49], v[70:73], v[158:161]
	v_mfma_f32_16x16x32_bf16 v[154:157], v[54:57], v[70:73], v[154:157]
	v_mfma_f32_16x16x32_bf16 v[142:145], v[46:49], v[86:89], v[142:145]
	v_mfma_f32_16x16x32_bf16 v[138:141], v[54:57], v[86:89], v[138:141]
	v_mfma_f32_16x16x32_bf16 v[126:129], v[46:49], v[224:227], v[126:129]
	v_mfma_f32_16x16x32_bf16 v[122:125], v[54:57], v[224:227], v[122:125]
	v_mfma_f32_16x16x32_bf16 v[110:113], v[46:49], v[232:235], v[110:113]
	v_mfma_f32_16x16x32_bf16 v[106:109], v[54:57], v[232:235], v[106:109]
	v_mfma_f32_16x16x32_bf16 v[150:153], v[182:185], v[66:69], v[150:153]
	v_mfma_f32_16x16x32_bf16 v[66:69], v[212:215], v[66:69], v[146:149]
	v_mfma_f32_16x16x32_bf16 v[146:149], v[216:219], v[70:73], v[66:69]
	v_mfma_f32_16x16x32_bf16 v[66:69], v[182:185], v[82:85], v[134:137]
	v_mfma_f32_16x16x32_bf16 v[134:137], v[186:189], v[86:89], v[66:69]
	v_mfma_f32_16x16x32_bf16 v[66:69], v[212:215], v[82:85], v[130:133]
	v_mfma_f32_16x16x32_bf16 v[130:133], v[216:219], v[86:89], v[66:69]
	v_mfma_f32_16x16x32_bf16 v[66:69], v[182:185], v[220:223], v[118:121]
	v_mfma_f32_16x16x32_bf16 v[118:121], v[186:189], v[224:227], v[66:69]
	v_mfma_f32_16x16x32_bf16 v[66:69], v[212:215], v[220:223], v[114:117]
	v_mfma_f32_16x16x32_bf16 v[114:117], v[216:219], v[224:227], v[66:69]
	v_mfma_f32_16x16x32_bf16 v[66:69], v[182:185], v[228:231], v[102:105]
	v_mfma_f32_16x16x32_bf16 v[102:105], v[186:189], v[232:235], v[66:69]
	v_mfma_f32_16x16x32_bf16 v[66:69], v[212:215], v[228:231], v[98:101]
	v_mfma_f32_16x16x32_bf16 v[150:153], v[186:189], v[70:73], v[150:153]
	v_mfma_f32_16x16x32_bf16 v[98:101], v[216:219], v[232:235], v[66:69]
	s_setprio 0
	s_barrier
; #define PG8_STAGE(bufoff, gbase, voff) do { _Pragma("unroll") for (int _i = 0; _i < 2; ++_i) \
;         __builtin_amdgcn_global_load_lds((const unsigned*)((const char*)(gbase) + (voff)[_i]), (LAS unsigned*)(lds + (bufoff) + ldsw + _i * 8192), 16, 0, 0); } while (0)
; #define PG8_LDA(dst, b, h) do { _Pragma("unroll") for (int m = 0; m < 4; ++m) _Pragma("unroll") for (int k = 0; k < 2; ++k) dst[m][k] = *(const LAS bf16x8*)(lds + PG8_SA(b, h) + aoff + m * 2048 + k * 1024); } while (0)
; #define PG8_MMA(ai, bj, At, Bt) do { __builtin_amdgcn_s_setprio(1); _Pragma("unroll") for (int m = 0; m < 4; ++m) _Pragma("unroll") for (int n = 0; n < 2; ++n) _Pragma("unroll") for (int k = 0; k < 2; ++k) \
;         acc[ai][bj][m][n] = __builtin_amdgcn_mfma_f32_16x16x32_bf16(Bt[n][k], At[m][k], acc[ai][bj][m][n], 0, 0, 0); __builtin_amdgcn_s_setprio(0); } while (0)
; #define PG8_WAIT_V(n) asm volatile("s_waitcnt vmcnt(" #n ")" ::: "memory")
; #define PG8_WAIT_L(n) asm volatile("s_waitcnt lgkmcnt(" #n ")" ::: "memory")
; #define PG8_BAR __builtin_amdgcn_s_barrier()
; #define PG8_SCHED __builtin_amdgcn_sched_barrier(0)
; template <class Epi>
; __device__ __forceinline__ void gemm_phase(LAS unsigned char* lds, const Gemm g, const StaticOrder& S, const Epi& E, const int tid) {
;     ...
;         for (int t = 0; t < ntt; t += 2) {
;     ...
;             PG8_LDA(At, 1, 1); PG8_STAGE(PG8_SB(1, 0), b3, voffB); PG8_STAGE(PG8_SB(1, 1), b3 + bhs, voffB); PG8_STAGE(PG8_SA(1, 0), a3, voffA);
;             PG8_WAIT_V(8); PG8_WAIT_L(0); PG8_BAR; PG8_MMA(1, 0, At, B0); PG8_MMA(1, 1, At, B1); PG8_BAR; PG8_SCHED;
	s_add_i32 s34, s52, s36
	v_lshl_add_u64 v[82:83], v[172:173], 0, s[70:71]
	s_mov_b32 m0, s34
	s_nop 0
	ds_read_b128 v[66:69], v199 offset:49152
	global_load_lds_dwordx4 v[82:83], off
	ds_read_b128 v[70:73], v199 offset:50176
	ds_read_b128 v[220:223], v199 offset:51200
	s_add_i32 m0, s34, 0x2000
	s_add_u32 s30, s30, 0x2080
	v_lshl_add_u64 v[82:83], v[174:175], 0, s[70:71]
	s_addc_u32 s31, s31, 0
	s_add_i32 s34, s53, s36
	global_load_lds_dwordx4 v[82:83], off
	ds_read_b128 v[224:227], v199 offset:52224
	ds_read_b128 v[228:231], v199 offset:53248
	v_lshl_add_u64 v[82:83], s[30:31], 0, v[0:1]
	s_mov_b32 m0, s34
	s_nop 0
	global_load_lds_dwordx4 v[82:83], off
	ds_read_b128 v[232:235], v199 offset:54272
	ds_read_b128 v[236:239], v199 offset:55296
	v_lshl_add_u64 v[82:83], s[30:31], 0, v[166:167]
	s_add_i32 m0, s34, 0x2000
	s_nop 0
	global_load_lds_dwordx4 v[82:83], off
	ds_read_b128 v[240:243], v199 offset:56320
	v_lshl_add_u64 v[82:83], v[176:177], 0, s[70:71]
	s_mov_b32 m0, s45
	s_nop 0
	global_load_lds_dwordx4 v[82:83], off
	v_lshl_add_u64 v[82:83], v[200:201], 0, s[70:71]
	s_mov_b32 m0, s46
	s_nop 0
	global_load_lds_dwordx4 v[82:83], off
	s_waitcnt vmcnt(8)
	s_waitcnt lgkmcnt(0)
	s_barrier
	s_setprio 1
	v_mfma_f32_16x16x32_bf16 v[82:85], v[42:45], v[66:69], v[94:97]
	v_mfma_f32_16x16x32_bf16 v[94:97], v[46:49], v[70:73], v[82:85]
	v_mfma_f32_16x16x32_bf16 v[82:85], v[50:53], v[66:69], v[90:93]
	v_mfma_f32_16x16x32_bf16 v[78:81], v[42:45], v[220:223], v[78:81]
	v_mfma_f32_16x16x32_bf16 v[74:77], v[50:53], v[220:223], v[74:77]
	v_mfma_f32_16x16x32_bf16 v[62:65], v[42:45], v[228:231], v[62:65]
	v_mfma_f32_16x16x32_bf16 v[58:61], v[50:53], v[228:231], v[58:61]
	v_mfma_f32_16x16x32_bf16 v[14:17], v[42:45], v[236:239], v[14:17]
	v_mfma_f32_16x16x32_bf16 v[10:13], v[50:53], v[236:239], v[10:13]
	v_mfma_f32_16x16x32_bf16 v[90:93], v[54:57], v[70:73], v[82:85]
	v_mfma_f32_16x16x32_bf16 v[78:81], v[46:49], v[224:227], v[78:81]
	v_mfma_f32_16x16x32_bf16 v[74:77], v[54:57], v[224:227], v[74:77]
	v_mfma_f32_16x16x32_bf16 v[62:65], v[46:49], v[232:235], v[62:65]
	v_mfma_f32_16x16x32_bf16 v[58:61], v[54:57], v[232:235], v[58:61]
	v_mfma_f32_16x16x32_bf16 v[14:17], v[46:49], v[240:243], v[14:17]
	v_mfma_f32_16x16x32_bf16 v[10:13], v[54:57], v[240:243], v[10:13]
	v_mfma_f32_16x16x32_bf16 v[18:21], v[182:185], v[66:69], v[18:21]
	v_mfma_f32_16x16x32_bf16 v[86:89], v[186:189], v[70:73], v[18:21]
	v_mfma_f32_16x16x32_bf16 v[18:21], v[212:215], v[66:69], v[22:25]
	v_mfma_f32_16x16x32_bf16 v[82:85], v[216:219], v[70:73], v[18:21]
	v_mfma_f32_16x16x32_bf16 v[18:21], v[182:185], v[220:223], v[26:29]
	v_mfma_f32_16x16x32_bf16 v[70:73], v[186:189], v[224:227], v[18:21]
	v_mfma_f32_16x16x32_bf16 v[18:21], v[212:215], v[220:223], v[30:33]
	v_mfma_f32_16x16x32_bf16 v[66:69], v[216:219], v[224:227], v[18:21]
	v_mfma_f32_16x16x32_bf16 v[18:21], v[182:185], v[228:231], v[38:41]
	v_mfma_f32_16x16x32_bf16 v[38:41], v[186:189], v[232:235], v[18:21]
	v_mfma_f32_16x16x32_bf16 v[18:21], v[212:215], v[228:231], v[34:37]
	v_mfma_f32_16x16x32_bf16 v[6:9], v[182:185], v[236:239], v[6:9]
	v_mfma_f32_16x16x32_bf16 v[2:5], v[212:215], v[236:239], v[2:5]
	v_mfma_f32_16x16x32_bf16 v[34:37], v[216:219], v[232:235], v[18:21]
	v_mfma_f32_16x16x32_bf16 v[6:9], v[186:189], v[240:243], v[6:9]
	v_mfma_f32_16x16x32_bf16 v[2:5], v[216:219], v[240:243], v[2:5]
	s_setprio 0
	s_barrier
	s_add_i32 s51, s51, 2
	s_add_u32 s49, s49, 0x100
	s_addc_u32 s50, s50, 0
	s_add_u32 s28, s28, 0x100
	s_addc_u32 s29, s29, 0
	s_cmp_gt_u32 s51, 5
	s_cbranch_scc0 .LBB0_206
	s_and_b64 vcc, exec, s[12:13]
	s_cbranch_vccz .LBB0_209
	s_barrier

; #define PG8_STAGE(bufoff, gbase, voff) do { _Pragma("unroll") for (int _i = 0; _i < 2; ++_i) \
;         __builtin_amdgcn_global_load_lds((const unsigned*)((const char*)(gbase) + (voff)[_i]), (LAS unsigned*)(lds + (bufoff) + ldsw + _i * 8192), 16, 0, 0); } while (0)
; #define PG8_LDA(dst, b, h) do { _Pragma("unroll") for (int m = 0; m < 4; ++m) _Pragma("unroll") for (int k = 0; k < 2; ++k) dst[m][k] = *(const LAS bf16x8*)(lds + PG8_SA(b, h) + aoff + m * 2048 + k * 1024); } while (0)
; #define PG8_LDB(dst, b, h) do { _Pragma("unroll") for (int n = 0; n < 2; ++n) _Pragma("unroll") for (int k = 0; k < 2; ++k) dst[n][k] = *(const LAS bf16x8*)(lds + PG8_SB(b, h) + boff + n * 2048 + k * 1024); } while (0)
; #define PG8_WAIT_V(n) asm volatile("s_waitcnt vmcnt(" #n ")" ::: "memory")
; #define PG8_WAIT_L(n) asm volatile("s_waitcnt lgkmcnt(" #n ")" ::: "memory")
; #define PG8_BAR __builtin_amdgcn_s_barrier()
; #define PG8_SCHED __builtin_amdgcn_sched_barrier(0)
; template <class Epi>
; __device__ __forceinline__ void gemm_phase(LAS unsigned char* lds, const Gemm g, const StaticOrder& S, const Epi& E, const int tid) {
;     ...
;             const bool last = (t == ntt - 2);
;             const bool s1 = Epi::TWO && (t >= nt), s2 = Epi::TWO && (t + 2 >= nt);
;             const char* a1 = (s1 ? cA2 + (size_t)(t - nt + 1) * kstep : cA + (size_t)(t + 1) * kstep);
;             const char* a2 = last ? nA : (s2 ? cA2 + (size_t)(t + 2 - nt) * kstep : cA + (size_t)(t + 2) * kstep);
;             const char* b2 = last ? nB : (s2 ? cB2 + (size_t)(t + 2 - nt) * kstep : cB + (size_t)(t + 2) * kstep);
;             const char* a3 = a2 + kstep; const char* b3 = b2 + kstep;
;             if constexpr (Epi::TWO) { if (t == nt) E.mid(acc, cur, wr, wc, fr, fq); }
;             if constexpr (SP2) {
;             PG8_LDB(B0, 0, 0); PG8_LDB(B1, 0, 1); PG8_SCHED; PG8_LDA(At, 0, 0); PG8_STAGE(PG8_SA(1, 1), a1 + hstep, voffA);
;             PG8_WAIT_V(8); PG8_WAIT_L(0); PG8_BAR; PG8_MMA(0, 0, At, B0); PG8_MMA(0, 1, At, B1); PG8_BAR; PG8_SCHED;
;             PG8_LDA(At, 0, 1); PG8_STAGE(PG8_SB(0, 0), b2, voffB); PG8_STAGE(PG8_SB(0, 1), b2 + bhs, voffB); PG8_STAGE(PG8_SA(0, 0), a2, voffA);
;             PG8_WAIT_V(8); PG8_WAIT_L(0); PG8_BAR; PG8_MMA(1, 0, At, B0); PG8_MMA(1, 1, At, B1); PG8_BAR; PG8_SCHED;
.LBB0_261:
	s_add_u32 s30, s28, 0xfff80080
	s_addc_u32 s31, s29, -1
	s_add_i32 s49, 0, 0x10000
	s_cmp_eq_u32 s48, 28
	s_cselect_b32 s35, s19, s31
	s_cselect_b32 s34, s44, s30
	v_add_u32_e32 v142, s49, v149
	s_cselect_b32 s31, s17, s47
	s_cselect_b32 s30, s45, s46
	s_add_i32 s52, 0, 0x14000
	ds_read_b128 v[156:159], v142
	ds_read_b128 v[160:163], v142 offset:1024
	ds_read_b128 v[164:167], v142 offset:2048
	ds_read_b128 v[178:181], v142 offset:3072
	v_add_u32_e32 v142, s52, v149
	ds_read_b128 v[182:185], v142
	ds_read_b128 v[186:189], v142 offset:1024
	ds_read_b128 v[190:193], v142 offset:2048
	ds_read_b128 v[194:197], v142 offset:3072
	v_lshl_add_u64 v[142:143], s[28:29], 0, v[140:141]
	s_add_i32 m0, s2, 0xc000
	ds_read_b128 v[198:201], v154
	global_load_lds_dwordx4 v[142:143], off
	ds_read_b128 v[212:215], v154 offset:1024
	ds_read_b128 v[216:219], v154 offset:2048
	v_lshl_add_u64 v[142:143], s[28:29], 0, v[138:139]
	s_add_i32 m0, s2, 0xe000
	s_nop 0
	global_load_lds_dwordx4 v[142:143], off
	ds_read_b128 v[220:223], v154 offset:3072
	ds_read_b128 v[224:227], v154 offset:4096
	ds_read_b128 v[228:231], v154 offset:5120
	ds_read_b128 v[232:235], v154 offset:6144
	ds_read_b128 v[236:239], v154 offset:7168
	s_waitcnt vmcnt(8)
	s_waitcnt lgkmcnt(0)
	s_barrier
	s_setprio 1
	v_mfma_f32_16x16x32_bf16 v[126:129], v[156:159], v[198:201], v[126:129]
	v_mfma_f32_16x16x32_bf16 v[122:125], v[164:167], v[198:201], v[122:125]
	v_mfma_f32_16x16x32_bf16 v[110:113], v[156:159], v[216:219], v[110:113]
	v_mfma_f32_16x16x32_bf16 v[106:109], v[164:167], v[216:219], v[106:109]
	v_mfma_f32_16x16x32_bf16 v[94:97], v[156:159], v[224:227], v[94:97]
	v_mfma_f32_16x16x32_bf16 v[90:93], v[164:167], v[224:227], v[90:93]
	v_mfma_f32_16x16x32_bf16 v[78:81], v[156:159], v[232:235], v[78:81]
	v_mfma_f32_16x16x32_bf16 v[74:77], v[164:167], v[232:235], v[74:77]
	v_mfma_f32_16x16x32_bf16 v[126:129], v[160:163], v[212:215], v[126:129]
	v_mfma_f32_16x16x32_bf16 v[122:125], v[178:181], v[212:215], v[122:125]
	v_mfma_f32_16x16x32_bf16 v[110:113], v[160:163], v[220:223], v[110:113]
	v_mfma_f32_16x16x32_bf16 v[106:109], v[178:181], v[220:223], v[106:109]
	v_mfma_f32_16x16x32_bf16 v[94:97], v[160:163], v[228:231], v[94:97]
	v_mfma_f32_16x16x32_bf16 v[90:93], v[178:181], v[228:231], v[90:93]
	v_mfma_f32_16x16x32_bf16 v[78:81], v[160:163], v[236:239], v[78:81]
	v_mfma_f32_16x16x32_bf16 v[74:77], v[178:181], v[236:239], v[74:77]
	v_mfma_f32_16x16x32_bf16 v[118:121], v[182:185], v[198:201], v[118:121]
	v_mfma_f32_16x16x32_bf16 v[114:117], v[190:193], v[198:201], v[114:117]
	v_mfma_f32_16x16x32_bf16 v[102:105], v[182:185], v[216:219], v[102:105]
	v_mfma_f32_16x16x32_bf16 v[98:101], v[190:193], v[216:219], v[98:101]
	v_mfma_f32_16x16x32_bf16 v[86:89], v[182:185], v[224:227], v[86:89]
	v_mfma_f32_16x16x32_bf16 v[82:85], v[190:193], v[224:227], v[82:85]
	v_mfma_f32_16x16x32_bf16 v[70:73], v[182:185], v[232:235], v[70:73]
	v_mfma_f32_16x16x32_bf16 v[66:69], v[190:193], v[232:235], v[66:69]
	v_mfma_f32_16x16x32_bf16 v[118:121], v[186:189], v[212:215], v[118:121]
	v_mfma_f32_16x16x32_bf16 v[114:117], v[194:197], v[212:215], v[114:117]
	v_mfma_f32_16x16x32_bf16 v[102:105], v[186:189], v[220:223], v[102:105]
	v_mfma_f32_16x16x32_bf16 v[98:101], v[194:197], v[220:223], v[98:101]
	v_mfma_f32_16x16x32_bf16 v[86:89], v[186:189], v[228:231], v[86:89]
	v_mfma_f32_16x16x32_bf16 v[82:85], v[194:197], v[228:231], v[82:85]
	v_mfma_f32_16x16x32_bf16 v[70:73], v[186:189], v[236:239], v[70:73]
	v_mfma_f32_16x16x32_bf16 v[66:69], v[194:197], v[236:239], v[66:69]
	s_setprio 0
	s_barrier
	s_add_i32 s49, s49, s36
	v_lshl_add_u64 v[142:143], s[30:31], 0, v[0:1]
	s_mov_b32 m0, s49
	ds_read_b128 v[198:201], v154 offset:16384
	global_load_lds_dwordx4 v[142:143], off
	ds_read_b128 v[212:215], v154 offset:17408
	ds_read_b128 v[216:219], v154 offset:18432
	s_add_i32 m0, s49, 0x2000
	s_add_u32 s50, s30, 0x8000
	v_lshl_add_u64 v[168:169], s[30:31], 0, v[134:135]
	s_addc_u32 s51, s31, 0
	s_add_i32 s49, s52, s36
	global_load_lds_dwordx4 v[168:169], off
	ds_read_b128 v[220:223], v154 offset:19456
	ds_read_b128 v[224:227], v154 offset:20480
	v_lshl_add_u64 v[172:173], s[50:51], 0, v[0:1]
	s_mov_b32 m0, s49
	v_lshl_add_u64 v[174:175], s[34:35], 0, v[132:133]
	global_load_lds_dwordx4 v[172:173], off
	ds_read_b128 v[228:231], v154 offset:21504
	ds_read_b128 v[232:235], v154 offset:22528
	v_lshl_add_u64 v[172:173], s[50:51], 0, v[134:135]
	s_add_i32 m0, s49, 0x2000
	s_nop 0
	global_load_lds_dwordx4 v[172:173], off
	ds_read_b128 v[236:239], v154 offset:23552
	v_lshl_add_u64 v[172:173], s[34:35], 0, v[130:131]
	s_mov_b32 m0, s2
	s_nop 0
	global_load_lds_dwordx4 v[172:173], off
	s_mov_b32 m0, s27
	s_nop 0
	global_load_lds_dwordx4 v[174:175], off
	s_waitcnt vmcnt(8)
	s_waitcnt lgkmcnt(0)
	s_barrier
; #define PG8_STAGE(bufoff, gbase, voff) do { _Pragma("unroll") for (int _i = 0; _i < 2; ++_i) \
;         __builtin_amdgcn_global_load_lds((const unsigned*)((const char*)(gbase) + (voff)[_i]), (LAS unsigned*)(lds + (bufoff) + ldsw + _i * 8192), 16, 0, 0); } while (0)
; #define PG8_LDA(dst, b, h) do { _Pragma("unroll") for (int m = 0; m < 4; ++m) _Pragma("unroll") for (int k = 0; k < 2; ++k) dst[m][k] = *(const LAS bf16x8*)(lds + PG8_SA(b, h) + aoff + m * 2048 + k * 1024); } while (0)
; #define PG8_LDB(dst, b, h) do { _Pragma("unroll") for (int n = 0; n < 2; ++n) _Pragma("unroll") for (int k = 0; k < 2; ++k) dst[n][k] = *(const LAS bf16x8*)(lds + PG8_SB(b, h) + boff + n * 2048 + k * 1024); } while (0)
; #define PG8_MMA(ai, bj, At, Bt) do { __builtin_amdgcn_s_setprio(1); _Pragma("unroll") for (int m = 0; m < 4; ++m) _Pragma("unroll") for (int n = 0; n < 2; ++n) _Pragma("unroll") for (int k = 0; k < 2; ++k) \
;         acc[ai][bj][m][n] = __builtin_amdgcn_mfma_f32_16x16x32_bf16(Bt[n][k], At[m][k], acc[ai][bj][m][n], 0, 0, 0); __builtin_amdgcn_s_setprio(0); } while (0)
; #define PG8_WAIT_V(n) asm volatile("s_waitcnt vmcnt(" #n ")" ::: "memory")
; #define PG8_WAIT_L(n) asm volatile("s_waitcnt lgkmcnt(" #n ")" ::: "memory")
; #define PG8_BAR __builtin_amdgcn_s_barrier()
; #define PG8_SCHED __builtin_amdgcn_sched_barrier(0)
; template <class Epi>
; __device__ __forceinline__ void gemm_phase(LAS unsigned char* lds, const Gemm g, const StaticOrder& S, const Epi& E, const int tid) {
;     ...
;             PG8_WAIT_V(8); PG8_WAIT_L(0); PG8_BAR; PG8_MMA(1, 0, At, B0); PG8_MMA(1, 1, At, B1); PG8_BAR; PG8_SCHED;
;             PG8_LDB(B0, 1, 0); PG8_LDB(B1, 1, 1); PG8_SCHED; PG8_LDA(At, 1, 0); PG8_STAGE(PG8_SA(0, 1), a2 + hstep, voffA);
;             PG8_WAIT_V(8); PG8_WAIT_L(0); PG8_BAR; PG8_MMA(0, 0, At, B0); PG8_MMA(0, 1, At, B1); PG8_BAR; PG8_SCHED;
	s_setprio 1
	v_mfma_f32_16x16x32_bf16 v[62:65], v[156:159], v[198:201], v[62:65]
	v_mfma_f32_16x16x32_bf16 v[58:61], v[164:167], v[198:201], v[58:61]
	v_mfma_f32_16x16x32_bf16 v[46:49], v[156:159], v[216:219], v[46:49]
	v_mfma_f32_16x16x32_bf16 v[42:45], v[164:167], v[216:219], v[42:45]
	v_mfma_f32_16x16x32_bf16 v[30:33], v[156:159], v[224:227], v[30:33]
	v_mfma_f32_16x16x32_bf16 v[26:29], v[164:167], v[224:227], v[26:29]
	v_mfma_f32_16x16x32_bf16 v[14:17], v[156:159], v[232:235], v[14:17]
	v_mfma_f32_16x16x32_bf16 v[10:13], v[164:167], v[232:235], v[10:13]
	v_mfma_f32_16x16x32_bf16 v[62:65], v[160:163], v[212:215], v[62:65]
	v_mfma_f32_16x16x32_bf16 v[58:61], v[178:181], v[212:215], v[58:61]
	v_mfma_f32_16x16x32_bf16 v[46:49], v[160:163], v[220:223], v[46:49]
	v_mfma_f32_16x16x32_bf16 v[42:45], v[178:181], v[220:223], v[42:45]
	v_mfma_f32_16x16x32_bf16 v[30:33], v[160:163], v[228:231], v[30:33]
	v_mfma_f32_16x16x32_bf16 v[26:29], v[178:181], v[228:231], v[26:29]
	v_mfma_f32_16x16x32_bf16 v[14:17], v[160:163], v[236:239], v[14:17]
	v_mfma_f32_16x16x32_bf16 v[10:13], v[178:181], v[236:239], v[10:13]
	v_mfma_f32_16x16x32_bf16 v[54:57], v[182:185], v[198:201], v[54:57]
	v_mfma_f32_16x16x32_bf16 v[50:53], v[190:193], v[198:201], v[50:53]
	v_mfma_f32_16x16x32_bf16 v[38:41], v[182:185], v[216:219], v[38:41]
	v_mfma_f32_16x16x32_bf16 v[34:37], v[190:193], v[216:219], v[34:37]
	v_mfma_f32_16x16x32_bf16 v[22:25], v[182:185], v[224:227], v[22:25]
	v_mfma_f32_16x16x32_bf16 v[18:21], v[190:193], v[224:227], v[18:21]
	v_mfma_f32_16x16x32_bf16 v[6:9], v[182:185], v[232:235], v[6:9]
	v_mfma_f32_16x16x32_bf16 v[2:5], v[190:193], v[232:235], v[2:5]
	v_mfma_f32_16x16x32_bf16 v[54:57], v[186:189], v[212:215], v[54:57]
	v_mfma_f32_16x16x32_bf16 v[50:53], v[194:197], v[212:215], v[50:53]
	v_mfma_f32_16x16x32_bf16 v[38:41], v[186:189], v[220:223], v[38:41]
	v_mfma_f32_16x16x32_bf16 v[34:37], v[194:197], v[220:223], v[34:37]
	v_mfma_f32_16x16x32_bf16 v[22:25], v[186:189], v[228:231], v[22:25]
	v_mfma_f32_16x16x32_bf16 v[18:21], v[194:197], v[228:231], v[18:21]
	v_mfma_f32_16x16x32_bf16 v[6:9], v[186:189], v[236:239], v[6:9]
	v_mfma_f32_16x16x32_bf16 v[2:5], v[194:197], v[236:239], v[2:5]
	s_setprio 0
	s_barrier
	s_add_i32 s49, 0, 0x18000
	v_add_u32_e32 v155, s49, v149
	s_add_i32 s50, 0, 0x1c000
	ds_read_b128 v[156:159], v155
	ds_read_b128 v[160:163], v155 offset:1024
	ds_read_b128 v[164:167], v155 offset:2048
	ds_read_b128 v[178:181], v155 offset:3072
	v_add_u32_e32 v155, s50, v149
	ds_read_b128 v[182:185], v155
	ds_read_b128 v[186:189], v155 offset:1024
	ds_read_b128 v[190:193], v155 offset:2048
	ds_read_b128 v[194:197], v155 offset:3072
	s_add_u32 s34, s34, 0x80000
	s_addc_u32 s35, s35, 0
	s_mov_b32 m0, s37
	v_lshl_add_u64 v[176:177], s[34:35], 0, v[130:131]
	ds_read_b128 v[198:201], v154 offset:32768
	global_load_lds_dwordx4 v[176:177], off
	ds_read_b128 v[212:215], v154 offset:33792
	ds_read_b128 v[216:219], v154 offset:34816
	v_lshl_add_u64 v[176:177], s[34:35], 0, v[132:133]
	s_mov_b32 m0, s38
	s_nop 0
	global_load_lds_dwordx4 v[176:177], off
	ds_read_b128 v[220:223], v154 offset:35840
	ds_read_b128 v[224:227], v154 offset:36864
	ds_read_b128 v[228:231], v154 offset:37888
	ds_read_b128 v[232:235], v154 offset:38912
	ds_read_b128 v[236:239], v154 offset:39936
	s_waitcnt vmcnt(8)
	s_waitcnt lgkmcnt(0)
	s_barrier
	s_setprio 1
	v_mfma_f32_16x16x32_bf16 v[126:129], v[156:159], v[198:201], v[126:129]
	v_mfma_f32_16x16x32_bf16 v[122:125], v[164:167], v[198:201], v[122:125]
	v_mfma_f32_16x16x32_bf16 v[110:113], v[156:159], v[216:219], v[110:113]
	v_mfma_f32_16x16x32_bf16 v[106:109], v[164:167], v[216:219], v[106:109]
	v_mfma_f32_16x16x32_bf16 v[94:97], v[156:159], v[224:227], v[94:97]
	v_mfma_f32_16x16x32_bf16 v[90:93], v[164:167], v[224:227], v[90:93]
	v_mfma_f32_16x16x32_bf16 v[78:81], v[156:159], v[232:235], v[78:81]
	v_mfma_f32_16x16x32_bf16 v[74:77], v[164:167], v[232:235], v[74:77]
	v_mfma_f32_16x16x32_bf16 v[126:129], v[160:163], v[212:215], v[126:129]
	v_mfma_f32_16x16x32_bf16 v[122:125], v[178:181], v[212:215], v[122:125]
	v_mfma_f32_16x16x32_bf16 v[110:113], v[160:163], v[220:223], v[110:113]
	v_mfma_f32_16x16x32_bf16 v[106:109], v[178:181], v[220:223], v[106:109]
	v_mfma_f32_16x16x32_bf16 v[94:97], v[160:163], v[228:231], v[94:97]
	v_mfma_f32_16x16x32_bf16 v[90:93], v[178:181], v[228:231], v[90:93]
	v_mfma_f32_16x16x32_bf16 v[78:81], v[160:163], v[236:239], v[78:81]
	v_mfma_f32_16x16x32_bf16 v[74:77], v[178:181], v[236:239], v[74:77]
	v_mfma_f32_16x16x32_bf16 v[118:121], v[182:185], v[198:201], v[118:121]
	v_mfma_f32_16x16x32_bf16 v[114:117], v[190:193], v[198:201], v[114:117]
	v_mfma_f32_16x16x32_bf16 v[102:105], v[182:185], v[216:219], v[102:105]
	v_mfma_f32_16x16x32_bf16 v[98:101], v[190:193], v[216:219], v[98:101]
	v_mfma_f32_16x16x32_bf16 v[86:89], v[182:185], v[224:227], v[86:89]
	v_mfma_f32_16x16x32_bf16 v[82:85], v[190:193], v[224:227], v[82:85]
	v_mfma_f32_16x16x32_bf16 v[70:73], v[182:185], v[232:235], v[70:73]
	v_mfma_f32_16x16x32_bf16 v[66:69], v[190:193], v[232:235], v[66:69]
	v_mfma_f32_16x16x32_bf16 v[118:121], v[186:189], v[212:215], v[118:121]
	v_mfma_f32_16x16x32_bf16 v[114:117], v[194:197], v[212:215], v[114:117]
	v_mfma_f32_16x16x32_bf16 v[102:105], v[186:189], v[220:223], v[102:105]
	v_mfma_f32_16x16x32_bf16 v[98:101], v[194:197], v[220:223], v[98:101]
	v_mfma_f32_16x16x32_bf16 v[86:89], v[186:189], v[228:231], v[86:89]
	v_mfma_f32_16x16x32_bf16 v[82:85], v[194:197], v[228:231], v[82:85]
	v_mfma_f32_16x16x32_bf16 v[70:73], v[186:189], v[236:239], v[70:73]
	v_mfma_f32_16x16x32_bf16 v[66:69], v[194:197], v[236:239], v[66:69]
	s_setprio 0
	s_barrier
; #define PG8_STAGE(bufoff, gbase, voff) do { _Pragma("unroll") for (int _i = 0; _i < 2; ++_i) \
;         __builtin_amdgcn_global_load_lds((const unsigned*)((const char*)(gbase) + (voff)[_i]), (LAS unsigned*)(lds + (bufoff) + ldsw + _i * 8192), 16, 0, 0); } while (0)
; #define PG8_LDA(dst, b, h) do { _Pragma("unroll") for (int m = 0; m < 4; ++m) _Pragma("unroll") for (int k = 0; k < 2; ++k) dst[m][k] = *(const LAS bf16x8*)(lds + PG8_SA(b, h) + aoff + m * 2048 + k * 1024); } while (0)
; #define PG8_MMA(ai, bj, At, Bt) do { __builtin_amdgcn_s_setprio(1); _Pragma("unroll") for (int m = 0; m < 4; ++m) _Pragma("unroll") for (int n = 0; n < 2; ++n) _Pragma("unroll") for (int k = 0; k < 2; ++k) \
;         acc[ai][bj][m][n] = __builtin_amdgcn_mfma_f32_16x16x32_bf16(Bt[n][k], At[m][k], acc[ai][bj][m][n], 0, 0, 0); __builtin_amdgcn_s_setprio(0); } while (0)
; #define PG8_WAIT_V(n) asm volatile("s_waitcnt vmcnt(" #n ")" ::: "memory")
; #define PG8_WAIT_L(n) asm volatile("s_waitcnt lgkmcnt(" #n ")" ::: "memory")
; #define PG8_BAR __builtin_amdgcn_s_barrier()
; #define PG8_SCHED __builtin_amdgcn_sched_barrier(0)
; template <class Epi>
; __device__ __forceinline__ void gemm_phase(LAS unsigned char* lds, const Gemm g, const StaticOrder& S, const Epi& E, const int tid) {
;     ...
;             PG8_LDA(At, 1, 1); PG8_STAGE(PG8_SB(1, 0), b3, voffB); PG8_STAGE(PG8_SB(1, 1), b3 + bhs, voffB); PG8_STAGE(PG8_SA(1, 0), a3, voffA);
;             PG8_WAIT_V(8); PG8_WAIT_L(0); PG8_BAR; PG8_MMA(1, 0, At, B0); PG8_MMA(1, 1, At, B1); PG8_BAR; PG8_SCHED;
	s_add_i32 s34, s49, s36
	v_lshl_add_u64 v[142:143], v[142:143], 0, s[70:71]
	s_mov_b32 m0, s34
	ds_read_b128 v[198:201], v154 offset:49152
	global_load_lds_dwordx4 v[142:143], off
	ds_read_b128 v[212:215], v154 offset:50176
	ds_read_b128 v[216:219], v154 offset:51200
	s_add_i32 m0, s34, 0x2000
	s_add_u32 s30, s30, 0x8080
	v_lshl_add_u64 v[142:143], v[168:169], 0, s[70:71]
	s_addc_u32 s31, s31, 0
	s_add_i32 s34, s50, s36
	global_load_lds_dwordx4 v[142:143], off
	ds_read_b128 v[220:223], v154 offset:52224
	ds_read_b128 v[224:227], v154 offset:53248
	v_lshl_add_u64 v[142:143], s[30:31], 0, v[0:1]
	s_mov_b32 m0, s34
	s_nop 0
	global_load_lds_dwordx4 v[142:143], off
	ds_read_b128 v[228:231], v154 offset:54272
	ds_read_b128 v[232:235], v154 offset:55296
	v_lshl_add_u64 v[142:143], s[30:31], 0, v[134:135]
	s_add_i32 m0, s34, 0x2000
	s_nop 0
	global_load_lds_dwordx4 v[142:143], off
	ds_read_b128 v[236:239], v154 offset:56320
	v_lshl_add_u64 v[142:143], v[172:173], 0, s[70:71]
	s_mov_b32 m0, s39
	s_nop 0
	global_load_lds_dwordx4 v[142:143], off
	v_lshl_add_u64 v[142:143], v[174:175], 0, s[70:71]
	s_mov_b32 m0, s40
	s_nop 0
	global_load_lds_dwordx4 v[142:143], off
	s_waitcnt vmcnt(8)
	s_waitcnt lgkmcnt(0)
	s_barrier
	s_setprio 1
	v_mfma_f32_16x16x32_bf16 v[62:65], v[156:159], v[198:201], v[62:65]
	v_mfma_f32_16x16x32_bf16 v[58:61], v[164:167], v[198:201], v[58:61]
	v_mfma_f32_16x16x32_bf16 v[46:49], v[156:159], v[216:219], v[46:49]
	v_mfma_f32_16x16x32_bf16 v[42:45], v[164:167], v[216:219], v[42:45]
	v_mfma_f32_16x16x32_bf16 v[30:33], v[156:159], v[224:227], v[30:33]
	v_mfma_f32_16x16x32_bf16 v[26:29], v[164:167], v[224:227], v[26:29]
	v_mfma_f32_16x16x32_bf16 v[14:17], v[156:159], v[232:235], v[14:17]
	v_mfma_f32_16x16x32_bf16 v[10:13], v[164:167], v[232:235], v[10:13]
	v_mfma_f32_16x16x32_bf16 v[62:65], v[160:163], v[212:215], v[62:65]
	v_mfma_f32_16x16x32_bf16 v[58:61], v[178:181], v[212:215], v[58:61]
	v_mfma_f32_16x16x32_bf16 v[46:49], v[160:163], v[220:223], v[46:49]
	v_mfma_f32_16x16x32_bf16 v[42:45], v[178:181], v[220:223], v[42:45]
	v_mfma_f32_16x16x32_bf16 v[30:33], v[160:163], v[228:231], v[30:33]
	v_mfma_f32_16x16x32_bf16 v[26:29], v[178:181], v[228:231], v[26:29]
	v_mfma_f32_16x16x32_bf16 v[14:17], v[160:163], v[236:239], v[14:17]
	v_mfma_f32_16x16x32_bf16 v[10:13], v[178:181], v[236:239], v[10:13]
	v_mfma_f32_16x16x32_bf16 v[54:57], v[182:185], v[198:201], v[54:57]
	v_mfma_f32_16x16x32_bf16 v[50:53], v[190:193], v[198:201], v[50:53]
	v_mfma_f32_16x16x32_bf16 v[38:41], v[182:185], v[216:219], v[38:41]
	v_mfma_f32_16x16x32_bf16 v[34:37], v[190:193], v[216:219], v[34:37]
	v_mfma_f32_16x16x32_bf16 v[22:25], v[182:185], v[224:227], v[22:25]
	v_mfma_f32_16x16x32_bf16 v[18:21], v[190:193], v[224:227], v[18:21]
	v_mfma_f32_16x16x32_bf16 v[6:9], v[182:185], v[232:235], v[6:9]
	v_mfma_f32_16x16x32_bf16 v[2:5], v[190:193], v[232:235], v[2:5]
	v_mfma_f32_16x16x32_bf16 v[54:57], v[186:189], v[212:215], v[54:57]
	v_mfma_f32_16x16x32_bf16 v[50:53], v[194:197], v[212:215], v[50:53]
	v_mfma_f32_16x16x32_bf16 v[38:41], v[186:189], v[220:223], v[38:41]
	v_mfma_f32_16x16x32_bf16 v[34:37], v[194:197], v[220:223], v[34:37]
	v_mfma_f32_16x16x32_bf16 v[22:25], v[186:189], v[228:231], v[22:25]
	v_mfma_f32_16x16x32_bf16 v[18:21], v[194:197], v[228:231], v[18:21]
	v_mfma_f32_16x16x32_bf16 v[6:9], v[186:189], v[236:239], v[6:9]
	v_mfma_f32_16x16x32_bf16 v[2:5], v[194:197], v[236:239], v[2:5]
	s_setprio 0
	s_barrier
	s_add_i32 s48, s48, 2
	s_add_u32 s46, s46, 0x100
	s_addc_u32 s47, s47, 0
	s_add_u32 s28, s28, 0x100
	s_addc_u32 s29, s29, 0
	s_cmp_gt_u32 s48, 29
	s_cbranch_scc0 .LBB0_261
	s_and_b64 vcc, exec, s[14:15]
	s_cbranch_vccz .LBB0_264
	s_barrier

; #define PG8_STAGE(bufoff, gbase, voff) do { _Pragma("unroll") for (int _i = 0; _i < 2; ++_i) \
;         __builtin_amdgcn_global_load_lds((const unsigned*)((const char*)(gbase) + (voff)[_i]), (LAS unsigned*)(lds + (bufoff) + ldsw + _i * 8192), 16, 0, 0); } while (0)
; #define PG8_LDA(dst, b, h) do { _Pragma("unroll") for (int m = 0; m < 4; ++m) _Pragma("unroll") for (int k = 0; k < 2; ++k) dst[m][k] = *(const LAS bf16x8*)(lds + PG8_SA(b, h) + aoff + m * 2048 + k * 1024); } while (0)
; #define PG8_LDB(dst, b, h) do { _Pragma("unroll") for (int n = 0; n < 2; ++n) _Pragma("unroll") for (int k = 0; k < 2; ++k) dst[n][k] = *(const LAS bf16x8*)(lds + PG8_SB(b, h) + boff + n * 2048 + k * 1024); } while (0)
; #define PG8_WAIT_V(n) asm volatile("s_waitcnt vmcnt(" #n ")" ::: "memory")
; #define PG8_WAIT_L(n) asm volatile("s_waitcnt lgkmcnt(" #n ")" ::: "memory")
; #define PG8_BAR __builtin_amdgcn_s_barrier()
; #define PG8_SCHED __builtin_amdgcn_sched_barrier(0)
; template <class Epi>
; __device__ __forceinline__ void gemm_phase(LAS unsigned char* lds, const Gemm g, const StaticOrder& S, const Epi& E, const int tid) {
;     ...
;             const bool last = (t == ntt - 2);
;             const bool s1 = Epi::TWO && (t >= nt), s2 = Epi::TWO && (t + 2 >= nt);
;             const char* a1 = (s1 ? cA2 + (size_t)(t - nt + 1) * kstep : cA + (size_t)(t + 1) * kstep);
;             const char* a2 = last ? nA : (s2 ? cA2 + (size_t)(t + 2 - nt) * kstep : cA + (size_t)(t + 2) * kstep);
;             const char* b2 = last ? nB : (s2 ? cB2 + (size_t)(t + 2 - nt) * kstep : cB + (size_t)(t + 2) * kstep);
;             const char* a3 = a2 + kstep; const char* b3 = b2 + kstep;
;             if constexpr (Epi::TWO) { if (t == nt) E.mid(acc, cur, wr, wc, fr, fq); }
;             if constexpr (SP2) {
;             PG8_LDB(B0, 0, 0); PG8_LDB(B1, 0, 1); PG8_SCHED; PG8_LDA(At, 0, 0); PG8_STAGE(PG8_SA(1, 1), a1 + hstep, voffA);
;             PG8_WAIT_V(8); PG8_WAIT_L(0); PG8_BAR; PG8_MMA(0, 0, At, B0); PG8_MMA(0, 1, At, B1); PG8_BAR; PG8_SCHED;
;             PG8_LDA(At, 0, 1); PG8_STAGE(PG8_SB(0, 0), b2, voffB); PG8_STAGE(PG8_SB(0, 1), b2 + bhs, voffB); PG8_STAGE(PG8_SA(0, 0), a2, voffA);
;             PG8_WAIT_V(8); PG8_WAIT_L(0); PG8_BAR; PG8_MMA(1, 0, At, B0); PG8_MMA(1, 1, At, B1); PG8_BAR; PG8_SCHED;
.LBB0_314:
	s_add_u32 s40, s6, 0xfff80080
	s_addc_u32 s41, s7, -1
	s_add_i32 s56, 0, 0x10000
	s_cmp_eq_u32 s55, 28
	s_cselect_b32 s43, s27, s41
	s_cselect_b32 s42, s39, s40
	s_cselect_b32 s41, s25, s54
	s_cselect_b32 s40, s52, s53
	s_add_i32 s58, 0, 0x14000
	v_add_u32_e32 v46, s56, v212
	v_add_u32_e32 v70, s58, v212
	ds_read_b128 v[34:37], v46
	ds_read_b128 v[38:41], v46 offset:1024
	ds_read_b128 v[42:45], v46 offset:2048
	ds_read_b128 v[46:49], v46 offset:3072
	ds_read_b128 v[58:61], v70
	ds_read_b128 v[62:65], v70 offset:1024
	ds_read_b128 v[66:69], v70 offset:2048
	ds_read_b128 v[70:73], v70 offset:3072
	v_lshl_add_u64 v[172:173], s[6:7], 0, v[188:189]
	s_add_i32 m0, s44, 0xc000
	ds_read_b128 v[162:165], v220
	global_load_lds_dwordx4 v[172:173], off
	ds_read_b128 v[166:169], v220 offset:1024
	ds_read_b128 v[190:193], v220 offset:2048
	v_lshl_add_u64 v[172:173], s[6:7], 0, v[186:187]
	s_add_i32 m0, s44, 0xe000
	s_nop 0
	global_load_lds_dwordx4 v[172:173], off
	ds_read_b128 v[194:197], v220 offset:3072
	ds_read_b128 v[198:201], v220 offset:4096
	ds_read_b128 v[222:225], v220 offset:5120
	ds_read_b128 v[226:229], v220 offset:6144
	ds_read_b128 v[230:233], v220 offset:7168
	s_waitcnt vmcnt(8)
	s_waitcnt lgkmcnt(0)
	s_barrier
	s_setprio 1
	v_mfma_f32_16x16x32_bf16 v[158:161], v[34:37], v[162:165], v[158:161]
	v_mfma_f32_16x16x32_bf16 v[154:157], v[42:45], v[162:165], v[154:157]
	v_mfma_f32_16x16x32_bf16 v[142:145], v[34:37], v[190:193], v[142:145]
	v_mfma_f32_16x16x32_bf16 v[138:141], v[42:45], v[190:193], v[138:141]
	v_mfma_f32_16x16x32_bf16 v[126:129], v[34:37], v[198:201], v[126:129]
	v_mfma_f32_16x16x32_bf16 v[122:125], v[42:45], v[198:201], v[122:125]
	v_mfma_f32_16x16x32_bf16 v[110:113], v[34:37], v[226:229], v[110:113]
	v_mfma_f32_16x16x32_bf16 v[106:109], v[42:45], v[226:229], v[106:109]
	v_mfma_f32_16x16x32_bf16 v[158:161], v[38:41], v[166:169], v[158:161]
	v_mfma_f32_16x16x32_bf16 v[154:157], v[46:49], v[166:169], v[154:157]
	v_mfma_f32_16x16x32_bf16 v[142:145], v[38:41], v[194:197], v[142:145]
	v_mfma_f32_16x16x32_bf16 v[138:141], v[46:49], v[194:197], v[138:141]
	v_mfma_f32_16x16x32_bf16 v[126:129], v[38:41], v[222:225], v[126:129]
	v_mfma_f32_16x16x32_bf16 v[122:125], v[46:49], v[222:225], v[122:125]
	v_mfma_f32_16x16x32_bf16 v[110:113], v[38:41], v[230:233], v[110:113]
	v_mfma_f32_16x16x32_bf16 v[106:109], v[46:49], v[230:233], v[106:109]
	v_mfma_f32_16x16x32_bf16 v[150:153], v[58:61], v[162:165], v[150:153]
	v_mfma_f32_16x16x32_bf16 v[146:149], v[66:69], v[162:165], v[146:149]
	v_mfma_f32_16x16x32_bf16 v[134:137], v[58:61], v[190:193], v[134:137]
	v_mfma_f32_16x16x32_bf16 v[130:133], v[66:69], v[190:193], v[130:133]
	v_mfma_f32_16x16x32_bf16 v[118:121], v[58:61], v[198:201], v[118:121]
	v_mfma_f32_16x16x32_bf16 v[114:117], v[66:69], v[198:201], v[114:117]
	v_mfma_f32_16x16x32_bf16 v[102:105], v[58:61], v[226:229], v[102:105]
	v_mfma_f32_16x16x32_bf16 v[98:101], v[66:69], v[226:229], v[98:101]
	v_mfma_f32_16x16x32_bf16 v[150:153], v[62:65], v[166:169], v[150:153]
	v_mfma_f32_16x16x32_bf16 v[146:149], v[70:73], v[166:169], v[146:149]
	v_mfma_f32_16x16x32_bf16 v[134:137], v[62:65], v[194:197], v[134:137]
	v_mfma_f32_16x16x32_bf16 v[130:133], v[70:73], v[194:197], v[130:133]
	v_mfma_f32_16x16x32_bf16 v[118:121], v[62:65], v[222:225], v[118:121]
	v_mfma_f32_16x16x32_bf16 v[114:117], v[70:73], v[222:225], v[114:117]
	v_mfma_f32_16x16x32_bf16 v[102:105], v[62:65], v[230:233], v[102:105]
	v_mfma_f32_16x16x32_bf16 v[98:101], v[70:73], v[230:233], v[98:101]
	s_setprio 0
	s_barrier
	s_add_i32 s56, s56, s33
	v_lshl_add_u64 v[172:173], s[40:41], 0, v[0:1]
	s_mov_b32 m0, s56
	ds_read_b128 v[162:165], v220 offset:16384
	global_load_lds_dwordx4 v[172:173], off
	ds_read_b128 v[166:169], v220 offset:17408
	ds_read_b128 v[190:193], v220 offset:18432
	s_add_i32 m0, s56, 0x2000
	s_add_u32 s56, s40, 0x8000
	v_lshl_add_u64 v[174:175], s[40:41], 0, v[182:183]
	s_addc_u32 s57, s41, 0
	s_add_i32 s58, s58, s33
	global_load_lds_dwordx4 v[174:175], off
	ds_read_b128 v[194:197], v220 offset:19456
	ds_read_b128 v[198:201], v220 offset:20480
	v_lshl_add_u64 v[176:177], s[56:57], 0, v[0:1]
	s_mov_b32 m0, s58
	v_lshl_add_u64 v[238:239], s[42:43], 0, v[180:181]
	global_load_lds_dwordx4 v[176:177], off
	ds_read_b128 v[222:225], v220 offset:21504
	ds_read_b128 v[226:229], v220 offset:22528
	v_lshl_add_u64 v[176:177], s[56:57], 0, v[182:183]
	s_add_i32 m0, s58, 0x2000
	s_nop 0
	global_load_lds_dwordx4 v[176:177], off
	ds_read_b128 v[230:233], v220 offset:23552
	v_lshl_add_u64 v[176:177], s[42:43], 0, v[178:179]
	s_mov_b32 m0, s44
	s_nop 0
	global_load_lds_dwordx4 v[176:177], off
	s_mov_b32 m0, s45
	s_nop 0
	global_load_lds_dwordx4 v[238:239], off
	s_waitcnt vmcnt(8)
	s_waitcnt lgkmcnt(0)
	s_barrier
; #define PG8_STAGE(bufoff, gbase, voff) do { _Pragma("unroll") for (int _i = 0; _i < 2; ++_i) \
;         __builtin_amdgcn_global_load_lds((const unsigned*)((const char*)(gbase) + (voff)[_i]), (LAS unsigned*)(lds + (bufoff) + ldsw + _i * 8192), 16, 0, 0); } while (0)
; #define PG8_LDA(dst, b, h) do { _Pragma("unroll") for (int m = 0; m < 4; ++m) _Pragma("unroll") for (int k = 0; k < 2; ++k) dst[m][k] = *(const LAS bf16x8*)(lds + PG8_SA(b, h) + aoff + m * 2048 + k * 1024); } while (0)
; #define PG8_LDB(dst, b, h) do { _Pragma("unroll") for (int n = 0; n < 2; ++n) _Pragma("unroll") for (int k = 0; k < 2; ++k) dst[n][k] = *(const LAS bf16x8*)(lds + PG8_SB(b, h) + boff + n * 2048 + k * 1024); } while (0)
; #define PG8_MMA(ai, bj, At, Bt) do { __builtin_amdgcn_s_setprio(1); _Pragma("unroll") for (int m = 0; m < 4; ++m) _Pragma("unroll") for (int n = 0; n < 2; ++n) _Pragma("unroll") for (int k = 0; k < 2; ++k) \
;         acc[ai][bj][m][n] = __builtin_amdgcn_mfma_f32_16x16x32_bf16(Bt[n][k], At[m][k], acc[ai][bj][m][n], 0, 0, 0); __builtin_amdgcn_s_setprio(0); } while (0)
; #define PG8_WAIT_V(n) asm volatile("s_waitcnt vmcnt(" #n ")" ::: "memory")
; #define PG8_WAIT_L(n) asm volatile("s_waitcnt lgkmcnt(" #n ")" ::: "memory")
; #define PG8_BAR __builtin_amdgcn_s_barrier()
; #define PG8_SCHED __builtin_amdgcn_sched_barrier(0)
; template <class Epi>
; __device__ __forceinline__ void gemm_phase(LAS unsigned char* lds, const Gemm g, const StaticOrder& S, const Epi& E, const int tid) {
;     ...
;             PG8_WAIT_V(8); PG8_WAIT_L(0); PG8_BAR; PG8_MMA(1, 0, At, B0); PG8_MMA(1, 1, At, B1); PG8_BAR; PG8_SCHED;
;             PG8_LDB(B0, 1, 0); PG8_LDB(B1, 1, 1); PG8_SCHED; PG8_LDA(At, 1, 0); PG8_STAGE(PG8_SA(0, 1), a2 + hstep, voffA);
;             PG8_WAIT_V(8); PG8_WAIT_L(0); PG8_BAR; PG8_MMA(0, 0, At, B0); PG8_MMA(0, 1, At, B1); PG8_BAR; PG8_SCHED;
	s_setprio 1
	v_mfma_f32_16x16x32_bf16 v[94:97], v[34:37], v[162:165], v[94:97]
	v_mfma_f32_16x16x32_bf16 v[90:93], v[42:45], v[162:165], v[90:93]
	v_mfma_f32_16x16x32_bf16 v[78:81], v[34:37], v[190:193], v[78:81]
	v_mfma_f32_16x16x32_bf16 v[74:77], v[42:45], v[190:193], v[74:77]
	v_mfma_f32_16x16x32_bf16 v[30:33], v[34:37], v[198:201], v[30:33]
	v_mfma_f32_16x16x32_bf16 v[26:29], v[42:45], v[198:201], v[26:29]
	v_mfma_f32_16x16x32_bf16 v[14:17], v[34:37], v[226:229], v[14:17]
	v_mfma_f32_16x16x32_bf16 v[10:13], v[42:45], v[226:229], v[10:13]
	v_mfma_f32_16x16x32_bf16 v[94:97], v[38:41], v[166:169], v[94:97]
	v_mfma_f32_16x16x32_bf16 v[90:93], v[46:49], v[166:169], v[90:93]
	v_mfma_f32_16x16x32_bf16 v[78:81], v[38:41], v[194:197], v[78:81]
	v_mfma_f32_16x16x32_bf16 v[74:77], v[46:49], v[194:197], v[74:77]
	v_mfma_f32_16x16x32_bf16 v[30:33], v[38:41], v[222:225], v[30:33]
	v_mfma_f32_16x16x32_bf16 v[26:29], v[46:49], v[222:225], v[26:29]
	v_mfma_f32_16x16x32_bf16 v[14:17], v[38:41], v[230:233], v[14:17]
	v_mfma_f32_16x16x32_bf16 v[10:13], v[46:49], v[230:233], v[10:13]
	v_mfma_f32_16x16x32_bf16 v[22:25], v[58:61], v[198:201], v[22:25]
	v_mfma_f32_16x16x32_bf16 v[18:21], v[66:69], v[198:201], v[18:21]
	v_mfma_f32_16x16x32_bf16 v[6:9], v[58:61], v[226:229], v[6:9]
	v_mfma_f32_16x16x32_bf16 v[2:5], v[66:69], v[226:229], v[2:5]
	v_mfma_f32_16x16x32_bf16 v[34:37], v[58:61], v[162:165], v[86:89]
	v_mfma_f32_16x16x32_bf16 v[38:41], v[66:69], v[162:165], v[82:85]
	v_mfma_f32_16x16x32_bf16 v[42:45], v[58:61], v[190:193], v[54:57]
	v_mfma_f32_16x16x32_bf16 v[46:49], v[66:69], v[190:193], v[50:53]
	v_mfma_f32_16x16x32_bf16 v[22:25], v[62:65], v[222:225], v[22:25]
	v_mfma_f32_16x16x32_bf16 v[18:21], v[70:73], v[222:225], v[18:21]
	v_mfma_f32_16x16x32_bf16 v[6:9], v[62:65], v[230:233], v[6:9]
	v_mfma_f32_16x16x32_bf16 v[2:5], v[70:73], v[230:233], v[2:5]
	v_mfma_f32_16x16x32_bf16 v[34:37], v[62:65], v[166:169], v[34:37]
	v_mfma_f32_16x16x32_bf16 v[38:41], v[70:73], v[166:169], v[38:41]
	v_mfma_f32_16x16x32_bf16 v[42:45], v[62:65], v[194:197], v[42:45]
	v_mfma_f32_16x16x32_bf16 v[46:49], v[70:73], v[194:197], v[46:49]
	s_setprio 0
	s_barrier
	s_add_i32 s56, 0, 0x18000
	s_add_i32 s57, 0, 0x1c000
	v_add_u32_e32 v62, s56, v212
	v_add_u32_e32 v82, s57, v212
	ds_read_b128 v[50:53], v62
	ds_read_b128 v[54:57], v62 offset:1024
	ds_read_b128 v[58:61], v62 offset:2048
	ds_read_b128 v[62:65], v62 offset:3072
	ds_read_b128 v[66:69], v82
	ds_read_b128 v[70:73], v82 offset:1024
	ds_read_b128 v[162:165], v82 offset:2048
	ds_read_b128 v[166:169], v82 offset:3072
	s_add_u32 s42, s42, 0x80000
	s_addc_u32 s43, s43, 0
	s_mov_b32 m0, s46
	v_lshl_add_u64 v[234:235], s[42:43], 0, v[178:179]
	ds_read_b128 v[82:85], v220 offset:32768
	global_load_lds_dwordx4 v[234:235], off
	ds_read_b128 v[86:89], v220 offset:33792
	ds_read_b128 v[190:193], v220 offset:34816
	v_lshl_add_u64 v[234:235], s[42:43], 0, v[180:181]
	s_mov_b32 m0, s47
	s_nop 0
	global_load_lds_dwordx4 v[234:235], off
	ds_read_b128 v[194:197], v220 offset:35840
	ds_read_b128 v[198:201], v220 offset:36864
	ds_read_b128 v[222:225], v220 offset:37888
	ds_read_b128 v[226:229], v220 offset:38912
	ds_read_b128 v[230:233], v220 offset:39936
	s_waitcnt vmcnt(8)
	s_waitcnt lgkmcnt(0)
	s_barrier
	s_setprio 1
	v_mfma_f32_16x16x32_bf16 v[158:161], v[50:53], v[82:85], v[158:161]
	v_mfma_f32_16x16x32_bf16 v[154:157], v[58:61], v[82:85], v[154:157]
	v_mfma_f32_16x16x32_bf16 v[142:145], v[50:53], v[190:193], v[142:145]
	v_mfma_f32_16x16x32_bf16 v[138:141], v[58:61], v[190:193], v[138:141]
	v_mfma_f32_16x16x32_bf16 v[126:129], v[50:53], v[198:201], v[126:129]
	v_mfma_f32_16x16x32_bf16 v[122:125], v[58:61], v[198:201], v[122:125]
	v_mfma_f32_16x16x32_bf16 v[110:113], v[50:53], v[226:229], v[110:113]
	v_mfma_f32_16x16x32_bf16 v[106:109], v[58:61], v[226:229], v[106:109]
	v_mfma_f32_16x16x32_bf16 v[158:161], v[54:57], v[86:89], v[158:161]
	v_mfma_f32_16x16x32_bf16 v[154:157], v[62:65], v[86:89], v[154:157]
	v_mfma_f32_16x16x32_bf16 v[142:145], v[54:57], v[194:197], v[142:145]
	v_mfma_f32_16x16x32_bf16 v[138:141], v[62:65], v[194:197], v[138:141]
	v_mfma_f32_16x16x32_bf16 v[126:129], v[54:57], v[222:225], v[126:129]
	v_mfma_f32_16x16x32_bf16 v[122:125], v[62:65], v[222:225], v[122:125]
	v_mfma_f32_16x16x32_bf16 v[110:113], v[54:57], v[230:233], v[110:113]
	v_mfma_f32_16x16x32_bf16 v[106:109], v[62:65], v[230:233], v[106:109]
	v_mfma_f32_16x16x32_bf16 v[150:153], v[66:69], v[82:85], v[150:153]
	v_mfma_f32_16x16x32_bf16 v[82:85], v[162:165], v[82:85], v[146:149]
	v_mfma_f32_16x16x32_bf16 v[146:149], v[166:169], v[86:89], v[82:85]
	v_mfma_f32_16x16x32_bf16 v[82:85], v[66:69], v[190:193], v[134:137]
	v_mfma_f32_16x16x32_bf16 v[134:137], v[70:73], v[194:197], v[82:85]
	v_mfma_f32_16x16x32_bf16 v[82:85], v[162:165], v[190:193], v[130:133]
	v_mfma_f32_16x16x32_bf16 v[130:133], v[166:169], v[194:197], v[82:85]
	v_mfma_f32_16x16x32_bf16 v[82:85], v[66:69], v[198:201], v[118:121]
	v_mfma_f32_16x16x32_bf16 v[118:121], v[70:73], v[222:225], v[82:85]
	v_mfma_f32_16x16x32_bf16 v[82:85], v[162:165], v[198:201], v[114:117]
	v_mfma_f32_16x16x32_bf16 v[114:117], v[166:169], v[222:225], v[82:85]
	v_mfma_f32_16x16x32_bf16 v[82:85], v[66:69], v[226:229], v[102:105]
	v_mfma_f32_16x16x32_bf16 v[102:105], v[70:73], v[230:233], v[82:85]
	v_mfma_f32_16x16x32_bf16 v[82:85], v[162:165], v[226:229], v[98:101]
	v_mfma_f32_16x16x32_bf16 v[150:153], v[70:73], v[86:89], v[150:153]
	v_mfma_f32_16x16x32_bf16 v[98:101], v[166:169], v[230:233], v[82:85]
	s_setprio 0
	s_barrier
; #define PG8_STAGE(bufoff, gbase, voff) do { _Pragma("unroll") for (int _i = 0; _i < 2; ++_i) \
;         __builtin_amdgcn_global_load_lds((const unsigned*)((const char*)(gbase) + (voff)[_i]), (LAS unsigned*)(lds + (bufoff) + ldsw + _i * 8192), 16, 0, 0); } while (0)
; #define PG8_LDA(dst, b, h) do { _Pragma("unroll") for (int m = 0; m < 4; ++m) _Pragma("unroll") for (int k = 0; k < 2; ++k) dst[m][k] = *(const LAS bf16x8*)(lds + PG8_SA(b, h) + aoff + m * 2048 + k * 1024); } while (0)
; #define PG8_MMA(ai, bj, At, Bt) do { __builtin_amdgcn_s_setprio(1); _Pragma("unroll") for (int m = 0; m < 4; ++m) _Pragma("unroll") for (int n = 0; n < 2; ++n) _Pragma("unroll") for (int k = 0; k < 2; ++k) \
;         acc[ai][bj][m][n] = __builtin_amdgcn_mfma_f32_16x16x32_bf16(Bt[n][k], At[m][k], acc[ai][bj][m][n], 0, 0, 0); __builtin_amdgcn_s_setprio(0); } while (0)
; #define PG8_WAIT_V(n) asm volatile("s_waitcnt vmcnt(" #n ")" ::: "memory")
; #define PG8_WAIT_L(n) asm volatile("s_waitcnt lgkmcnt(" #n ")" ::: "memory")
; #define PG8_BAR __builtin_amdgcn_s_barrier()
; #define PG8_SCHED __builtin_amdgcn_sched_barrier(0)
; template <class Epi>
; __device__ __forceinline__ void gemm_phase(LAS unsigned char* lds, const Gemm g, const StaticOrder& S, const Epi& E, const int tid) {
;     ...
;             PG8_LDA(At, 1, 1); PG8_STAGE(PG8_SB(1, 0), b3, voffB); PG8_STAGE(PG8_SB(1, 1), b3 + bhs, voffB); PG8_STAGE(PG8_SA(1, 0), a3, voffA);
;             PG8_WAIT_V(8); PG8_WAIT_L(0); PG8_BAR; PG8_MMA(1, 0, At, B0); PG8_MMA(1, 1, At, B1); PG8_BAR; PG8_SCHED;
	s_add_i32 s42, s56, s33
	v_lshl_add_u64 v[86:87], v[172:173], 0, s[70:71]
	s_mov_b32 m0, s42
	s_nop 0
	ds_read_b128 v[82:85], v220 offset:49152
	global_load_lds_dwordx4 v[86:87], off
	ds_read_b128 v[190:193], v220 offset:50176
	ds_read_b128 v[194:197], v220 offset:51200
	s_add_i32 m0, s42, 0x2000
	s_add_u32 s40, s40, 0x8080
	v_lshl_add_u64 v[86:87], v[174:175], 0, s[70:71]
	s_addc_u32 s41, s41, 0
	s_add_i32 s42, s57, s33
	global_load_lds_dwordx4 v[86:87], off
	ds_read_b128 v[198:201], v220 offset:52224
	ds_read_b128 v[222:225], v220 offset:53248
	v_lshl_add_u64 v[86:87], s[40:41], 0, v[0:1]
	s_mov_b32 m0, s42
	s_nop 0
	global_load_lds_dwordx4 v[86:87], off
	ds_read_b128 v[226:229], v220 offset:54272
	ds_read_b128 v[230:233], v220 offset:55296
	v_lshl_add_u64 v[86:87], s[40:41], 0, v[182:183]
	s_add_i32 m0, s42, 0x2000
	s_nop 0
	global_load_lds_dwordx4 v[86:87], off
	ds_read_b128 v[234:237], v220 offset:56320
	v_lshl_add_u64 v[86:87], v[176:177], 0, s[70:71]
	s_mov_b32 m0, s48
	s_nop 0
	global_load_lds_dwordx4 v[86:87], off
	v_lshl_add_u64 v[86:87], v[238:239], 0, s[70:71]
	s_mov_b32 m0, s49
	s_nop 0
	global_load_lds_dwordx4 v[86:87], off
	s_waitcnt vmcnt(8)
	s_waitcnt lgkmcnt(0)
	s_barrier
	s_setprio 1
	v_mfma_f32_16x16x32_bf16 v[86:89], v[50:53], v[82:85], v[94:97]
	v_mfma_f32_16x16x32_bf16 v[94:97], v[54:57], v[190:193], v[86:89]
	v_mfma_f32_16x16x32_bf16 v[86:89], v[58:61], v[82:85], v[90:93]
	v_mfma_f32_16x16x32_bf16 v[78:81], v[50:53], v[194:197], v[78:81]
	v_mfma_f32_16x16x32_bf16 v[74:77], v[58:61], v[194:197], v[74:77]
	v_mfma_f32_16x16x32_bf16 v[30:33], v[50:53], v[222:225], v[30:33]
	v_mfma_f32_16x16x32_bf16 v[26:29], v[58:61], v[222:225], v[26:29]
	v_mfma_f32_16x16x32_bf16 v[14:17], v[50:53], v[230:233], v[14:17]
	v_mfma_f32_16x16x32_bf16 v[10:13], v[58:61], v[230:233], v[10:13]
	v_mfma_f32_16x16x32_bf16 v[90:93], v[62:65], v[190:193], v[86:89]
	v_mfma_f32_16x16x32_bf16 v[78:81], v[54:57], v[198:201], v[78:81]
	v_mfma_f32_16x16x32_bf16 v[74:77], v[62:65], v[198:201], v[74:77]
	v_mfma_f32_16x16x32_bf16 v[30:33], v[54:57], v[226:229], v[30:33]
	v_mfma_f32_16x16x32_bf16 v[26:29], v[62:65], v[226:229], v[26:29]
	v_mfma_f32_16x16x32_bf16 v[14:17], v[54:57], v[234:237], v[14:17]
	v_mfma_f32_16x16x32_bf16 v[10:13], v[62:65], v[234:237], v[10:13]
	v_mfma_f32_16x16x32_bf16 v[34:37], v[66:69], v[82:85], v[34:37]
	v_mfma_f32_16x16x32_bf16 v[86:89], v[70:73], v[190:193], v[34:37]
	v_mfma_f32_16x16x32_bf16 v[34:37], v[162:165], v[82:85], v[38:41]
	v_mfma_f32_16x16x32_bf16 v[82:85], v[166:169], v[190:193], v[34:37]
	v_mfma_f32_16x16x32_bf16 v[34:37], v[66:69], v[194:197], v[42:45]
	v_mfma_f32_16x16x32_bf16 v[54:57], v[70:73], v[198:201], v[34:37]
	v_mfma_f32_16x16x32_bf16 v[34:37], v[162:165], v[194:197], v[46:49]
	v_mfma_f32_16x16x32_bf16 v[22:25], v[66:69], v[222:225], v[22:25]
	v_mfma_f32_16x16x32_bf16 v[18:21], v[162:165], v[222:225], v[18:21]
	v_mfma_f32_16x16x32_bf16 v[6:9], v[66:69], v[230:233], v[6:9]
	v_mfma_f32_16x16x32_bf16 v[2:5], v[162:165], v[230:233], v[2:5]
	v_mfma_f32_16x16x32_bf16 v[50:53], v[166:169], v[198:201], v[34:37]
	v_mfma_f32_16x16x32_bf16 v[22:25], v[70:73], v[226:229], v[22:25]
	v_mfma_f32_16x16x32_bf16 v[18:21], v[166:169], v[226:229], v[18:21]
	v_mfma_f32_16x16x32_bf16 v[6:9], v[70:73], v[234:237], v[6:9]
	v_mfma_f32_16x16x32_bf16 v[2:5], v[166:169], v[234:237], v[2:5]
	s_setprio 0
	s_barrier
	s_add_i32 s55, s55, 2
	s_add_u32 s53, s53, 0x100
	s_addc_u32 s54, s54, 0
	s_add_u32 s6, s6, 0x100
	s_addc_u32 s7, s7, 0
	s_cmp_gt_u32 s55, 29
	s_cbranch_scc0 .LBB0_314
	s_and_b64 vcc, exec, s[22:23]
	s_cbranch_vccz .LBB0_317
	s_barrier

; #define PG8_STAGE(bufoff, gbase, voff) do { _Pragma("unroll") for (int _i = 0; _i < 2; ++_i) \
;         __builtin_amdgcn_global_load_lds((const unsigned*)((const char*)(gbase) + (voff)[_i]), (LAS unsigned*)(lds + (bufoff) + ldsw + _i * 8192), 16, 0, 0); } while (0)
; #define PG8_LDA(dst, b, h) do { _Pragma("unroll") for (int m = 0; m < 4; ++m) _Pragma("unroll") for (int k = 0; k < 2; ++k) dst[m][k] = *(const LAS bf16x8*)(lds + PG8_SA(b, h) + aoff + m * 2048 + k * 1024); } while (0)
; #define PG8_LDB(dst, b, h) do { _Pragma("unroll") for (int n = 0; n < 2; ++n) _Pragma("unroll") for (int k = 0; k < 2; ++k) dst[n][k] = *(const LAS bf16x8*)(lds + PG8_SB(b, h) + boff + n * 2048 + k * 1024); } while (0)
; #define PG8_MMA(ai, bj, At, Bt) do { __builtin_amdgcn_s_setprio(1); _Pragma("unroll") for (int m = 0; m < 4; ++m) _Pragma("unroll") for (int n = 0; n < 2; ++n) _Pragma("unroll") for (int k = 0; k < 2; ++k) \
;         acc[ai][bj][m][n] = __builtin_amdgcn_mfma_f32_16x16x32_bf16(Bt[n][k], At[m][k], acc[ai][bj][m][n], 0, 0, 0); __builtin_amdgcn_s_setprio(0); } while (0)
; #define PG8_WAIT_V(n) asm volatile("s_waitcnt vmcnt(" #n ")" ::: "memory")
; template <class Epi>
; __device__ __forceinline__ void gemm_phase(LAS unsigned char* lds, const Gemm g, const StaticOrder& S, const Epi& E, const int tid) {
;     ...
;             const char* a1 = (s1 ? cA2 + (size_t)(t - nt + 1) * kstep : cA + (size_t)(t + 1) * kstep);
;             const char* a2 = last ? nA : (s2 ? cA2 + (size_t)(t + 2 - nt) * kstep : cA + (size_t)(t + 2) * kstep);
;             const char* b2 = last ? nB : (s2 ? cB2 + (size_t)(t + 2 - nt) * kstep : cB + (size_t)(t + 2) * kstep);
;             const char* a3 = a2 + kstep; const char* b3 = b2 + kstep;
;             if constexpr (Epi::TWO) { if (t == nt) E.mid(acc, cur, wr, wc, fr, fq); }
;             if constexpr (SP2) {
;             PG8_LDB(B0, 0, 0); PG8_LDB(B1, 0, 1); PG8_SCHED; PG8_LDA(At, 0, 0); PG8_STAGE(PG8_SA(1, 1), a1 + hstep, voffA);
;             PG8_WAIT_V(8); PG8_WAIT_L(0); PG8_BAR; PG8_MMA(0, 0, At, B0); PG8_MMA(0, 1, At, B1); PG8_BAR; PG8_SCHED;
;             PG8_LDA(At, 0, 1); PG8_STAGE(PG8_SB(0, 0), b2, voffB); PG8_STAGE(PG8_SB(0, 1), b2 + bhs, voffB); PG8_STAGE(PG8_SA(0, 0), a2, voffA);
;             PG8_WAIT_V(8); PG8_WAIT_L(0); PG8_BAR; PG8_MMA(1, 0, At, B0); PG8_MMA(1, 1, At, B1); PG8_BAR; PG8_SCHED;
.LBB0_454:
	s_add_i32 s13, 0, 0x10000
	v_add_u32_e32 v0, s13, v153
	s_add_i32 s36, 0, 0x14000
	ds_read_b128 v[132:135], v0
	ds_read_b128 v[136:139], v0 offset:1024
	ds_read_b128 v[156:159], v0 offset:2048
	ds_read_b128 v[160:163], v0 offset:3072
	v_add_u32_e32 v0, s36, v153
	ds_read_b128 v[164:167], v0
	ds_read_b128 v[178:181], v0 offset:1024
	ds_read_b128 v[182:185], v0 offset:2048
	ds_read_b128 v[186:189], v0 offset:3072
	s_add_u32 s34, s34, 0x40000
	s_addc_u32 s35, s35, 0
	v_lshl_add_u64 v[2:3], s[34:35], 0, v[140:141]
	s_add_i32 m0, s43, 0xc000
	ds_read_b128 v[190:193], v155
	global_load_lds_dwordx4 v[2:3], off
	ds_read_b128 v[194:197], v155 offset:1024
	ds_read_b128 v[198:201], v155 offset:2048
	v_lshl_add_u64 v[2:3], s[34:35], 0, v[144:145]
	s_add_i32 m0, s43, 0xe000
	s_nop 0
	global_load_lds_dwordx4 v[2:3], off
	ds_read_b128 v[212:215], v155 offset:3072
	ds_read_b128 v[216:219], v155 offset:4096
	ds_read_b128 v[220:223], v155 offset:5120
	ds_read_b128 v[224:227], v155 offset:6144
	ds_read_b128 v[228:231], v155 offset:7168
	s_waitcnt vmcnt(8)
	s_waitcnt lgkmcnt(0)
	s_barrier
	s_setprio 1
	v_mfma_f32_16x16x32_bf16 v[128:131], v[132:135], v[190:193], v[128:131]
	v_mfma_f32_16x16x32_bf16 v[124:127], v[156:159], v[190:193], v[124:127]
	v_mfma_f32_16x16x32_bf16 v[112:115], v[132:135], v[198:201], v[112:115]
	v_mfma_f32_16x16x32_bf16 v[108:111], v[156:159], v[198:201], v[108:111]
	v_mfma_f32_16x16x32_bf16 v[96:99], v[132:135], v[216:219], v[96:99]
	v_mfma_f32_16x16x32_bf16 v[92:95], v[156:159], v[216:219], v[92:95]
	v_mfma_f32_16x16x32_bf16 v[80:83], v[132:135], v[224:227], v[80:83]
	v_mfma_f32_16x16x32_bf16 v[76:79], v[156:159], v[224:227], v[76:79]
	v_mfma_f32_16x16x32_bf16 v[128:131], v[136:139], v[194:197], v[128:131]
	v_mfma_f32_16x16x32_bf16 v[124:127], v[160:163], v[194:197], v[124:127]
	v_mfma_f32_16x16x32_bf16 v[112:115], v[136:139], v[212:215], v[112:115]
	v_mfma_f32_16x16x32_bf16 v[108:111], v[160:163], v[212:215], v[108:111]
	v_mfma_f32_16x16x32_bf16 v[96:99], v[136:139], v[220:223], v[96:99]
	v_mfma_f32_16x16x32_bf16 v[92:95], v[160:163], v[220:223], v[92:95]
	v_mfma_f32_16x16x32_bf16 v[80:83], v[136:139], v[228:231], v[80:83]
	v_mfma_f32_16x16x32_bf16 v[76:79], v[160:163], v[228:231], v[76:79]
	v_mfma_f32_16x16x32_bf16 v[120:123], v[164:167], v[190:193], v[120:123]
	v_mfma_f32_16x16x32_bf16 v[116:119], v[182:185], v[190:193], v[116:119]
	v_mfma_f32_16x16x32_bf16 v[104:107], v[164:167], v[198:201], v[104:107]
	v_mfma_f32_16x16x32_bf16 v[100:103], v[182:185], v[198:201], v[100:103]
	v_mfma_f32_16x16x32_bf16 v[88:91], v[164:167], v[216:219], v[88:91]
	v_mfma_f32_16x16x32_bf16 v[84:87], v[182:185], v[216:219], v[84:87]
	v_mfma_f32_16x16x32_bf16 v[72:75], v[164:167], v[224:227], v[72:75]
	v_mfma_f32_16x16x32_bf16 v[68:71], v[182:185], v[224:227], v[68:71]
	v_mfma_f32_16x16x32_bf16 v[120:123], v[178:181], v[194:197], v[120:123]
	v_mfma_f32_16x16x32_bf16 v[116:119], v[186:189], v[194:197], v[116:119]
	v_mfma_f32_16x16x32_bf16 v[104:107], v[178:181], v[212:215], v[104:107]
	v_mfma_f32_16x16x32_bf16 v[100:103], v[186:189], v[212:215], v[100:103]
	v_mfma_f32_16x16x32_bf16 v[88:91], v[178:181], v[220:223], v[88:91]
	v_mfma_f32_16x16x32_bf16 v[84:87], v[186:189], v[220:223], v[84:87]
	v_mfma_f32_16x16x32_bf16 v[72:75], v[178:181], v[228:231], v[72:75]
	v_mfma_f32_16x16x32_bf16 v[68:71], v[186:189], v[228:231], v[68:71]
	s_setprio 0
	s_barrier
	s_add_i32 s13, s13, s42
	v_lshl_add_u64 v[168:169], s[28:29], 0, v[142:143]
	s_mov_b32 m0, s13
	ds_read_b128 v[190:193], v155 offset:16384
	global_load_lds_dwordx4 v[168:169], off
	ds_read_b128 v[194:197], v155 offset:17408
	ds_read_b128 v[198:201], v155 offset:18432
	s_add_i32 m0, s13, 0x2000
	s_add_u32 s34, s28, 0x4000
	v_lshl_add_u64 v[172:173], s[28:29], 0, v[146:147]
	s_addc_u32 s35, s29, 0
	s_add_i32 s13, s36, s42
	global_load_lds_dwordx4 v[172:173], off
	ds_read_b128 v[212:215], v155 offset:19456
	ds_read_b128 v[216:219], v155 offset:20480
	v_lshl_add_u64 v[2:3], s[34:35], 0, v[142:143]
	s_mov_b32 m0, s13
	v_lshl_add_u64 v[174:175], s[30:31], 0, v[140:141]
	global_load_lds_dwordx4 v[2:3], off
	ds_read_b128 v[220:223], v155 offset:21504
	ds_read_b128 v[224:227], v155 offset:22528
	v_lshl_add_u64 v[2:3], s[34:35], 0, v[146:147]
	s_add_i32 m0, s13, 0x2000
	v_lshl_add_u64 v[176:177], s[30:31], 0, v[144:145]
	global_load_lds_dwordx4 v[2:3], off
	ds_read_b128 v[228:231], v155 offset:23552
	s_mov_b32 m0, s43
	s_nop 0
	global_load_lds_dwordx4 v[174:175], off
	s_mov_b32 m0, s44
	s_nop 0
	global_load_lds_dwordx4 v[176:177], off
	s_waitcnt vmcnt(8)
	s_waitcnt lgkmcnt(0)
	s_barrier
; #define PG8_STAGE(bufoff, gbase, voff) do { _Pragma("unroll") for (int _i = 0; _i < 2; ++_i) \
;         __builtin_amdgcn_global_load_lds((const unsigned*)((const char*)(gbase) + (voff)[_i]), (LAS unsigned*)(lds + (bufoff) + ldsw + _i * 8192), 16, 0, 0); } while (0)
; #define PG8_LDA(dst, b, h) do { _Pragma("unroll") for (int m = 0; m < 4; ++m) _Pragma("unroll") for (int k = 0; k < 2; ++k) dst[m][k] = *(const LAS bf16x8*)(lds + PG8_SA(b, h) + aoff + m * 2048 + k * 1024); } while (0)
; #define PG8_LDB(dst, b, h) do { _Pragma("unroll") for (int n = 0; n < 2; ++n) _Pragma("unroll") for (int k = 0; k < 2; ++k) dst[n][k] = *(const LAS bf16x8*)(lds + PG8_SB(b, h) + boff + n * 2048 + k * 1024); } while (0)
; #define PG8_MMA(ai, bj, At, Bt) do { __builtin_amdgcn_s_setprio(1); _Pragma("unroll") for (int m = 0; m < 4; ++m) _Pragma("unroll") for (int n = 0; n < 2; ++n) _Pragma("unroll") for (int k = 0; k < 2; ++k) \
;         acc[ai][bj][m][n] = __builtin_amdgcn_mfma_f32_16x16x32_bf16(Bt[n][k], At[m][k], acc[ai][bj][m][n], 0, 0, 0); __builtin_amdgcn_s_setprio(0); } while (0)
; #define PG8_WAIT_V(n) asm volatile("s_waitcnt vmcnt(" #n ")" ::: "memory")
; #define PG8_WAIT_L(n) asm volatile("s_waitcnt lgkmcnt(" #n ")" ::: "memory")
; #define PG8_BAR __builtin_amdgcn_s_barrier()
; #define PG8_SCHED __builtin_amdgcn_sched_barrier(0)
; template <class Epi>
; __device__ __forceinline__ void gemm_phase(LAS unsigned char* lds, const Gemm g, const StaticOrder& S, const Epi& E, const int tid) {
;     ...
;             PG8_WAIT_V(8); PG8_WAIT_L(0); PG8_BAR; PG8_MMA(1, 0, At, B0); PG8_MMA(1, 1, At, B1); PG8_BAR; PG8_SCHED;
;             PG8_LDB(B0, 1, 0); PG8_LDB(B1, 1, 1); PG8_SCHED; PG8_LDA(At, 1, 0); PG8_STAGE(PG8_SA(0, 1), a2 + hstep, voffA);
;             PG8_WAIT_V(8); PG8_WAIT_L(0); PG8_BAR; PG8_MMA(0, 0, At, B0); PG8_MMA(0, 1, At, B1); PG8_BAR; PG8_SCHED;
	s_setprio 1
	v_mfma_f32_16x16x32_bf16 v[64:67], v[132:135], v[190:193], v[64:67]
	v_mfma_f32_16x16x32_bf16 v[60:63], v[156:159], v[190:193], v[60:63]
	v_mfma_f32_16x16x32_bf16 v[48:51], v[132:135], v[198:201], v[48:51]
	v_mfma_f32_16x16x32_bf16 v[44:47], v[156:159], v[198:201], v[44:47]
	v_mfma_f32_16x16x32_bf16 v[32:35], v[132:135], v[216:219], v[32:35]
	v_mfma_f32_16x16x32_bf16 v[28:31], v[156:159], v[216:219], v[28:31]
	v_mfma_f32_16x16x32_bf16 v[16:19], v[132:135], v[224:227], v[16:19]
	v_mfma_f32_16x16x32_bf16 v[12:15], v[156:159], v[224:227], v[12:15]
	v_mfma_f32_16x16x32_bf16 v[64:67], v[136:139], v[194:197], v[64:67]
	v_mfma_f32_16x16x32_bf16 v[60:63], v[160:163], v[194:197], v[60:63]
	v_mfma_f32_16x16x32_bf16 v[48:51], v[136:139], v[212:215], v[48:51]
	v_mfma_f32_16x16x32_bf16 v[44:47], v[160:163], v[212:215], v[44:47]
	v_mfma_f32_16x16x32_bf16 v[32:35], v[136:139], v[220:223], v[32:35]
	v_mfma_f32_16x16x32_bf16 v[28:31], v[160:163], v[220:223], v[28:31]
	v_mfma_f32_16x16x32_bf16 v[16:19], v[136:139], v[228:231], v[16:19]
	v_mfma_f32_16x16x32_bf16 v[12:15], v[160:163], v[228:231], v[12:15]
	v_mfma_f32_16x16x32_bf16 v[56:59], v[164:167], v[190:193], v[56:59]
	v_mfma_f32_16x16x32_bf16 v[52:55], v[182:185], v[190:193], v[52:55]
	v_mfma_f32_16x16x32_bf16 v[40:43], v[164:167], v[198:201], v[40:43]
	v_mfma_f32_16x16x32_bf16 v[36:39], v[182:185], v[198:201], v[36:39]
	v_mfma_f32_16x16x32_bf16 v[24:27], v[164:167], v[216:219], v[24:27]
	v_mfma_f32_16x16x32_bf16 v[20:23], v[182:185], v[216:219], v[20:23]
	v_mfma_f32_16x16x32_bf16 v[8:11], v[164:167], v[224:227], v[8:11]
	v_mfma_f32_16x16x32_bf16 v[2:5], v[182:185], v[224:227], v[4:7]
	v_mfma_f32_16x16x32_bf16 v[56:59], v[178:181], v[194:197], v[56:59]
	v_mfma_f32_16x16x32_bf16 v[52:55], v[186:189], v[194:197], v[52:55]
	v_mfma_f32_16x16x32_bf16 v[40:43], v[178:181], v[212:215], v[40:43]
	v_mfma_f32_16x16x32_bf16 v[36:39], v[186:189], v[212:215], v[36:39]
	v_mfma_f32_16x16x32_bf16 v[24:27], v[178:181], v[220:223], v[24:27]
	v_mfma_f32_16x16x32_bf16 v[20:23], v[186:189], v[220:223], v[20:23]
	v_mfma_f32_16x16x32_bf16 v[8:11], v[178:181], v[228:231], v[8:11]
	v_mfma_f32_16x16x32_bf16 v[2:5], v[186:189], v[228:231], v[2:5]
	s_setprio 0
	s_barrier
	s_add_i32 s13, 0, 0x18000
	v_add_u32_e32 v0, s13, v153
	s_add_i32 s34, 0, 0x1c000
	ds_read_b128 v[132:135], v0
	ds_read_b128 v[136:139], v0 offset:1024
	ds_read_b128 v[156:159], v0 offset:2048
	ds_read_b128 v[160:163], v0 offset:3072
	v_add_u32_e32 v0, s34, v153
	ds_read_b128 v[164:167], v0
	ds_read_b128 v[178:181], v0 offset:1024
	ds_read_b128 v[182:185], v0 offset:2048
	ds_read_b128 v[186:189], v0 offset:3072
	s_add_u32 s30, s30, 0x40000
	s_addc_u32 s31, s31, 0
	s_mov_b32 m0, s45
	v_lshl_add_u64 v[6:7], s[30:31], 0, v[140:141]
	ds_read_b128 v[190:193], v155 offset:32768
	global_load_lds_dwordx4 v[6:7], off
	ds_read_b128 v[194:197], v155 offset:33792
	ds_read_b128 v[198:201], v155 offset:34816
	v_lshl_add_u64 v[6:7], s[30:31], 0, v[144:145]
	s_mov_b32 m0, s46
	s_nop 0
	global_load_lds_dwordx4 v[6:7], off
	ds_read_b128 v[212:215], v155 offset:35840
	ds_read_b128 v[216:219], v155 offset:36864
	ds_read_b128 v[220:223], v155 offset:37888
	ds_read_b128 v[224:227], v155 offset:38912
	ds_read_b128 v[228:231], v155 offset:39936
	s_waitcnt vmcnt(8)
	s_waitcnt lgkmcnt(0)
	s_barrier
	s_setprio 1
	v_mfma_f32_16x16x32_bf16 v[128:131], v[132:135], v[190:193], v[128:131]
	v_mfma_f32_16x16x32_bf16 v[124:127], v[156:159], v[190:193], v[124:127]
	v_mfma_f32_16x16x32_bf16 v[112:115], v[132:135], v[198:201], v[112:115]
	v_mfma_f32_16x16x32_bf16 v[108:111], v[156:159], v[198:201], v[108:111]
	v_mfma_f32_16x16x32_bf16 v[96:99], v[132:135], v[216:219], v[96:99]
	v_mfma_f32_16x16x32_bf16 v[92:95], v[156:159], v[216:219], v[92:95]
	v_mfma_f32_16x16x32_bf16 v[80:83], v[132:135], v[224:227], v[80:83]
	v_mfma_f32_16x16x32_bf16 v[76:79], v[156:159], v[224:227], v[76:79]
	v_mfma_f32_16x16x32_bf16 v[128:131], v[136:139], v[194:197], v[128:131]
	v_mfma_f32_16x16x32_bf16 v[124:127], v[160:163], v[194:197], v[124:127]
	v_mfma_f32_16x16x32_bf16 v[112:115], v[136:139], v[212:215], v[112:115]
	v_mfma_f32_16x16x32_bf16 v[108:111], v[160:163], v[212:215], v[108:111]
	v_mfma_f32_16x16x32_bf16 v[96:99], v[136:139], v[220:223], v[96:99]
	v_mfma_f32_16x16x32_bf16 v[92:95], v[160:163], v[220:223], v[92:95]
	v_mfma_f32_16x16x32_bf16 v[80:83], v[136:139], v[228:231], v[80:83]
	v_mfma_f32_16x16x32_bf16 v[76:79], v[160:163], v[228:231], v[76:79]
	v_mfma_f32_16x16x32_bf16 v[120:123], v[164:167], v[190:193], v[120:123]
	v_mfma_f32_16x16x32_bf16 v[116:119], v[182:185], v[190:193], v[116:119]
	v_mfma_f32_16x16x32_bf16 v[104:107], v[164:167], v[198:201], v[104:107]
	v_mfma_f32_16x16x32_bf16 v[100:103], v[182:185], v[198:201], v[100:103]
	v_mfma_f32_16x16x32_bf16 v[88:91], v[164:167], v[216:219], v[88:91]
	v_mfma_f32_16x16x32_bf16 v[84:87], v[182:185], v[216:219], v[84:87]
	v_mfma_f32_16x16x32_bf16 v[72:75], v[164:167], v[224:227], v[72:75]
	v_mfma_f32_16x16x32_bf16 v[68:71], v[182:185], v[224:227], v[68:71]
	v_mfma_f32_16x16x32_bf16 v[120:123], v[178:181], v[194:197], v[120:123]
	v_mfma_f32_16x16x32_bf16 v[116:119], v[186:189], v[194:197], v[116:119]
	v_mfma_f32_16x16x32_bf16 v[104:107], v[178:181], v[212:215], v[104:107]
	v_mfma_f32_16x16x32_bf16 v[100:103], v[186:189], v[212:215], v[100:103]
	v_mfma_f32_16x16x32_bf16 v[88:91], v[178:181], v[220:223], v[88:91]
	v_mfma_f32_16x16x32_bf16 v[84:87], v[186:189], v[220:223], v[84:87]
	v_mfma_f32_16x16x32_bf16 v[72:75], v[178:181], v[228:231], v[72:75]
	v_mfma_f32_16x16x32_bf16 v[68:71], v[186:189], v[228:231], v[68:71]
	s_setprio 0
	s_barrier
; #define PG8_STAGE(bufoff, gbase, voff) do { _Pragma("unroll") for (int _i = 0; _i < 2; ++_i) \
;         __builtin_amdgcn_global_load_lds((const unsigned*)((const char*)(gbase) + (voff)[_i]), (LAS unsigned*)(lds + (bufoff) + ldsw + _i * 8192), 16, 0, 0); } while (0)
; #define PG8_LDA(dst, b, h) do { _Pragma("unroll") for (int m = 0; m < 4; ++m) _Pragma("unroll") for (int k = 0; k < 2; ++k) dst[m][k] = *(const LAS bf16x8*)(lds + PG8_SA(b, h) + aoff + m * 2048 + k * 1024); } while (0)
; #define PG8_MMA(ai, bj, At, Bt) do { __builtin_amdgcn_s_setprio(1); _Pragma("unroll") for (int m = 0; m < 4; ++m) _Pragma("unroll") for (int n = 0; n < 2; ++n) _Pragma("unroll") for (int k = 0; k < 2; ++k) \
;         acc[ai][bj][m][n] = __builtin_amdgcn_mfma_f32_16x16x32_bf16(Bt[n][k], At[m][k], acc[ai][bj][m][n], 0, 0, 0); __builtin_amdgcn_s_setprio(0); } while (0)
; #define PG8_WAIT_V(n) asm volatile("s_waitcnt vmcnt(" #n ")" ::: "memory")
; #define PG8_WAIT_L(n) asm volatile("s_waitcnt lgkmcnt(" #n ")" ::: "memory")
; #define PG8_BAR __builtin_amdgcn_s_barrier()
; #define PG8_SCHED __builtin_amdgcn_sched_barrier(0)
; template <class Epi>
; __device__ __forceinline__ void gemm_phase(LAS unsigned char* lds, const Gemm g, const StaticOrder& S, const Epi& E, const int tid) {
;     ...
;             PG8_LDA(At, 1, 1); PG8_STAGE(PG8_SB(1, 0), b3, voffB); PG8_STAGE(PG8_SB(1, 1), b3 + bhs, voffB); PG8_STAGE(PG8_SA(1, 0), a3, voffA);
;             PG8_WAIT_V(8); PG8_WAIT_L(0); PG8_BAR; PG8_MMA(1, 0, At, B0); PG8_MMA(1, 1, At, B1); PG8_BAR; PG8_SCHED;
	s_add_i32 s13, s13, s42
	v_lshl_add_u64 v[6:7], v[168:169], 0, s[70:71]
	s_mov_b32 m0, s13
	ds_read_b128 v[190:193], v155 offset:49152
	global_load_lds_dwordx4 v[6:7], off
	ds_read_b128 v[194:197], v155 offset:50176
	ds_read_b128 v[198:201], v155 offset:51200
	s_add_i32 m0, s13, 0x2000
	s_add_u32 s28, s28, 0x4080
	v_lshl_add_u64 v[6:7], v[172:173], 0, s[70:71]
	s_addc_u32 s29, s29, 0
	s_add_i32 s13, s34, s42
	global_load_lds_dwordx4 v[6:7], off
	ds_read_b128 v[212:215], v155 offset:52224
	ds_read_b128 v[216:219], v155 offset:53248
	v_lshl_add_u64 v[6:7], s[28:29], 0, v[142:143]
	s_mov_b32 m0, s13
	s_nop 0
	global_load_lds_dwordx4 v[6:7], off
	ds_read_b128 v[220:223], v155 offset:54272
	ds_read_b128 v[224:227], v155 offset:55296
	v_lshl_add_u64 v[6:7], s[28:29], 0, v[146:147]
	s_add_i32 m0, s13, 0x2000
	s_nop 0
	global_load_lds_dwordx4 v[6:7], off
	ds_read_b128 v[228:231], v155 offset:56320
	v_lshl_add_u64 v[6:7], v[174:175], 0, s[70:71]
	s_mov_b32 m0, s47
	s_nop 0
	global_load_lds_dwordx4 v[6:7], off
	v_lshl_add_u64 v[6:7], v[176:177], 0, s[70:71]
	s_mov_b32 m0, s48
	s_nop 0
	global_load_lds_dwordx4 v[6:7], off
	s_waitcnt vmcnt(8)
	s_waitcnt lgkmcnt(0)
	s_barrier
	s_setprio 1
	v_mfma_f32_16x16x32_bf16 v[64:67], v[132:135], v[190:193], v[64:67]
	v_mfma_f32_16x16x32_bf16 v[60:63], v[156:159], v[190:193], v[60:63]
	v_mfma_f32_16x16x32_bf16 v[48:51], v[132:135], v[198:201], v[48:51]
	v_mfma_f32_16x16x32_bf16 v[44:47], v[156:159], v[198:201], v[44:47]
	v_mfma_f32_16x16x32_bf16 v[32:35], v[132:135], v[216:219], v[32:35]
	v_mfma_f32_16x16x32_bf16 v[28:31], v[156:159], v[216:219], v[28:31]
	v_mfma_f32_16x16x32_bf16 v[16:19], v[132:135], v[224:227], v[16:19]
	v_mfma_f32_16x16x32_bf16 v[12:15], v[156:159], v[224:227], v[12:15]
	v_mfma_f32_16x16x32_bf16 v[64:67], v[136:139], v[194:197], v[64:67]
	v_mfma_f32_16x16x32_bf16 v[60:63], v[160:163], v[194:197], v[60:63]
	v_mfma_f32_16x16x32_bf16 v[48:51], v[136:139], v[212:215], v[48:51]
	v_mfma_f32_16x16x32_bf16 v[44:47], v[160:163], v[212:215], v[44:47]
	v_mfma_f32_16x16x32_bf16 v[32:35], v[136:139], v[220:223], v[32:35]
	v_mfma_f32_16x16x32_bf16 v[28:31], v[160:163], v[220:223], v[28:31]
	v_mfma_f32_16x16x32_bf16 v[16:19], v[136:139], v[228:231], v[16:19]
	v_mfma_f32_16x16x32_bf16 v[12:15], v[160:163], v[228:231], v[12:15]
	v_mfma_f32_16x16x32_bf16 v[56:59], v[164:167], v[190:193], v[56:59]
	v_mfma_f32_16x16x32_bf16 v[52:55], v[182:185], v[190:193], v[52:55]
	v_mfma_f32_16x16x32_bf16 v[40:43], v[164:167], v[198:201], v[40:43]
	v_mfma_f32_16x16x32_bf16 v[36:39], v[182:185], v[198:201], v[36:39]
	v_mfma_f32_16x16x32_bf16 v[24:27], v[164:167], v[216:219], v[24:27]
	v_mfma_f32_16x16x32_bf16 v[20:23], v[182:185], v[216:219], v[20:23]
	v_mfma_f32_16x16x32_bf16 v[6:9], v[164:167], v[224:227], v[8:11]
	v_mfma_f32_16x16x32_bf16 v[2:5], v[182:185], v[224:227], v[2:5]
	v_mfma_f32_16x16x32_bf16 v[56:59], v[178:181], v[194:197], v[56:59]
	v_mfma_f32_16x16x32_bf16 v[52:55], v[186:189], v[194:197], v[52:55]
	v_mfma_f32_16x16x32_bf16 v[40:43], v[178:181], v[212:215], v[40:43]
	v_mfma_f32_16x16x32_bf16 v[36:39], v[186:189], v[212:215], v[36:39]
	v_mfma_f32_16x16x32_bf16 v[24:27], v[178:181], v[220:223], v[24:27]
	v_mfma_f32_16x16x32_bf16 v[20:23], v[186:189], v[220:223], v[20:23]
	v_mfma_f32_16x16x32_bf16 v[8:11], v[178:181], v[228:231], v[6:9]
	v_mfma_f32_16x16x32_bf16 v[4:7], v[186:189], v[228:231], v[2:5]
	s_setprio 0
	s_barrier
	s_add_i32 s2, s2, 2
	s_add_u32 s24, s24, 0x100
	s_addc_u32 s25, s25, 0
	s_add_u32 s26, s26, 0x100
	s_addc_u32 s27, s27, 0
	s_cmp_gt_u32 s11, 29
	s_cbranch_scc1 .LBB0_467

; #define PG8_STAGE(bufoff, gbase, voff) do { _Pragma("unroll") for (int _i = 0; _i < 2; ++_i) \
;         __builtin_amdgcn_global_load_lds((const unsigned*)((const char*)(gbase) + (voff)[_i]), (LAS unsigned*)(lds + (bufoff) + ldsw + _i * 8192), 16, 0, 0); } while (0)
; #define PG8_LDA(dst, b, h) do { _Pragma("unroll") for (int m = 0; m < 4; ++m) _Pragma("unroll") for (int k = 0; k < 2; ++k) dst[m][k] = *(const LAS bf16x8*)(lds + PG8_SA(b, h) + aoff + m * 2048 + k * 1024); } while (0)
; #define PG8_LDB(dst, b, h) do { _Pragma("unroll") for (int n = 0; n < 2; ++n) _Pragma("unroll") for (int k = 0; k < 2; ++k) dst[n][k] = *(const LAS bf16x8*)(lds + PG8_SB(b, h) + boff + n * 2048 + k * 1024); } while (0)
; #define PG8_WAIT_V(n) asm volatile("s_waitcnt vmcnt(" #n ")" ::: "memory")
; #define PG8_WAIT_L(n) asm volatile("s_waitcnt lgkmcnt(" #n ")" ::: "memory")
; #define PG8_BAR __builtin_amdgcn_s_barrier()
; #define PG8_SCHED __builtin_amdgcn_sched_barrier(0)
; template <class Epi>
; __device__ __forceinline__ void gemm_phase(LAS unsigned char* lds, const Gemm g, const StaticOrder& S, const Epi& E, const int tid) {
;     ...
;             const bool last = (t == ntt - 2);
;             const bool s1 = Epi::TWO && (t >= nt), s2 = Epi::TWO && (t + 2 >= nt);
;             const char* a1 = (s1 ? cA2 + (size_t)(t - nt + 1) * kstep : cA + (size_t)(t + 1) * kstep);
;             const char* a2 = last ? nA : (s2 ? cA2 + (size_t)(t + 2 - nt) * kstep : cA + (size_t)(t + 2) * kstep);
;             const char* b2 = last ? nB : (s2 ? cB2 + (size_t)(t + 2 - nt) * kstep : cB + (size_t)(t + 2) * kstep);
;             const char* a3 = a2 + kstep; const char* b3 = b2 + kstep;
;             if constexpr (Epi::TWO) { if (t == nt) E.mid(acc, cur, wr, wc, fr, fq); }
;             if constexpr (SP2) {
;             PG8_LDB(B0, 0, 0); PG8_LDB(B1, 0, 1); PG8_SCHED; PG8_LDA(At, 0, 0); PG8_STAGE(PG8_SA(1, 1), a1 + hstep, voffA);
;             PG8_WAIT_V(8); PG8_WAIT_L(0); PG8_BAR; PG8_MMA(0, 0, At, B0); PG8_MMA(0, 1, At, B1); PG8_BAR; PG8_SCHED;
;             PG8_LDA(At, 0, 1); PG8_STAGE(PG8_SB(0, 0), b2, voffB); PG8_STAGE(PG8_SB(0, 1), b2 + bhs, voffB); PG8_STAGE(PG8_SA(0, 0), a2, voffA);
;             PG8_WAIT_V(8); PG8_WAIT_L(0); PG8_BAR; PG8_MMA(1, 0, At, B0); PG8_MMA(1, 1, At, B1); PG8_BAR; PG8_SCHED;
.LBB0_546:
	s_add_u32 s28, s26, 0xfff80080
	s_addc_u32 s29, s27, -1
	s_add_i32 s44, 0, 0x10000
	s_cmp_eq_u32 s39, 28
	s_cselect_b32 s35, s19, s29
	s_cselect_b32 s34, s31, s28
	v_add_u32_e32 v0, s44, v149
	s_cselect_b32 s29, s17, s38
	s_cselect_b32 s28, s33, s37
	s_add_i32 s46, 0, 0x14000
	ds_read_b128 v[150:153], v0
	ds_read_b128 v[154:157], v0 offset:1024
	ds_read_b128 v[158:161], v0 offset:2048
	ds_read_b128 v[186:189], v0 offset:3072
	v_add_u32_e32 v0, s46, v149
	ds_read_b128 v[190:193], v0
	ds_read_b128 v[194:197], v0 offset:1024
	ds_read_b128 v[198:201], v0 offset:2048
	ds_read_b128 v[212:215], v0 offset:3072
	v_lshl_add_u64 v[162:163], s[26:27], 0, v[146:147]
	s_add_i32 m0, s57, 0xc000
	ds_read_b128 v[216:219], v184
	global_load_lds_dwordx4 v[162:163], off
	ds_read_b128 v[220:223], v184 offset:1024
	ds_read_b128 v[224:227], v184 offset:2048
	v_lshl_add_u64 v[162:163], s[26:27], 0, v[144:145]
	s_add_i32 m0, s57, 0xe000
	s_nop 0
	global_load_lds_dwordx4 v[162:163], off
	ds_read_b128 v[228:231], v184 offset:3072
	ds_read_b128 v[232:235], v184 offset:4096
	ds_read_b128 v[236:239], v184 offset:5120
	ds_read_b128 v[240:243], v184 offset:6144
	ds_read_b128 v[244:247], v184 offset:7168
	s_waitcnt vmcnt(8)
	s_waitcnt lgkmcnt(0)
	s_barrier
	s_setprio 1
	v_mfma_f32_16x16x32_bf16 v[126:129], v[150:153], v[216:219], v[126:129]
	v_mfma_f32_16x16x32_bf16 v[122:125], v[158:161], v[216:219], v[122:125]
	v_mfma_f32_16x16x32_bf16 v[110:113], v[150:153], v[224:227], v[110:113]
	v_mfma_f32_16x16x32_bf16 v[106:109], v[158:161], v[224:227], v[106:109]
	v_mfma_f32_16x16x32_bf16 v[94:97], v[150:153], v[232:235], v[94:97]
	v_mfma_f32_16x16x32_bf16 v[90:93], v[158:161], v[232:235], v[90:93]
	v_mfma_f32_16x16x32_bf16 v[78:81], v[150:153], v[240:243], v[78:81]
	v_mfma_f32_16x16x32_bf16 v[74:77], v[158:161], v[240:243], v[74:77]
	v_mfma_f32_16x16x32_bf16 v[126:129], v[154:157], v[220:223], v[126:129]
	v_mfma_f32_16x16x32_bf16 v[122:125], v[186:189], v[220:223], v[122:125]
	v_mfma_f32_16x16x32_bf16 v[110:113], v[154:157], v[228:231], v[110:113]
	v_mfma_f32_16x16x32_bf16 v[106:109], v[186:189], v[228:231], v[106:109]
	v_mfma_f32_16x16x32_bf16 v[94:97], v[154:157], v[236:239], v[94:97]
	v_mfma_f32_16x16x32_bf16 v[90:93], v[186:189], v[236:239], v[90:93]
	v_mfma_f32_16x16x32_bf16 v[78:81], v[154:157], v[244:247], v[78:81]
	v_mfma_f32_16x16x32_bf16 v[74:77], v[186:189], v[244:247], v[74:77]
	v_mfma_f32_16x16x32_bf16 v[118:121], v[190:193], v[216:219], v[118:121]
	v_mfma_f32_16x16x32_bf16 v[114:117], v[198:201], v[216:219], v[114:117]
	v_mfma_f32_16x16x32_bf16 v[102:105], v[190:193], v[224:227], v[102:105]
	v_mfma_f32_16x16x32_bf16 v[98:101], v[198:201], v[224:227], v[98:101]
	v_mfma_f32_16x16x32_bf16 v[86:89], v[190:193], v[232:235], v[86:89]
	v_mfma_f32_16x16x32_bf16 v[82:85], v[198:201], v[232:235], v[82:85]
	v_mfma_f32_16x16x32_bf16 v[70:73], v[190:193], v[240:243], v[70:73]
	v_mfma_f32_16x16x32_bf16 v[66:69], v[198:201], v[240:243], v[66:69]
	v_mfma_f32_16x16x32_bf16 v[118:121], v[194:197], v[220:223], v[118:121]
	v_mfma_f32_16x16x32_bf16 v[114:117], v[212:215], v[220:223], v[114:117]
	v_mfma_f32_16x16x32_bf16 v[102:105], v[194:197], v[228:231], v[102:105]
	v_mfma_f32_16x16x32_bf16 v[98:101], v[212:215], v[228:231], v[98:101]
	v_mfma_f32_16x16x32_bf16 v[86:89], v[194:197], v[236:239], v[86:89]
	v_mfma_f32_16x16x32_bf16 v[82:85], v[212:215], v[236:239], v[82:85]
	v_mfma_f32_16x16x32_bf16 v[70:73], v[194:197], v[244:247], v[70:73]
	v_mfma_f32_16x16x32_bf16 v[66:69], v[212:215], v[244:247], v[66:69]
	s_setprio 0
	s_barrier
	s_add_i32 s44, s44, s56
	v_lshl_add_u64 v[162:163], s[28:29], 0, v[132:133]
	s_mov_b32 m0, s44
	ds_read_b128 v[216:219], v184 offset:16384
	global_load_lds_dwordx4 v[162:163], off
	ds_read_b128 v[220:223], v184 offset:17408
	ds_read_b128 v[224:227], v184 offset:18432
	s_add_i32 m0, s44, 0x2000
	s_add_u32 s44, s28, 0x8000
	v_lshl_add_u64 v[248:249], s[28:29], 0, v[136:137]
	s_addc_u32 s45, s29, 0
	s_add_i32 s46, s46, s56
	global_load_lds_dwordx4 v[248:249], off
	ds_read_b128 v[228:231], v184 offset:19456
	ds_read_b128 v[232:235], v184 offset:20480
	v_lshl_add_u64 v[172:173], s[44:45], 0, v[132:133]
	s_mov_b32 m0, s46
	v_lshl_add_u64 v[174:175], s[34:35], 0, v[134:135]
	global_load_lds_dwordx4 v[172:173], off
	ds_read_b128 v[236:239], v184 offset:21504
	ds_read_b128 v[240:243], v184 offset:22528
	v_lshl_add_u64 v[172:173], s[44:45], 0, v[136:137]
	s_add_i32 m0, s46, 0x2000
	s_nop 0
	global_load_lds_dwordx4 v[172:173], off
	ds_read_b128 v[244:247], v184 offset:23552
	v_lshl_add_u64 v[172:173], s[34:35], 0, v[130:131]
	s_mov_b32 m0, s57
	s_nop 0
	global_load_lds_dwordx4 v[172:173], off
	s_mov_b32 m0, s58
	s_nop 0
	global_load_lds_dwordx4 v[174:175], off
	s_waitcnt vmcnt(8)
	s_waitcnt lgkmcnt(0)
	s_barrier
; #define PG8_STAGE(bufoff, gbase, voff) do { _Pragma("unroll") for (int _i = 0; _i < 2; ++_i) \
;         __builtin_amdgcn_global_load_lds((const unsigned*)((const char*)(gbase) + (voff)[_i]), (LAS unsigned*)(lds + (bufoff) + ldsw + _i * 8192), 16, 0, 0); } while (0)
; #define PG8_LDA(dst, b, h) do { _Pragma("unroll") for (int m = 0; m < 4; ++m) _Pragma("unroll") for (int k = 0; k < 2; ++k) dst[m][k] = *(const LAS bf16x8*)(lds + PG8_SA(b, h) + aoff + m * 2048 + k * 1024); } while (0)
; #define PG8_LDB(dst, b, h) do { _Pragma("unroll") for (int n = 0; n < 2; ++n) _Pragma("unroll") for (int k = 0; k < 2; ++k) dst[n][k] = *(const LAS bf16x8*)(lds + PG8_SB(b, h) + boff + n * 2048 + k * 1024); } while (0)
; #define PG8_MMA(ai, bj, At, Bt) do { __builtin_amdgcn_s_setprio(1); _Pragma("unroll") for (int m = 0; m < 4; ++m) _Pragma("unroll") for (int n = 0; n < 2; ++n) _Pragma("unroll") for (int k = 0; k < 2; ++k) \
;         acc[ai][bj][m][n] = __builtin_amdgcn_mfma_f32_16x16x32_bf16(Bt[n][k], At[m][k], acc[ai][bj][m][n], 0, 0, 0); __builtin_amdgcn_s_setprio(0); } while (0)
; #define PG8_WAIT_V(n) asm volatile("s_waitcnt vmcnt(" #n ")" ::: "memory")
; #define PG8_WAIT_L(n) asm volatile("s_waitcnt lgkmcnt(" #n ")" ::: "memory")
; #define PG8_BAR __builtin_amdgcn_s_barrier()
; #define PG8_SCHED __builtin_amdgcn_sched_barrier(0)
; template <class Epi>
; __device__ __forceinline__ void gemm_phase(LAS unsigned char* lds, const Gemm g, const StaticOrder& S, const Epi& E, const int tid) {
;     ...
;             PG8_WAIT_V(8); PG8_WAIT_L(0); PG8_BAR; PG8_MMA(1, 0, At, B0); PG8_MMA(1, 1, At, B1); PG8_BAR; PG8_SCHED;
;             PG8_LDB(B0, 1, 0); PG8_LDB(B1, 1, 1); PG8_SCHED; PG8_LDA(At, 1, 0); PG8_STAGE(PG8_SA(0, 1), a2 + hstep, voffA);
;             PG8_WAIT_V(8); PG8_WAIT_L(0); PG8_BAR; PG8_MMA(0, 0, At, B0); PG8_MMA(0, 1, At, B1); PG8_BAR; PG8_SCHED;
	s_setprio 1
	v_mfma_f32_16x16x32_bf16 v[62:65], v[150:153], v[216:219], v[62:65]
	v_mfma_f32_16x16x32_bf16 v[58:61], v[158:161], v[216:219], v[58:61]
	v_mfma_f32_16x16x32_bf16 v[46:49], v[150:153], v[224:227], v[46:49]
	v_mfma_f32_16x16x32_bf16 v[42:45], v[158:161], v[224:227], v[42:45]
	v_mfma_f32_16x16x32_bf16 v[30:33], v[150:153], v[232:235], v[30:33]
	v_mfma_f32_16x16x32_bf16 v[26:29], v[158:161], v[232:235], v[26:29]
	v_mfma_f32_16x16x32_bf16 v[14:17], v[150:153], v[240:243], v[14:17]
	v_mfma_f32_16x16x32_bf16 v[10:13], v[158:161], v[240:243], v[10:13]
	v_mfma_f32_16x16x32_bf16 v[62:65], v[154:157], v[220:223], v[62:65]
	v_mfma_f32_16x16x32_bf16 v[58:61], v[186:189], v[220:223], v[58:61]
	v_mfma_f32_16x16x32_bf16 v[46:49], v[154:157], v[228:231], v[46:49]
	v_mfma_f32_16x16x32_bf16 v[42:45], v[186:189], v[228:231], v[42:45]
	v_mfma_f32_16x16x32_bf16 v[30:33], v[154:157], v[236:239], v[30:33]
	v_mfma_f32_16x16x32_bf16 v[26:29], v[186:189], v[236:239], v[26:29]
	v_mfma_f32_16x16x32_bf16 v[14:17], v[154:157], v[244:247], v[14:17]
	v_mfma_f32_16x16x32_bf16 v[10:13], v[186:189], v[244:247], v[10:13]
	v_mfma_f32_16x16x32_bf16 v[54:57], v[190:193], v[216:219], v[54:57]
	v_mfma_f32_16x16x32_bf16 v[50:53], v[198:201], v[216:219], v[50:53]
	v_mfma_f32_16x16x32_bf16 v[38:41], v[190:193], v[224:227], v[38:41]
	v_mfma_f32_16x16x32_bf16 v[34:37], v[198:201], v[224:227], v[34:37]
	v_mfma_f32_16x16x32_bf16 v[22:25], v[190:193], v[232:235], v[22:25]
	v_mfma_f32_16x16x32_bf16 v[18:21], v[198:201], v[232:235], v[18:21]
	v_mfma_f32_16x16x32_bf16 v[6:9], v[190:193], v[240:243], v[6:9]
	v_mfma_f32_16x16x32_bf16 v[2:5], v[198:201], v[240:243], v[2:5]
	v_mfma_f32_16x16x32_bf16 v[54:57], v[194:197], v[220:223], v[54:57]
	v_mfma_f32_16x16x32_bf16 v[50:53], v[212:215], v[220:223], v[50:53]
	v_mfma_f32_16x16x32_bf16 v[38:41], v[194:197], v[228:231], v[38:41]
	v_mfma_f32_16x16x32_bf16 v[34:37], v[212:215], v[228:231], v[34:37]
	v_mfma_f32_16x16x32_bf16 v[22:25], v[194:197], v[236:239], v[22:25]
	v_mfma_f32_16x16x32_bf16 v[18:21], v[212:215], v[236:239], v[18:21]
	v_mfma_f32_16x16x32_bf16 v[6:9], v[194:197], v[244:247], v[6:9]
	v_mfma_f32_16x16x32_bf16 v[2:5], v[212:215], v[244:247], v[2:5]
	s_setprio 0
	s_barrier
	s_add_i32 s44, 0, 0x18000
	v_add_u32_e32 v0, s44, v149
	s_add_i32 s45, 0, 0x1c000
	ds_read_b128 v[150:153], v0
	ds_read_b128 v[154:157], v0 offset:1024
	ds_read_b128 v[158:161], v0 offset:2048
	ds_read_b128 v[186:189], v0 offset:3072
	v_add_u32_e32 v0, s45, v149
	ds_read_b128 v[190:193], v0
	ds_read_b128 v[194:197], v0 offset:1024
	ds_read_b128 v[198:201], v0 offset:2048
	ds_read_b128 v[212:215], v0 offset:3072
	s_add_u32 s34, s34, 0x80000
	s_addc_u32 s35, s35, 0
	s_mov_b32 m0, s59
	v_lshl_add_u64 v[176:177], s[34:35], 0, v[130:131]
	ds_read_b128 v[216:219], v184 offset:32768
	global_load_lds_dwordx4 v[176:177], off
	ds_read_b128 v[220:223], v184 offset:33792
	ds_read_b128 v[224:227], v184 offset:34816
	v_lshl_add_u64 v[176:177], s[34:35], 0, v[134:135]
	s_mov_b32 m0, s60
	s_nop 0
	global_load_lds_dwordx4 v[176:177], off
	ds_read_b128 v[228:231], v184 offset:35840
	ds_read_b128 v[232:235], v184 offset:36864
	ds_read_b128 v[236:239], v184 offset:37888
	ds_read_b128 v[240:243], v184 offset:38912
	ds_read_b128 v[244:247], v184 offset:39936
	s_waitcnt vmcnt(8)
	s_waitcnt lgkmcnt(0)
	s_barrier
	s_setprio 1
	v_mfma_f32_16x16x32_bf16 v[126:129], v[150:153], v[216:219], v[126:129]
	v_mfma_f32_16x16x32_bf16 v[122:125], v[158:161], v[216:219], v[122:125]
	v_mfma_f32_16x16x32_bf16 v[110:113], v[150:153], v[224:227], v[110:113]
	v_mfma_f32_16x16x32_bf16 v[106:109], v[158:161], v[224:227], v[106:109]
	v_mfma_f32_16x16x32_bf16 v[94:97], v[150:153], v[232:235], v[94:97]
	v_mfma_f32_16x16x32_bf16 v[90:93], v[158:161], v[232:235], v[90:93]
	v_mfma_f32_16x16x32_bf16 v[78:81], v[150:153], v[240:243], v[78:81]
	v_mfma_f32_16x16x32_bf16 v[74:77], v[158:161], v[240:243], v[74:77]
	v_mfma_f32_16x16x32_bf16 v[126:129], v[154:157], v[220:223], v[126:129]
	v_mfma_f32_16x16x32_bf16 v[122:125], v[186:189], v[220:223], v[122:125]
	v_mfma_f32_16x16x32_bf16 v[110:113], v[154:157], v[228:231], v[110:113]
	v_mfma_f32_16x16x32_bf16 v[106:109], v[186:189], v[228:231], v[106:109]
	v_mfma_f32_16x16x32_bf16 v[94:97], v[154:157], v[236:239], v[94:97]
	v_mfma_f32_16x16x32_bf16 v[90:93], v[186:189], v[236:239], v[90:93]
	v_mfma_f32_16x16x32_bf16 v[78:81], v[154:157], v[244:247], v[78:81]
	v_mfma_f32_16x16x32_bf16 v[74:77], v[186:189], v[244:247], v[74:77]
	v_mfma_f32_16x16x32_bf16 v[118:121], v[190:193], v[216:219], v[118:121]
	v_mfma_f32_16x16x32_bf16 v[114:117], v[198:201], v[216:219], v[114:117]
	v_mfma_f32_16x16x32_bf16 v[102:105], v[190:193], v[224:227], v[102:105]
	v_mfma_f32_16x16x32_bf16 v[98:101], v[198:201], v[224:227], v[98:101]
	v_mfma_f32_16x16x32_bf16 v[86:89], v[190:193], v[232:235], v[86:89]
	v_mfma_f32_16x16x32_bf16 v[82:85], v[198:201], v[232:235], v[82:85]
	v_mfma_f32_16x16x32_bf16 v[70:73], v[190:193], v[240:243], v[70:73]
	v_mfma_f32_16x16x32_bf16 v[66:69], v[198:201], v[240:243], v[66:69]
	v_mfma_f32_16x16x32_bf16 v[118:121], v[194:197], v[220:223], v[118:121]
	v_mfma_f32_16x16x32_bf16 v[114:117], v[212:215], v[220:223], v[114:117]
	v_mfma_f32_16x16x32_bf16 v[102:105], v[194:197], v[228:231], v[102:105]
	v_mfma_f32_16x16x32_bf16 v[98:101], v[212:215], v[228:231], v[98:101]
	v_mfma_f32_16x16x32_bf16 v[86:89], v[194:197], v[236:239], v[86:89]
	v_mfma_f32_16x16x32_bf16 v[82:85], v[212:215], v[236:239], v[82:85]
	v_mfma_f32_16x16x32_bf16 v[70:73], v[194:197], v[244:247], v[70:73]
	v_mfma_f32_16x16x32_bf16 v[66:69], v[212:215], v[244:247], v[66:69]
	s_setprio 0
	s_barrier
; #define PG8_STAGE(bufoff, gbase, voff) do { _Pragma("unroll") for (int _i = 0; _i < 2; ++_i) \
;         __builtin_amdgcn_global_load_lds((const unsigned*)((const char*)(gbase) + (voff)[_i]), (LAS unsigned*)(lds + (bufoff) + ldsw + _i * 8192), 16, 0, 0); } while (0)
; #define PG8_LDA(dst, b, h) do { _Pragma("unroll") for (int m = 0; m < 4; ++m) _Pragma("unroll") for (int k = 0; k < 2; ++k) dst[m][k] = *(const LAS bf16x8*)(lds + PG8_SA(b, h) + aoff + m * 2048 + k * 1024); } while (0)
; #define PG8_MMA(ai, bj, At, Bt) do { __builtin_amdgcn_s_setprio(1); _Pragma("unroll") for (int m = 0; m < 4; ++m) _Pragma("unroll") for (int n = 0; n < 2; ++n) _Pragma("unroll") for (int k = 0; k < 2; ++k) \
;         acc[ai][bj][m][n] = __builtin_amdgcn_mfma_f32_16x16x32_bf16(Bt[n][k], At[m][k], acc[ai][bj][m][n], 0, 0, 0); __builtin_amdgcn_s_setprio(0); } while (0)
; #define PG8_WAIT_V(n) asm volatile("s_waitcnt vmcnt(" #n ")" ::: "memory")
; #define PG8_WAIT_L(n) asm volatile("s_waitcnt lgkmcnt(" #n ")" ::: "memory")
; #define PG8_BAR __builtin_amdgcn_s_barrier()
; #define PG8_SCHED __builtin_amdgcn_sched_barrier(0)
; template <class Epi>
; __device__ __forceinline__ void gemm_phase(LAS unsigned char* lds, const Gemm g, const StaticOrder& S, const Epi& E, const int tid) {
;     ...
;             PG8_LDA(At, 1, 1); PG8_STAGE(PG8_SB(1, 0), b3, voffB); PG8_STAGE(PG8_SB(1, 1), b3 + bhs, voffB); PG8_STAGE(PG8_SA(1, 0), a3, voffA);
;             PG8_WAIT_V(8); PG8_WAIT_L(0); PG8_BAR; PG8_MMA(1, 0, At, B0); PG8_MMA(1, 1, At, B1); PG8_BAR; PG8_SCHED;
;     ...
;         if (ALIGN_EPI) { if (wr == 0) PG8_BAR; }
	s_add_i32 s34, s44, s56
	v_lshl_add_u64 v[162:163], v[162:163], 0, s[70:71]
	s_mov_b32 m0, s34
	ds_read_b128 v[216:219], v184 offset:49152
	global_load_lds_dwordx4 v[162:163], off
	ds_read_b128 v[220:223], v184 offset:50176
	ds_read_b128 v[224:227], v184 offset:51200
	s_add_i32 m0, s34, 0x2000
	s_add_u32 s28, s28, 0x8080
	v_lshl_add_u64 v[162:163], v[248:249], 0, s[70:71]
	s_addc_u32 s29, s29, 0
	s_add_i32 s34, s45, s56
	global_load_lds_dwordx4 v[162:163], off
	ds_read_b128 v[228:231], v184 offset:52224
	ds_read_b128 v[232:235], v184 offset:53248
	v_lshl_add_u64 v[162:163], s[28:29], 0, v[132:133]
	s_mov_b32 m0, s34
	s_nop 0
	global_load_lds_dwordx4 v[162:163], off
	ds_read_b128 v[236:239], v184 offset:54272
	ds_read_b128 v[240:243], v184 offset:55296
	v_lshl_add_u64 v[162:163], s[28:29], 0, v[136:137]
	s_add_i32 m0, s34, 0x2000
	s_nop 0
	global_load_lds_dwordx4 v[162:163], off
	ds_read_b128 v[244:247], v184 offset:56320
	v_lshl_add_u64 v[162:163], v[172:173], 0, s[70:71]
	s_mov_b32 m0, s61
	s_nop 0
	global_load_lds_dwordx4 v[162:163], off
	v_lshl_add_u64 v[162:163], v[174:175], 0, s[70:71]
	s_mov_b32 m0, s62
	s_nop 0
	global_load_lds_dwordx4 v[162:163], off
	s_waitcnt vmcnt(8)
	s_waitcnt lgkmcnt(0)
	s_barrier
	s_setprio 1
	v_mfma_f32_16x16x32_bf16 v[62:65], v[150:153], v[216:219], v[62:65]
	v_mfma_f32_16x16x32_bf16 v[58:61], v[158:161], v[216:219], v[58:61]
	v_mfma_f32_16x16x32_bf16 v[46:49], v[150:153], v[224:227], v[46:49]
	v_mfma_f32_16x16x32_bf16 v[42:45], v[158:161], v[224:227], v[42:45]
	v_mfma_f32_16x16x32_bf16 v[30:33], v[150:153], v[232:235], v[30:33]
	v_mfma_f32_16x16x32_bf16 v[26:29], v[158:161], v[232:235], v[26:29]
	v_mfma_f32_16x16x32_bf16 v[14:17], v[150:153], v[240:243], v[14:17]
	v_mfma_f32_16x16x32_bf16 v[10:13], v[158:161], v[240:243], v[10:13]
	v_mfma_f32_16x16x32_bf16 v[62:65], v[154:157], v[220:223], v[62:65]
	v_mfma_f32_16x16x32_bf16 v[58:61], v[186:189], v[220:223], v[58:61]
	v_mfma_f32_16x16x32_bf16 v[46:49], v[154:157], v[228:231], v[46:49]
	v_mfma_f32_16x16x32_bf16 v[42:45], v[186:189], v[228:231], v[42:45]
	v_mfma_f32_16x16x32_bf16 v[30:33], v[154:157], v[236:239], v[30:33]
	v_mfma_f32_16x16x32_bf16 v[26:29], v[186:189], v[236:239], v[26:29]
	v_mfma_f32_16x16x32_bf16 v[14:17], v[154:157], v[244:247], v[14:17]
	v_mfma_f32_16x16x32_bf16 v[10:13], v[186:189], v[244:247], v[10:13]
	v_mfma_f32_16x16x32_bf16 v[54:57], v[190:193], v[216:219], v[54:57]
	v_mfma_f32_16x16x32_bf16 v[50:53], v[198:201], v[216:219], v[50:53]
	v_mfma_f32_16x16x32_bf16 v[38:41], v[190:193], v[224:227], v[38:41]
	v_mfma_f32_16x16x32_bf16 v[34:37], v[198:201], v[224:227], v[34:37]
	v_mfma_f32_16x16x32_bf16 v[22:25], v[190:193], v[232:235], v[22:25]
	v_mfma_f32_16x16x32_bf16 v[18:21], v[198:201], v[232:235], v[18:21]
	v_mfma_f32_16x16x32_bf16 v[6:9], v[190:193], v[240:243], v[6:9]
	v_mfma_f32_16x16x32_bf16 v[2:5], v[198:201], v[240:243], v[2:5]
	v_mfma_f32_16x16x32_bf16 v[54:57], v[194:197], v[220:223], v[54:57]
	v_mfma_f32_16x16x32_bf16 v[50:53], v[212:215], v[220:223], v[50:53]
	v_mfma_f32_16x16x32_bf16 v[38:41], v[194:197], v[228:231], v[38:41]
	v_mfma_f32_16x16x32_bf16 v[34:37], v[212:215], v[228:231], v[34:37]
	v_mfma_f32_16x16x32_bf16 v[22:25], v[194:197], v[236:239], v[22:25]
	v_mfma_f32_16x16x32_bf16 v[18:21], v[212:215], v[236:239], v[18:21]
	v_mfma_f32_16x16x32_bf16 v[6:9], v[194:197], v[244:247], v[6:9]
	v_mfma_f32_16x16x32_bf16 v[2:5], v[212:215], v[244:247], v[2:5]
	s_setprio 0
	s_barrier
	s_add_i32 s39, s39, 2
	s_add_u32 s37, s37, 0x100
	s_addc_u32 s38, s38, 0
	s_add_u32 s26, s26, 0x100
	s_addc_u32 s27, s27, 0
	s_cmp_gt_u32 s39, 29
	s_cbranch_scc0 .LBB0_546
	s_and_b64 vcc, exec, s[14:15]
	s_cbranch_vccz .LBB0_549
	s_barrier

; #define PG8_STAGE(bufoff, gbase, voff) do { _Pragma("unroll") for (int _i = 0; _i < 2; ++_i) \
;         __builtin_amdgcn_global_load_lds((const unsigned*)((const char*)(gbase) + (voff)[_i]), (LAS unsigned*)(lds + (bufoff) + ldsw + _i * 8192), 16, 0, 0); } while (0)
; #define PG8_LDA(dst, b, h) do { _Pragma("unroll") for (int m = 0; m < 4; ++m) _Pragma("unroll") for (int k = 0; k < 2; ++k) dst[m][k] = *(const LAS bf16x8*)(lds + PG8_SA(b, h) + aoff + m * 2048 + k * 1024); } while (0)
; #define PG8_LDB(dst, b, h) do { _Pragma("unroll") for (int n = 0; n < 2; ++n) _Pragma("unroll") for (int k = 0; k < 2; ++k) dst[n][k] = *(const LAS bf16x8*)(lds + PG8_SB(b, h) + boff + n * 2048 + k * 1024); } while (0)
; #define PG8_WAIT_V(n) asm volatile("s_waitcnt vmcnt(" #n ")" ::: "memory")
; #define PG8_WAIT_L(n) asm volatile("s_waitcnt lgkmcnt(" #n ")" ::: "memory")
; #define PG8_BAR __builtin_amdgcn_s_barrier()
; #define PG8_SCHED __builtin_amdgcn_sched_barrier(0)
; template <class Epi>
; __device__ __forceinline__ void gemm_phase(LAS unsigned char* lds, const Gemm g, const StaticOrder& S, const Epi& E, const int tid) {
;     ...
;             const bool last = (t == ntt - 2);
;             const bool s1 = Epi::TWO && (t >= nt), s2 = Epi::TWO && (t + 2 >= nt);
;             const char* a1 = (s1 ? cA2 + (size_t)(t - nt + 1) * kstep : cA + (size_t)(t + 1) * kstep);
;             const char* a2 = last ? nA : (s2 ? cA2 + (size_t)(t + 2 - nt) * kstep : cA + (size_t)(t + 2) * kstep);
;             const char* b2 = last ? nB : (s2 ? cB2 + (size_t)(t + 2 - nt) * kstep : cB + (size_t)(t + 2) * kstep);
;             const char* a3 = a2 + kstep; const char* b3 = b2 + kstep;
;             if constexpr (Epi::TWO) { if (t == nt) E.mid(acc, cur, wr, wc, fr, fq); }
;             if constexpr (SP2) {
;             PG8_LDB(B0, 0, 0); PG8_LDB(B1, 0, 1); PG8_SCHED; PG8_LDA(At, 0, 0); PG8_STAGE(PG8_SA(1, 1), a1 + hstep, voffA);
;             PG8_WAIT_V(8); PG8_WAIT_L(0); PG8_BAR; PG8_MMA(0, 0, At, B0); PG8_MMA(0, 1, At, B1); PG8_BAR; PG8_SCHED;
;             PG8_LDA(At, 0, 1); PG8_STAGE(PG8_SB(0, 0), b2, voffB); PG8_STAGE(PG8_SB(0, 1), b2 + bhs, voffB); PG8_STAGE(PG8_SA(0, 0), a2, voffA);
;             PG8_WAIT_V(8); PG8_WAIT_L(0); PG8_BAR; PG8_MMA(1, 0, At, B0); PG8_MMA(1, 1, At, B1); PG8_BAR; PG8_SCHED;
.LBB0_844:
	s_add_u32 s28, s26, 0xfff80080
	s_addc_u32 s29, s27, -1
	s_add_i32 s48, 0, 0x10000
	s_cmp_eq_u32 s47, 28
	s_cselect_b32 s31, s15, s29
	s_cselect_b32 s30, s43, s28
	v_add_u32_e32 v145, s48, v142
	s_cselect_b32 s29, s13, s46
	s_cselect_b32 s28, s44, s45
	s_add_i32 s50, 0, 0x14000
	ds_read_b128 v[146:149], v145
	ds_read_b128 v[150:153], v145 offset:1024
	ds_read_b128 v[154:157], v145 offset:2048
	ds_read_b128 v[158:161], v145 offset:3072
	v_add_u32_e32 v145, s50, v142
	ds_read_b128 v[162:165], v145
	ds_read_b128 v[166:169], v145 offset:1024
	ds_read_b128 v[178:181], v145 offset:2048
	ds_read_b128 v[182:185], v145 offset:3072
	v_lshl_add_u64 v[172:173], s[26:27], 0, v[138:139]
	s_add_i32 m0, s23, 0xc000
	ds_read_b128 v[186:189], v144
	global_load_lds_dwordx4 v[172:173], off
	ds_read_b128 v[190:193], v144 offset:1024
	ds_read_b128 v[194:197], v144 offset:2048
	v_lshl_add_u64 v[172:173], s[26:27], 0, v[136:137]
	s_add_i32 m0, s23, 0xe000
	s_nop 0
	global_load_lds_dwordx4 v[172:173], off
	ds_read_b128 v[198:201], v144 offset:3072
	ds_read_b128 v[212:215], v144 offset:4096
	ds_read_b128 v[216:219], v144 offset:5120
	ds_read_b128 v[220:223], v144 offset:6144
	ds_read_b128 v[224:227], v144 offset:7168
	s_waitcnt vmcnt(8)
	s_waitcnt lgkmcnt(0)
	s_barrier
	s_setprio 1
	v_mfma_f32_16x16x32_bf16 v[126:129], v[146:149], v[186:189], v[126:129]
	v_mfma_f32_16x16x32_bf16 v[122:125], v[154:157], v[186:189], v[122:125]
	v_mfma_f32_16x16x32_bf16 v[118:121], v[146:149], v[194:197], v[118:121]
	v_mfma_f32_16x16x32_bf16 v[110:113], v[154:157], v[194:197], v[110:113]
	v_mfma_f32_16x16x32_bf16 v[102:105], v[146:149], v[212:215], v[102:105]
	v_mfma_f32_16x16x32_bf16 v[94:97], v[154:157], v[212:215], v[94:97]
	v_mfma_f32_16x16x32_bf16 v[86:89], v[146:149], v[220:223], v[86:89]
	v_mfma_f32_16x16x32_bf16 v[78:81], v[154:157], v[220:223], v[78:81]
	v_mfma_f32_16x16x32_bf16 v[126:129], v[150:153], v[190:193], v[126:129]
	v_mfma_f32_16x16x32_bf16 v[122:125], v[158:161], v[190:193], v[122:125]
	v_mfma_f32_16x16x32_bf16 v[118:121], v[150:153], v[198:201], v[118:121]
	v_mfma_f32_16x16x32_bf16 v[110:113], v[158:161], v[198:201], v[110:113]
	v_mfma_f32_16x16x32_bf16 v[102:105], v[150:153], v[216:219], v[102:105]
	v_mfma_f32_16x16x32_bf16 v[94:97], v[158:161], v[216:219], v[94:97]
	v_mfma_f32_16x16x32_bf16 v[86:89], v[150:153], v[224:227], v[86:89]
	v_mfma_f32_16x16x32_bf16 v[78:81], v[158:161], v[224:227], v[78:81]
	v_mfma_f32_16x16x32_bf16 v[114:117], v[162:165], v[186:189], v[114:117]
	v_mfma_f32_16x16x32_bf16 v[106:109], v[178:181], v[186:189], v[106:109]
	v_mfma_f32_16x16x32_bf16 v[98:101], v[162:165], v[194:197], v[98:101]
	v_mfma_f32_16x16x32_bf16 v[90:93], v[178:181], v[194:197], v[90:93]
	v_mfma_f32_16x16x32_bf16 v[82:85], v[162:165], v[212:215], v[82:85]
	v_mfma_f32_16x16x32_bf16 v[74:77], v[178:181], v[212:215], v[74:77]
	v_mfma_f32_16x16x32_bf16 v[70:73], v[162:165], v[220:223], v[70:73]
	v_mfma_f32_16x16x32_bf16 v[66:69], v[178:181], v[220:223], v[66:69]
	v_mfma_f32_16x16x32_bf16 v[114:117], v[166:169], v[190:193], v[114:117]
	v_mfma_f32_16x16x32_bf16 v[106:109], v[182:185], v[190:193], v[106:109]
	v_mfma_f32_16x16x32_bf16 v[98:101], v[166:169], v[198:201], v[98:101]
	v_mfma_f32_16x16x32_bf16 v[90:93], v[182:185], v[198:201], v[90:93]
	v_mfma_f32_16x16x32_bf16 v[82:85], v[166:169], v[216:219], v[82:85]
	v_mfma_f32_16x16x32_bf16 v[74:77], v[182:185], v[216:219], v[74:77]
	v_mfma_f32_16x16x32_bf16 v[70:73], v[166:169], v[224:227], v[70:73]
	v_mfma_f32_16x16x32_bf16 v[66:69], v[182:185], v[224:227], v[66:69]
	s_setprio 0
	s_barrier
	s_add_i32 s48, s48, s37
	v_lshl_add_u64 v[172:173], s[28:29], 0, v[0:1]
	s_mov_b32 m0, s48
	ds_read_b128 v[186:189], v144 offset:16384
	global_load_lds_dwordx4 v[172:173], off
	ds_read_b128 v[190:193], v144 offset:17408
	ds_read_b128 v[194:197], v144 offset:18432
	s_add_i32 m0, s48, 0x2000
	s_add_u32 s48, s28, 0x8000
	v_lshl_add_u64 v[174:175], s[28:29], 0, v[134:135]
	s_addc_u32 s49, s29, 0
	s_add_i32 s50, s50, s37
	global_load_lds_dwordx4 v[174:175], off
	ds_read_b128 v[198:201], v144 offset:19456
	ds_read_b128 v[212:215], v144 offset:20480
	v_lshl_add_u64 v[176:177], s[48:49], 0, v[0:1]
	s_mov_b32 m0, s50
	v_lshl_add_u64 v[228:229], s[30:31], 0, v[132:133]
	global_load_lds_dwordx4 v[176:177], off
	ds_read_b128 v[216:219], v144 offset:21504
	ds_read_b128 v[220:223], v144 offset:22528
	v_lshl_add_u64 v[176:177], s[48:49], 0, v[134:135]
	s_add_i32 m0, s50, 0x2000
	s_nop 0
	global_load_lds_dwordx4 v[176:177], off
	ds_read_b128 v[224:227], v144 offset:23552
	v_lshl_add_u64 v[176:177], s[30:31], 0, v[130:131]
	s_mov_b32 m0, s23
	s_nop 0
	global_load_lds_dwordx4 v[176:177], off
	s_mov_b32 m0, s25
	s_nop 0
	global_load_lds_dwordx4 v[228:229], off
	s_waitcnt vmcnt(8)
	s_waitcnt lgkmcnt(0)
	s_barrier
; #define PG8_STAGE(bufoff, gbase, voff) do { _Pragma("unroll") for (int _i = 0; _i < 2; ++_i) \
;         __builtin_amdgcn_global_load_lds((const unsigned*)((const char*)(gbase) + (voff)[_i]), (LAS unsigned*)(lds + (bufoff) + ldsw + _i * 8192), 16, 0, 0); } while (0)
; #define PG8_LDA(dst, b, h) do { _Pragma("unroll") for (int m = 0; m < 4; ++m) _Pragma("unroll") for (int k = 0; k < 2; ++k) dst[m][k] = *(const LAS bf16x8*)(lds + PG8_SA(b, h) + aoff + m * 2048 + k * 1024); } while (0)
; #define PG8_LDB(dst, b, h) do { _Pragma("unroll") for (int n = 0; n < 2; ++n) _Pragma("unroll") for (int k = 0; k < 2; ++k) dst[n][k] = *(const LAS bf16x8*)(lds + PG8_SB(b, h) + boff + n * 2048 + k * 1024); } while (0)
; #define PG8_MMA(ai, bj, At, Bt) do { __builtin_amdgcn_s_setprio(1); _Pragma("unroll") for (int m = 0; m < 4; ++m) _Pragma("unroll") for (int n = 0; n < 2; ++n) _Pragma("unroll") for (int k = 0; k < 2; ++k) \
;         acc[ai][bj][m][n] = __builtin_amdgcn_mfma_f32_16x16x32_bf16(Bt[n][k], At[m][k], acc[ai][bj][m][n], 0, 0, 0); __builtin_amdgcn_s_setprio(0); } while (0)
; #define PG8_WAIT_V(n) asm volatile("s_waitcnt vmcnt(" #n ")" ::: "memory")
; #define PG8_WAIT_L(n) asm volatile("s_waitcnt lgkmcnt(" #n ")" ::: "memory")
; #define PG8_BAR __builtin_amdgcn_s_barrier()
; #define PG8_SCHED __builtin_amdgcn_sched_barrier(0)
; template <class Epi>
; __device__ __forceinline__ void gemm_phase(LAS unsigned char* lds, const Gemm g, const StaticOrder& S, const Epi& E, const int tid) {
;     ...
;             PG8_WAIT_V(8); PG8_WAIT_L(0); PG8_BAR; PG8_MMA(1, 0, At, B0); PG8_MMA(1, 1, At, B1); PG8_BAR; PG8_SCHED;
;             PG8_LDB(B0, 1, 0); PG8_LDB(B1, 1, 1); PG8_SCHED; PG8_LDA(At, 1, 0); PG8_STAGE(PG8_SA(0, 1), a2 + hstep, voffA);
;             PG8_WAIT_V(8); PG8_WAIT_L(0); PG8_BAR; PG8_MMA(0, 0, At, B0); PG8_MMA(0, 1, At, B1); PG8_BAR; PG8_SCHED;
	s_setprio 1
	v_mfma_f32_16x16x32_bf16 v[62:65], v[146:149], v[186:189], v[62:65]
	v_mfma_f32_16x16x32_bf16 v[58:61], v[154:157], v[186:189], v[58:61]
	v_mfma_f32_16x16x32_bf16 v[54:57], v[146:149], v[194:197], v[54:57]
	v_mfma_f32_16x16x32_bf16 v[46:49], v[154:157], v[194:197], v[46:49]
	v_mfma_f32_16x16x32_bf16 v[38:41], v[146:149], v[212:215], v[38:41]
	v_mfma_f32_16x16x32_bf16 v[30:33], v[154:157], v[212:215], v[30:33]
	v_mfma_f32_16x16x32_bf16 v[22:25], v[146:149], v[220:223], v[22:25]
	v_mfma_f32_16x16x32_bf16 v[14:17], v[154:157], v[220:223], v[14:17]
	v_mfma_f32_16x16x32_bf16 v[62:65], v[150:153], v[190:193], v[62:65]
	v_mfma_f32_16x16x32_bf16 v[58:61], v[158:161], v[190:193], v[58:61]
	v_mfma_f32_16x16x32_bf16 v[54:57], v[150:153], v[198:201], v[54:57]
	v_mfma_f32_16x16x32_bf16 v[46:49], v[158:161], v[198:201], v[46:49]
	v_mfma_f32_16x16x32_bf16 v[38:41], v[150:153], v[216:219], v[38:41]
	v_mfma_f32_16x16x32_bf16 v[30:33], v[158:161], v[216:219], v[30:33]
	v_mfma_f32_16x16x32_bf16 v[22:25], v[150:153], v[224:227], v[22:25]
	v_mfma_f32_16x16x32_bf16 v[14:17], v[158:161], v[224:227], v[14:17]
	v_mfma_f32_16x16x32_bf16 v[50:53], v[162:165], v[186:189], v[50:53]
	v_mfma_f32_16x16x32_bf16 v[42:45], v[178:181], v[186:189], v[42:45]
	v_mfma_f32_16x16x32_bf16 v[34:37], v[162:165], v[194:197], v[34:37]
	v_mfma_f32_16x16x32_bf16 v[26:29], v[178:181], v[194:197], v[26:29]
	v_mfma_f32_16x16x32_bf16 v[18:21], v[162:165], v[212:215], v[18:21]
	v_mfma_f32_16x16x32_bf16 v[10:13], v[178:181], v[212:215], v[10:13]
	v_mfma_f32_16x16x32_bf16 v[6:9], v[162:165], v[220:223], v[6:9]
	v_mfma_f32_16x16x32_bf16 v[2:5], v[178:181], v[220:223], v[2:5]
	v_mfma_f32_16x16x32_bf16 v[50:53], v[166:169], v[190:193], v[50:53]
	v_mfma_f32_16x16x32_bf16 v[42:45], v[182:185], v[190:193], v[42:45]
	v_mfma_f32_16x16x32_bf16 v[34:37], v[166:169], v[198:201], v[34:37]
	v_mfma_f32_16x16x32_bf16 v[26:29], v[182:185], v[198:201], v[26:29]
	v_mfma_f32_16x16x32_bf16 v[18:21], v[166:169], v[216:219], v[18:21]
	v_mfma_f32_16x16x32_bf16 v[10:13], v[182:185], v[216:219], v[10:13]
	v_mfma_f32_16x16x32_bf16 v[6:9], v[166:169], v[224:227], v[6:9]
	v_mfma_f32_16x16x32_bf16 v[2:5], v[182:185], v[224:227], v[2:5]
	s_setprio 0
	s_barrier
	s_add_i32 s48, 0, 0x18000
	v_add_u32_e32 v145, s48, v142
	s_add_i32 s49, 0, 0x1c000
	ds_read_b128 v[146:149], v145
	ds_read_b128 v[150:153], v145 offset:1024
	ds_read_b128 v[154:157], v145 offset:2048
	ds_read_b128 v[158:161], v145 offset:3072
	v_add_u32_e32 v145, s49, v142
	ds_read_b128 v[162:165], v145
	ds_read_b128 v[166:169], v145 offset:1024
	ds_read_b128 v[178:181], v145 offset:2048
	ds_read_b128 v[182:185], v145 offset:3072
	s_add_u32 s30, s30, 0x80000
	s_addc_u32 s31, s31, 0
	s_mov_b32 m0, s38
	v_lshl_add_u64 v[230:231], s[30:31], 0, v[130:131]
	ds_read_b128 v[186:189], v144 offset:32768
	global_load_lds_dwordx4 v[230:231], off
	ds_read_b128 v[190:193], v144 offset:33792
	ds_read_b128 v[194:197], v144 offset:34816
	v_lshl_add_u64 v[230:231], s[30:31], 0, v[132:133]
	s_mov_b32 m0, s39
	s_nop 0
	global_load_lds_dwordx4 v[230:231], off
	ds_read_b128 v[198:201], v144 offset:35840
	ds_read_b128 v[212:215], v144 offset:36864
	ds_read_b128 v[216:219], v144 offset:37888
	ds_read_b128 v[220:223], v144 offset:38912
	ds_read_b128 v[224:227], v144 offset:39936
	s_waitcnt vmcnt(8)
	s_waitcnt lgkmcnt(0)
	s_barrier
	s_setprio 1
	v_mfma_f32_16x16x32_bf16 v[126:129], v[146:149], v[186:189], v[126:129]
	v_mfma_f32_16x16x32_bf16 v[122:125], v[154:157], v[186:189], v[122:125]
	v_mfma_f32_16x16x32_bf16 v[118:121], v[146:149], v[194:197], v[118:121]
	v_mfma_f32_16x16x32_bf16 v[110:113], v[154:157], v[194:197], v[110:113]
	v_mfma_f32_16x16x32_bf16 v[102:105], v[146:149], v[212:215], v[102:105]
	v_mfma_f32_16x16x32_bf16 v[94:97], v[154:157], v[212:215], v[94:97]
	v_mfma_f32_16x16x32_bf16 v[86:89], v[146:149], v[220:223], v[86:89]
	v_mfma_f32_16x16x32_bf16 v[78:81], v[154:157], v[220:223], v[78:81]
	v_mfma_f32_16x16x32_bf16 v[126:129], v[150:153], v[190:193], v[126:129]
	v_mfma_f32_16x16x32_bf16 v[122:125], v[158:161], v[190:193], v[122:125]
	v_mfma_f32_16x16x32_bf16 v[118:121], v[150:153], v[198:201], v[118:121]
	v_mfma_f32_16x16x32_bf16 v[110:113], v[158:161], v[198:201], v[110:113]
	v_mfma_f32_16x16x32_bf16 v[102:105], v[150:153], v[216:219], v[102:105]
	v_mfma_f32_16x16x32_bf16 v[94:97], v[158:161], v[216:219], v[94:97]
	v_mfma_f32_16x16x32_bf16 v[86:89], v[150:153], v[224:227], v[86:89]
	v_mfma_f32_16x16x32_bf16 v[78:81], v[158:161], v[224:227], v[78:81]
	v_mfma_f32_16x16x32_bf16 v[114:117], v[162:165], v[186:189], v[114:117]
	v_mfma_f32_16x16x32_bf16 v[106:109], v[178:181], v[186:189], v[106:109]
	v_mfma_f32_16x16x32_bf16 v[98:101], v[162:165], v[194:197], v[98:101]
	v_mfma_f32_16x16x32_bf16 v[90:93], v[178:181], v[194:197], v[90:93]
	v_mfma_f32_16x16x32_bf16 v[82:85], v[162:165], v[212:215], v[82:85]
	v_mfma_f32_16x16x32_bf16 v[74:77], v[178:181], v[212:215], v[74:77]
	v_mfma_f32_16x16x32_bf16 v[70:73], v[162:165], v[220:223], v[70:73]
	v_mfma_f32_16x16x32_bf16 v[66:69], v[178:181], v[220:223], v[66:69]
	v_mfma_f32_16x16x32_bf16 v[114:117], v[166:169], v[190:193], v[114:117]
	v_mfma_f32_16x16x32_bf16 v[106:109], v[182:185], v[190:193], v[106:109]
	v_mfma_f32_16x16x32_bf16 v[98:101], v[166:169], v[198:201], v[98:101]
	v_mfma_f32_16x16x32_bf16 v[90:93], v[182:185], v[198:201], v[90:93]
	v_mfma_f32_16x16x32_bf16 v[82:85], v[166:169], v[216:219], v[82:85]
	v_mfma_f32_16x16x32_bf16 v[74:77], v[182:185], v[216:219], v[74:77]
	v_mfma_f32_16x16x32_bf16 v[70:73], v[166:169], v[224:227], v[70:73]
	v_mfma_f32_16x16x32_bf16 v[66:69], v[182:185], v[224:227], v[66:69]
	s_setprio 0
	s_barrier
; #define PG8_STAGE(bufoff, gbase, voff) do { _Pragma("unroll") for (int _i = 0; _i < 2; ++_i) \
;         __builtin_amdgcn_global_load_lds((const unsigned*)((const char*)(gbase) + (voff)[_i]), (LAS unsigned*)(lds + (bufoff) + ldsw + _i * 8192), 16, 0, 0); } while (0)
; #define PG8_LDA(dst, b, h) do { _Pragma("unroll") for (int m = 0; m < 4; ++m) _Pragma("unroll") for (int k = 0; k < 2; ++k) dst[m][k] = *(const LAS bf16x8*)(lds + PG8_SA(b, h) + aoff + m * 2048 + k * 1024); } while (0)
; #define PG8_MMA(ai, bj, At, Bt) do { __builtin_amdgcn_s_setprio(1); _Pragma("unroll") for (int m = 0; m < 4; ++m) _Pragma("unroll") for (int n = 0; n < 2; ++n) _Pragma("unroll") for (int k = 0; k < 2; ++k) \
;         acc[ai][bj][m][n] = __builtin_amdgcn_mfma_f32_16x16x32_bf16(Bt[n][k], At[m][k], acc[ai][bj][m][n], 0, 0, 0); __builtin_amdgcn_s_setprio(0); } while (0)
; #define PG8_WAIT_V(n) asm volatile("s_waitcnt vmcnt(" #n ")" ::: "memory")
; #define PG8_WAIT_L(n) asm volatile("s_waitcnt lgkmcnt(" #n ")" ::: "memory")
; #define PG8_BAR __builtin_amdgcn_s_barrier()
; #define PG8_SCHED __builtin_amdgcn_sched_barrier(0)
; template <class Epi>
; __device__ __forceinline__ void gemm_phase(LAS unsigned char* lds, const Gemm g, const StaticOrder& S, const Epi& E, const int tid) {
;     ...
;             PG8_LDA(At, 1, 1); PG8_STAGE(PG8_SB(1, 0), b3, voffB); PG8_STAGE(PG8_SB(1, 1), b3 + bhs, voffB); PG8_STAGE(PG8_SA(1, 0), a3, voffA);
;             PG8_WAIT_V(8); PG8_WAIT_L(0); PG8_BAR; PG8_MMA(1, 0, At, B0); PG8_MMA(1, 1, At, B1); PG8_BAR; PG8_SCHED;
;     ...
;         if (ALIGN_EPI) { if (wr == 0) PG8_BAR; }
	s_add_i32 s30, s48, s37
	v_lshl_add_u64 v[172:173], v[172:173], 0, s[70:71]
	s_mov_b32 m0, s30
	ds_read_b128 v[186:189], v144 offset:49152
	global_load_lds_dwordx4 v[172:173], off
	ds_read_b128 v[190:193], v144 offset:50176
	ds_read_b128 v[194:197], v144 offset:51200
	s_add_i32 m0, s30, 0x2000
	s_add_u32 s28, s28, 0x8080
	v_lshl_add_u64 v[172:173], v[174:175], 0, s[70:71]
	s_addc_u32 s29, s29, 0
	s_add_i32 s30, s49, s37
	global_load_lds_dwordx4 v[172:173], off
	ds_read_b128 v[198:201], v144 offset:52224
	ds_read_b128 v[212:215], v144 offset:53248
	v_lshl_add_u64 v[172:173], s[28:29], 0, v[0:1]
	s_mov_b32 m0, s30
	s_nop 0
	global_load_lds_dwordx4 v[172:173], off
	ds_read_b128 v[216:219], v144 offset:54272
	ds_read_b128 v[220:223], v144 offset:55296
	v_lshl_add_u64 v[172:173], s[28:29], 0, v[134:135]
	s_add_i32 m0, s30, 0x2000
	s_nop 0
	global_load_lds_dwordx4 v[172:173], off
	ds_read_b128 v[224:227], v144 offset:56320
	v_lshl_add_u64 v[172:173], v[176:177], 0, s[70:71]
	s_mov_b32 m0, s40
	s_nop 0
	global_load_lds_dwordx4 v[172:173], off
	v_lshl_add_u64 v[172:173], v[228:229], 0, s[70:71]
	s_mov_b32 m0, s41
	s_nop 0
	global_load_lds_dwordx4 v[172:173], off
	s_waitcnt vmcnt(8)
	s_waitcnt lgkmcnt(0)
	s_barrier
	s_setprio 1
	v_mfma_f32_16x16x32_bf16 v[62:65], v[146:149], v[186:189], v[62:65]
	v_mfma_f32_16x16x32_bf16 v[58:61], v[154:157], v[186:189], v[58:61]
	v_mfma_f32_16x16x32_bf16 v[54:57], v[146:149], v[194:197], v[54:57]
	v_mfma_f32_16x16x32_bf16 v[46:49], v[154:157], v[194:197], v[46:49]
	v_mfma_f32_16x16x32_bf16 v[38:41], v[146:149], v[212:215], v[38:41]
	v_mfma_f32_16x16x32_bf16 v[30:33], v[154:157], v[212:215], v[30:33]
	v_mfma_f32_16x16x32_bf16 v[22:25], v[146:149], v[220:223], v[22:25]
	v_mfma_f32_16x16x32_bf16 v[14:17], v[154:157], v[220:223], v[14:17]
	v_mfma_f32_16x16x32_bf16 v[62:65], v[150:153], v[190:193], v[62:65]
	v_mfma_f32_16x16x32_bf16 v[58:61], v[158:161], v[190:193], v[58:61]
	v_mfma_f32_16x16x32_bf16 v[54:57], v[150:153], v[198:201], v[54:57]
	v_mfma_f32_16x16x32_bf16 v[46:49], v[158:161], v[198:201], v[46:49]
	v_mfma_f32_16x16x32_bf16 v[38:41], v[150:153], v[216:219], v[38:41]
	v_mfma_f32_16x16x32_bf16 v[30:33], v[158:161], v[216:219], v[30:33]
	v_mfma_f32_16x16x32_bf16 v[22:25], v[150:153], v[224:227], v[22:25]
	v_mfma_f32_16x16x32_bf16 v[14:17], v[158:161], v[224:227], v[14:17]
	v_mfma_f32_16x16x32_bf16 v[50:53], v[162:165], v[186:189], v[50:53]
	v_mfma_f32_16x16x32_bf16 v[42:45], v[178:181], v[186:189], v[42:45]
	v_mfma_f32_16x16x32_bf16 v[34:37], v[162:165], v[194:197], v[34:37]
	v_mfma_f32_16x16x32_bf16 v[26:29], v[178:181], v[194:197], v[26:29]
	v_mfma_f32_16x16x32_bf16 v[18:21], v[162:165], v[212:215], v[18:21]
	v_mfma_f32_16x16x32_bf16 v[10:13], v[178:181], v[212:215], v[10:13]
	v_mfma_f32_16x16x32_bf16 v[6:9], v[162:165], v[220:223], v[6:9]
	v_mfma_f32_16x16x32_bf16 v[2:5], v[178:181], v[220:223], v[2:5]
	v_mfma_f32_16x16x32_bf16 v[50:53], v[166:169], v[190:193], v[50:53]
	v_mfma_f32_16x16x32_bf16 v[42:45], v[182:185], v[190:193], v[42:45]
	v_mfma_f32_16x16x32_bf16 v[34:37], v[166:169], v[198:201], v[34:37]
	v_mfma_f32_16x16x32_bf16 v[26:29], v[182:185], v[198:201], v[26:29]
	v_mfma_f32_16x16x32_bf16 v[18:21], v[166:169], v[216:219], v[18:21]
	v_mfma_f32_16x16x32_bf16 v[10:13], v[182:185], v[216:219], v[10:13]
	v_mfma_f32_16x16x32_bf16 v[6:9], v[166:169], v[224:227], v[6:9]
	v_mfma_f32_16x16x32_bf16 v[2:5], v[182:185], v[224:227], v[2:5]
	s_setprio 0
	s_barrier
	s_add_i32 s47, s47, 2
	s_add_u32 s45, s45, 0x100
	s_addc_u32 s46, s46, 0
	s_add_u32 s26, s26, 0x100
	s_addc_u32 s27, s27, 0
	s_cmp_gt_u32 s47, 29
	s_cbranch_scc0 .LBB0_844
	s_and_b64 vcc, exec, s[10:11]
	s_cbranch_vccz .LBB0_847
	s_barrier

; #define PG8_STAGE(bufoff, gbase, voff) do { _Pragma("unroll") for (int _i = 0; _i < 2; ++_i) \
;         __builtin_amdgcn_global_load_lds((const unsigned*)((const char*)(gbase) + (voff)[_i]), (LAS unsigned*)(lds + (bufoff) + ldsw + _i * 8192), 16, 0, 0); } while (0)
; #define PG8_LDA(dst, b, h) do { _Pragma("unroll") for (int m = 0; m < 4; ++m) _Pragma("unroll") for (int k = 0; k < 2; ++k) dst[m][k] = *(const LAS bf16x8*)(lds + PG8_SA(b, h) + aoff + m * 2048 + k * 1024); } while (0)
; #define PG8_LDB(dst, b, h) do { _Pragma("unroll") for (int n = 0; n < 2; ++n) _Pragma("unroll") for (int k = 0; k < 2; ++k) dst[n][k] = *(const LAS bf16x8*)(lds + PG8_SB(b, h) + boff + n * 2048 + k * 1024); } while (0)
; #define PG8_WAIT_V(n) asm volatile("s_waitcnt vmcnt(" #n ")" ::: "memory")
; #define PG8_WAIT_L(n) asm volatile("s_waitcnt lgkmcnt(" #n ")" ::: "memory")
; #define PG8_BAR __builtin_amdgcn_s_barrier()
; #define PG8_SCHED __builtin_amdgcn_sched_barrier(0)
; template <class Epi>
; __device__ __forceinline__ void gemm_phase(LAS unsigned char* lds, const Gemm g, const StaticOrder& S, const Epi& E, const int tid) {
;     ...
;             const bool last = (t == ntt - 2);
;             const bool s1 = Epi::TWO && (t >= nt), s2 = Epi::TWO && (t + 2 >= nt);
;             const char* a1 = (s1 ? cA2 + (size_t)(t - nt + 1) * kstep : cA + (size_t)(t + 1) * kstep);
;             const char* a2 = last ? nA : (s2 ? cA2 + (size_t)(t + 2 - nt) * kstep : cA + (size_t)(t + 2) * kstep);
;             const char* b2 = last ? nB : (s2 ? cB2 + (size_t)(t + 2 - nt) * kstep : cB + (size_t)(t + 2) * kstep);
;             const char* a3 = a2 + kstep; const char* b3 = b2 + kstep;
;             if constexpr (Epi::TWO) { if (t == nt) E.mid(acc, cur, wr, wc, fr, fq); }
;             if constexpr (SP2) {
;             PG8_LDB(B0, 0, 0); PG8_LDB(B1, 0, 1); PG8_SCHED; PG8_LDA(At, 0, 0); PG8_STAGE(PG8_SA(1, 1), a1 + hstep, voffA);
;             PG8_WAIT_V(8); PG8_WAIT_L(0); PG8_BAR; PG8_MMA(0, 0, At, B0); PG8_MMA(0, 1, At, B1); PG8_BAR; PG8_SCHED;
;             PG8_LDA(At, 0, 1); PG8_STAGE(PG8_SB(0, 0), b2, voffB); PG8_STAGE(PG8_SB(0, 1), b2 + bhs, voffB); PG8_STAGE(PG8_SA(0, 0), a2, voffA);
;             PG8_WAIT_V(8); PG8_WAIT_L(0); PG8_BAR; PG8_MMA(1, 0, At, B0); PG8_MMA(1, 1, At, B1); PG8_BAR; PG8_SCHED;
.LBB0_861:
	s_add_u32 s30, s28, 0xfff80080
	s_addc_u32 s31, s29, -1
	s_add_i32 s51, 0, 0x10000
	s_cmp_eq_u32 s50, 28
	s_cselect_b32 s35, s17, s31
	s_cselect_b32 s34, s46, s30
	v_add_u32_e32 v145, s51, v142
	s_cselect_b32 s31, s15, s49
	s_cselect_b32 s30, s47, s48
	s_add_i32 s54, 0, 0x14000
	ds_read_b128 v[146:149], v145
	ds_read_b128 v[150:153], v145 offset:1024
	ds_read_b128 v[154:157], v145 offset:2048
	ds_read_b128 v[158:161], v145 offset:3072
	v_add_u32_e32 v145, s54, v142
	ds_read_b128 v[162:165], v145
	ds_read_b128 v[166:169], v145 offset:1024
	ds_read_b128 v[178:181], v145 offset:2048
	ds_read_b128 v[182:185], v145 offset:3072
	v_lshl_add_u64 v[172:173], s[28:29], 0, v[138:139]
	s_add_i32 m0, s25, 0xc000
	ds_read_b128 v[186:189], v144
	global_load_lds_dwordx4 v[172:173], off
	ds_read_b128 v[190:193], v144 offset:1024
	ds_read_b128 v[194:197], v144 offset:2048
	v_lshl_add_u64 v[172:173], s[28:29], 0, v[136:137]
	s_add_i32 m0, s25, 0xe000
	s_nop 0
	global_load_lds_dwordx4 v[172:173], off
	ds_read_b128 v[198:201], v144 offset:3072
	ds_read_b128 v[212:215], v144 offset:4096
	ds_read_b128 v[216:219], v144 offset:5120
	ds_read_b128 v[220:223], v144 offset:6144
	ds_read_b128 v[224:227], v144 offset:7168
	s_waitcnt vmcnt(8)
	s_waitcnt lgkmcnt(0)
	s_barrier
	s_setprio 1
	v_mfma_f32_16x16x32_bf16 v[126:129], v[146:149], v[186:189], v[126:129]
	v_mfma_f32_16x16x32_bf16 v[122:125], v[154:157], v[186:189], v[122:125]
	v_mfma_f32_16x16x32_bf16 v[118:121], v[146:149], v[194:197], v[118:121]
	v_mfma_f32_16x16x32_bf16 v[110:113], v[154:157], v[194:197], v[110:113]
	v_mfma_f32_16x16x32_bf16 v[102:105], v[146:149], v[212:215], v[102:105]
	v_mfma_f32_16x16x32_bf16 v[94:97], v[154:157], v[212:215], v[94:97]
	v_mfma_f32_16x16x32_bf16 v[86:89], v[146:149], v[220:223], v[86:89]
	v_mfma_f32_16x16x32_bf16 v[78:81], v[154:157], v[220:223], v[78:81]
	v_mfma_f32_16x16x32_bf16 v[126:129], v[150:153], v[190:193], v[126:129]
	v_mfma_f32_16x16x32_bf16 v[122:125], v[158:161], v[190:193], v[122:125]
	v_mfma_f32_16x16x32_bf16 v[118:121], v[150:153], v[198:201], v[118:121]
	v_mfma_f32_16x16x32_bf16 v[110:113], v[158:161], v[198:201], v[110:113]
	v_mfma_f32_16x16x32_bf16 v[102:105], v[150:153], v[216:219], v[102:105]
	v_mfma_f32_16x16x32_bf16 v[94:97], v[158:161], v[216:219], v[94:97]
	v_mfma_f32_16x16x32_bf16 v[86:89], v[150:153], v[224:227], v[86:89]
	v_mfma_f32_16x16x32_bf16 v[78:81], v[158:161], v[224:227], v[78:81]
	v_mfma_f32_16x16x32_bf16 v[114:117], v[162:165], v[186:189], v[114:117]
	v_mfma_f32_16x16x32_bf16 v[106:109], v[178:181], v[186:189], v[106:109]
	v_mfma_f32_16x16x32_bf16 v[98:101], v[162:165], v[194:197], v[98:101]
	v_mfma_f32_16x16x32_bf16 v[90:93], v[178:181], v[194:197], v[90:93]
	v_mfma_f32_16x16x32_bf16 v[82:85], v[162:165], v[212:215], v[82:85]
	v_mfma_f32_16x16x32_bf16 v[74:77], v[178:181], v[212:215], v[74:77]
	v_mfma_f32_16x16x32_bf16 v[70:73], v[162:165], v[220:223], v[70:73]
	v_mfma_f32_16x16x32_bf16 v[66:69], v[178:181], v[220:223], v[66:69]
	v_mfma_f32_16x16x32_bf16 v[114:117], v[166:169], v[190:193], v[114:117]
	v_mfma_f32_16x16x32_bf16 v[106:109], v[182:185], v[190:193], v[106:109]
	v_mfma_f32_16x16x32_bf16 v[98:101], v[166:169], v[198:201], v[98:101]
	v_mfma_f32_16x16x32_bf16 v[90:93], v[182:185], v[198:201], v[90:93]
	v_mfma_f32_16x16x32_bf16 v[82:85], v[166:169], v[216:219], v[82:85]
	v_mfma_f32_16x16x32_bf16 v[74:77], v[182:185], v[216:219], v[74:77]
	v_mfma_f32_16x16x32_bf16 v[70:73], v[166:169], v[224:227], v[70:73]
	v_mfma_f32_16x16x32_bf16 v[66:69], v[182:185], v[224:227], v[66:69]
	s_setprio 0
	s_barrier
	s_add_i32 s51, s51, s40
	v_lshl_add_u64 v[172:173], s[30:31], 0, v[0:1]
	s_mov_b32 m0, s51
	ds_read_b128 v[186:189], v144 offset:16384
	global_load_lds_dwordx4 v[172:173], off
	ds_read_b128 v[190:193], v144 offset:17408
	ds_read_b128 v[194:197], v144 offset:18432
	s_add_i32 m0, s51, 0x2000
	s_add_u32 s52, s30, 0x8000
	v_lshl_add_u64 v[174:175], s[30:31], 0, v[134:135]
	s_addc_u32 s53, s31, 0
	s_add_i32 s51, s54, s40
	global_load_lds_dwordx4 v[174:175], off
	ds_read_b128 v[198:201], v144 offset:19456
	ds_read_b128 v[212:215], v144 offset:20480
	v_lshl_add_u64 v[176:177], s[52:53], 0, v[0:1]
	s_mov_b32 m0, s51
	v_lshl_add_u64 v[228:229], s[34:35], 0, v[132:133]
	global_load_lds_dwordx4 v[176:177], off
	ds_read_b128 v[216:219], v144 offset:21504
	ds_read_b128 v[220:223], v144 offset:22528
	v_lshl_add_u64 v[176:177], s[52:53], 0, v[134:135]
	s_add_i32 m0, s51, 0x2000
	s_nop 0
	global_load_lds_dwordx4 v[176:177], off
	ds_read_b128 v[224:227], v144 offset:23552
	v_lshl_add_u64 v[176:177], s[34:35], 0, v[130:131]
	s_mov_b32 m0, s25
	s_nop 0
	global_load_lds_dwordx4 v[176:177], off
	s_mov_b32 m0, s27
	s_nop 0
	global_load_lds_dwordx4 v[228:229], off
	s_waitcnt vmcnt(8)
	s_waitcnt lgkmcnt(0)
	s_barrier
; #define PG8_STAGE(bufoff, gbase, voff) do { _Pragma("unroll") for (int _i = 0; _i < 2; ++_i) \
;         __builtin_amdgcn_global_load_lds((const unsigned*)((const char*)(gbase) + (voff)[_i]), (LAS unsigned*)(lds + (bufoff) + ldsw + _i * 8192), 16, 0, 0); } while (0)
; #define PG8_LDA(dst, b, h) do { _Pragma("unroll") for (int m = 0; m < 4; ++m) _Pragma("unroll") for (int k = 0; k < 2; ++k) dst[m][k] = *(const LAS bf16x8*)(lds + PG8_SA(b, h) + aoff + m * 2048 + k * 1024); } while (0)
; #define PG8_LDB(dst, b, h) do { _Pragma("unroll") for (int n = 0; n < 2; ++n) _Pragma("unroll") for (int k = 0; k < 2; ++k) dst[n][k] = *(const LAS bf16x8*)(lds + PG8_SB(b, h) + boff + n * 2048 + k * 1024); } while (0)
; #define PG8_MMA(ai, bj, At, Bt) do { __builtin_amdgcn_s_setprio(1); _Pragma("unroll") for (int m = 0; m < 4; ++m) _Pragma("unroll") for (int n = 0; n < 2; ++n) _Pragma("unroll") for (int k = 0; k < 2; ++k) \
;         acc[ai][bj][m][n] = __builtin_amdgcn_mfma_f32_16x16x32_bf16(Bt[n][k], At[m][k], acc[ai][bj][m][n], 0, 0, 0); __builtin_amdgcn_s_setprio(0); } while (0)
; #define PG8_WAIT_V(n) asm volatile("s_waitcnt vmcnt(" #n ")" ::: "memory")
; #define PG8_WAIT_L(n) asm volatile("s_waitcnt lgkmcnt(" #n ")" ::: "memory")
; #define PG8_BAR __builtin_amdgcn_s_barrier()
; #define PG8_SCHED __builtin_amdgcn_sched_barrier(0)
; template <class Epi>
; __device__ __forceinline__ void gemm_phase(LAS unsigned char* lds, const Gemm g, const StaticOrder& S, const Epi& E, const int tid) {
;     ...
;             PG8_WAIT_V(8); PG8_WAIT_L(0); PG8_BAR; PG8_MMA(1, 0, At, B0); PG8_MMA(1, 1, At, B1); PG8_BAR; PG8_SCHED;
;             PG8_LDB(B0, 1, 0); PG8_LDB(B1, 1, 1); PG8_SCHED; PG8_LDA(At, 1, 0); PG8_STAGE(PG8_SA(0, 1), a2 + hstep, voffA);
;             PG8_WAIT_V(8); PG8_WAIT_L(0); PG8_BAR; PG8_MMA(0, 0, At, B0); PG8_MMA(0, 1, At, B1); PG8_BAR; PG8_SCHED;
	s_setprio 1
	v_mfma_f32_16x16x32_bf16 v[62:65], v[146:149], v[186:189], v[62:65]
	v_mfma_f32_16x16x32_bf16 v[58:61], v[154:157], v[186:189], v[58:61]
	v_mfma_f32_16x16x32_bf16 v[54:57], v[146:149], v[194:197], v[54:57]
	v_mfma_f32_16x16x32_bf16 v[46:49], v[154:157], v[194:197], v[46:49]
	v_mfma_f32_16x16x32_bf16 v[38:41], v[146:149], v[212:215], v[38:41]
	v_mfma_f32_16x16x32_bf16 v[30:33], v[154:157], v[212:215], v[30:33]
	v_mfma_f32_16x16x32_bf16 v[22:25], v[146:149], v[220:223], v[22:25]
	v_mfma_f32_16x16x32_bf16 v[14:17], v[154:157], v[220:223], v[14:17]
	v_mfma_f32_16x16x32_bf16 v[62:65], v[150:153], v[190:193], v[62:65]
	v_mfma_f32_16x16x32_bf16 v[58:61], v[158:161], v[190:193], v[58:61]
	v_mfma_f32_16x16x32_bf16 v[54:57], v[150:153], v[198:201], v[54:57]
	v_mfma_f32_16x16x32_bf16 v[46:49], v[158:161], v[198:201], v[46:49]
	v_mfma_f32_16x16x32_bf16 v[38:41], v[150:153], v[216:219], v[38:41]
	v_mfma_f32_16x16x32_bf16 v[30:33], v[158:161], v[216:219], v[30:33]
	v_mfma_f32_16x16x32_bf16 v[22:25], v[150:153], v[224:227], v[22:25]
	v_mfma_f32_16x16x32_bf16 v[14:17], v[158:161], v[224:227], v[14:17]
	v_mfma_f32_16x16x32_bf16 v[50:53], v[162:165], v[186:189], v[50:53]
	v_mfma_f32_16x16x32_bf16 v[42:45], v[178:181], v[186:189], v[42:45]
	v_mfma_f32_16x16x32_bf16 v[34:37], v[162:165], v[194:197], v[34:37]
	v_mfma_f32_16x16x32_bf16 v[26:29], v[178:181], v[194:197], v[26:29]
	v_mfma_f32_16x16x32_bf16 v[18:21], v[162:165], v[212:215], v[18:21]
	v_mfma_f32_16x16x32_bf16 v[10:13], v[178:181], v[212:215], v[10:13]
	v_mfma_f32_16x16x32_bf16 v[6:9], v[162:165], v[220:223], v[6:9]
	v_mfma_f32_16x16x32_bf16 v[2:5], v[178:181], v[220:223], v[2:5]
	v_mfma_f32_16x16x32_bf16 v[50:53], v[166:169], v[190:193], v[50:53]
	v_mfma_f32_16x16x32_bf16 v[42:45], v[182:185], v[190:193], v[42:45]
	v_mfma_f32_16x16x32_bf16 v[34:37], v[166:169], v[198:201], v[34:37]
	v_mfma_f32_16x16x32_bf16 v[26:29], v[182:185], v[198:201], v[26:29]
	v_mfma_f32_16x16x32_bf16 v[18:21], v[166:169], v[216:219], v[18:21]
	v_mfma_f32_16x16x32_bf16 v[10:13], v[182:185], v[216:219], v[10:13]
	v_mfma_f32_16x16x32_bf16 v[6:9], v[166:169], v[224:227], v[6:9]
	v_mfma_f32_16x16x32_bf16 v[2:5], v[182:185], v[224:227], v[2:5]
	s_setprio 0
	s_barrier
	s_add_i32 s51, 0, 0x18000
	v_add_u32_e32 v145, s51, v142
	s_add_i32 s52, 0, 0x1c000
	ds_read_b128 v[146:149], v145
	ds_read_b128 v[150:153], v145 offset:1024
	ds_read_b128 v[154:157], v145 offset:2048
	ds_read_b128 v[158:161], v145 offset:3072
	v_add_u32_e32 v145, s52, v142
	ds_read_b128 v[162:165], v145
	ds_read_b128 v[166:169], v145 offset:1024
	ds_read_b128 v[178:181], v145 offset:2048
	ds_read_b128 v[182:185], v145 offset:3072
	s_add_u32 s34, s34, 0x80000
	s_addc_u32 s35, s35, 0
	s_mov_b32 m0, s41
	v_lshl_add_u64 v[230:231], s[34:35], 0, v[130:131]
	ds_read_b128 v[186:189], v144 offset:32768
	global_load_lds_dwordx4 v[230:231], off
	ds_read_b128 v[190:193], v144 offset:33792
	ds_read_b128 v[194:197], v144 offset:34816
	v_lshl_add_u64 v[230:231], s[34:35], 0, v[132:133]
	s_mov_b32 m0, s42
	s_nop 0
	global_load_lds_dwordx4 v[230:231], off
	ds_read_b128 v[198:201], v144 offset:35840
	ds_read_b128 v[212:215], v144 offset:36864
	ds_read_b128 v[216:219], v144 offset:37888
	ds_read_b128 v[220:223], v144 offset:38912
	ds_read_b128 v[224:227], v144 offset:39936
	s_waitcnt vmcnt(8)
	s_waitcnt lgkmcnt(0)
	s_barrier
	s_setprio 1
	v_mfma_f32_16x16x32_bf16 v[126:129], v[146:149], v[186:189], v[126:129]
	v_mfma_f32_16x16x32_bf16 v[122:125], v[154:157], v[186:189], v[122:125]
	v_mfma_f32_16x16x32_bf16 v[118:121], v[146:149], v[194:197], v[118:121]
	v_mfma_f32_16x16x32_bf16 v[110:113], v[154:157], v[194:197], v[110:113]
	v_mfma_f32_16x16x32_bf16 v[102:105], v[146:149], v[212:215], v[102:105]
	v_mfma_f32_16x16x32_bf16 v[94:97], v[154:157], v[212:215], v[94:97]
	v_mfma_f32_16x16x32_bf16 v[86:89], v[146:149], v[220:223], v[86:89]
	v_mfma_f32_16x16x32_bf16 v[78:81], v[154:157], v[220:223], v[78:81]
	v_mfma_f32_16x16x32_bf16 v[126:129], v[150:153], v[190:193], v[126:129]
	v_mfma_f32_16x16x32_bf16 v[122:125], v[158:161], v[190:193], v[122:125]
	v_mfma_f32_16x16x32_bf16 v[118:121], v[150:153], v[198:201], v[118:121]
	v_mfma_f32_16x16x32_bf16 v[110:113], v[158:161], v[198:201], v[110:113]
	v_mfma_f32_16x16x32_bf16 v[102:105], v[150:153], v[216:219], v[102:105]
	v_mfma_f32_16x16x32_bf16 v[94:97], v[158:161], v[216:219], v[94:97]
	v_mfma_f32_16x16x32_bf16 v[86:89], v[150:153], v[224:227], v[86:89]
	v_mfma_f32_16x16x32_bf16 v[78:81], v[158:161], v[224:227], v[78:81]
	v_mfma_f32_16x16x32_bf16 v[114:117], v[162:165], v[186:189], v[114:117]
	v_mfma_f32_16x16x32_bf16 v[106:109], v[178:181], v[186:189], v[106:109]
	v_mfma_f32_16x16x32_bf16 v[98:101], v[162:165], v[194:197], v[98:101]
	v_mfma_f32_16x16x32_bf16 v[90:93], v[178:181], v[194:197], v[90:93]
	v_mfma_f32_16x16x32_bf16 v[82:85], v[162:165], v[212:215], v[82:85]
	v_mfma_f32_16x16x32_bf16 v[74:77], v[178:181], v[212:215], v[74:77]
	v_mfma_f32_16x16x32_bf16 v[70:73], v[162:165], v[220:223], v[70:73]
	v_mfma_f32_16x16x32_bf16 v[66:69], v[178:181], v[220:223], v[66:69]
	v_mfma_f32_16x16x32_bf16 v[114:117], v[166:169], v[190:193], v[114:117]
	v_mfma_f32_16x16x32_bf16 v[106:109], v[182:185], v[190:193], v[106:109]
	v_mfma_f32_16x16x32_bf16 v[98:101], v[166:169], v[198:201], v[98:101]
	v_mfma_f32_16x16x32_bf16 v[90:93], v[182:185], v[198:201], v[90:93]
	v_mfma_f32_16x16x32_bf16 v[82:85], v[166:169], v[216:219], v[82:85]
	v_mfma_f32_16x16x32_bf16 v[74:77], v[182:185], v[216:219], v[74:77]
	v_mfma_f32_16x16x32_bf16 v[70:73], v[166:169], v[224:227], v[70:73]
	v_mfma_f32_16x16x32_bf16 v[66:69], v[182:185], v[224:227], v[66:69]
	s_setprio 0
	s_barrier
; #define PG8_STAGE(bufoff, gbase, voff) do { _Pragma("unroll") for (int _i = 0; _i < 2; ++_i) \
;         __builtin_amdgcn_global_load_lds((const unsigned*)((const char*)(gbase) + (voff)[_i]), (LAS unsigned*)(lds + (bufoff) + ldsw + _i * 8192), 16, 0, 0); } while (0)
; #define PG8_LDA(dst, b, h) do { _Pragma("unroll") for (int m = 0; m < 4; ++m) _Pragma("unroll") for (int k = 0; k < 2; ++k) dst[m][k] = *(const LAS bf16x8*)(lds + PG8_SA(b, h) + aoff + m * 2048 + k * 1024); } while (0)
; #define PG8_MMA(ai, bj, At, Bt) do { __builtin_amdgcn_s_setprio(1); _Pragma("unroll") for (int m = 0; m < 4; ++m) _Pragma("unroll") for (int n = 0; n < 2; ++n) _Pragma("unroll") for (int k = 0; k < 2; ++k) \
;         acc[ai][bj][m][n] = __builtin_amdgcn_mfma_f32_16x16x32_bf16(Bt[n][k], At[m][k], acc[ai][bj][m][n], 0, 0, 0); __builtin_amdgcn_s_setprio(0); } while (0)
; #define PG8_WAIT_V(n) asm volatile("s_waitcnt vmcnt(" #n ")" ::: "memory")
; #define PG8_WAIT_L(n) asm volatile("s_waitcnt lgkmcnt(" #n ")" ::: "memory")
; #define PG8_BAR __builtin_amdgcn_s_barrier()
; #define PG8_SCHED __builtin_amdgcn_sched_barrier(0)
; template <class Epi>
; __device__ __forceinline__ void gemm_phase(LAS unsigned char* lds, const Gemm g, const StaticOrder& S, const Epi& E, const int tid) {
;     ...
;             PG8_LDA(At, 1, 1); PG8_STAGE(PG8_SB(1, 0), b3, voffB); PG8_STAGE(PG8_SB(1, 1), b3 + bhs, voffB); PG8_STAGE(PG8_SA(1, 0), a3, voffA);
;             PG8_WAIT_V(8); PG8_WAIT_L(0); PG8_BAR; PG8_MMA(1, 0, At, B0); PG8_MMA(1, 1, At, B1); PG8_BAR; PG8_SCHED;
;     ...
;         if (ALIGN_EPI) { if (wr == 0) PG8_BAR; }
	s_add_i32 s34, s51, s40
	v_lshl_add_u64 v[172:173], v[172:173], 0, s[70:71]
	s_mov_b32 m0, s34
	ds_read_b128 v[186:189], v144 offset:49152
	global_load_lds_dwordx4 v[172:173], off
	ds_read_b128 v[190:193], v144 offset:50176
	ds_read_b128 v[194:197], v144 offset:51200
	s_add_i32 m0, s34, 0x2000
	s_add_u32 s30, s30, 0x8080
	v_lshl_add_u64 v[172:173], v[174:175], 0, s[70:71]
	s_addc_u32 s31, s31, 0
	s_add_i32 s34, s52, s40
	global_load_lds_dwordx4 v[172:173], off
	ds_read_b128 v[198:201], v144 offset:52224
	ds_read_b128 v[212:215], v144 offset:53248
	v_lshl_add_u64 v[172:173], s[30:31], 0, v[0:1]
	s_mov_b32 m0, s34
	s_nop 0
	global_load_lds_dwordx4 v[172:173], off
	ds_read_b128 v[216:219], v144 offset:54272
	ds_read_b128 v[220:223], v144 offset:55296
	v_lshl_add_u64 v[172:173], s[30:31], 0, v[134:135]
	s_add_i32 m0, s34, 0x2000
	s_nop 0
	global_load_lds_dwordx4 v[172:173], off
	ds_read_b128 v[224:227], v144 offset:56320
	v_lshl_add_u64 v[172:173], v[176:177], 0, s[70:71]
	s_mov_b32 m0, s43
	s_nop 0
	global_load_lds_dwordx4 v[172:173], off
	v_lshl_add_u64 v[172:173], v[228:229], 0, s[70:71]
	s_mov_b32 m0, s44
	s_nop 0
	global_load_lds_dwordx4 v[172:173], off
	s_waitcnt vmcnt(8)
	s_waitcnt lgkmcnt(0)
	s_barrier
	s_setprio 1
	v_mfma_f32_16x16x32_bf16 v[62:65], v[146:149], v[186:189], v[62:65]
	v_mfma_f32_16x16x32_bf16 v[58:61], v[154:157], v[186:189], v[58:61]
	v_mfma_f32_16x16x32_bf16 v[54:57], v[146:149], v[194:197], v[54:57]
	v_mfma_f32_16x16x32_bf16 v[46:49], v[154:157], v[194:197], v[46:49]
	v_mfma_f32_16x16x32_bf16 v[38:41], v[146:149], v[212:215], v[38:41]
	v_mfma_f32_16x16x32_bf16 v[30:33], v[154:157], v[212:215], v[30:33]
	v_mfma_f32_16x16x32_bf16 v[22:25], v[146:149], v[220:223], v[22:25]
	v_mfma_f32_16x16x32_bf16 v[14:17], v[154:157], v[220:223], v[14:17]
	v_mfma_f32_16x16x32_bf16 v[62:65], v[150:153], v[190:193], v[62:65]
	v_mfma_f32_16x16x32_bf16 v[58:61], v[158:161], v[190:193], v[58:61]
	v_mfma_f32_16x16x32_bf16 v[54:57], v[150:153], v[198:201], v[54:57]
	v_mfma_f32_16x16x32_bf16 v[46:49], v[158:161], v[198:201], v[46:49]
	v_mfma_f32_16x16x32_bf16 v[38:41], v[150:153], v[216:219], v[38:41]
	v_mfma_f32_16x16x32_bf16 v[30:33], v[158:161], v[216:219], v[30:33]
	v_mfma_f32_16x16x32_bf16 v[22:25], v[150:153], v[224:227], v[22:25]
	v_mfma_f32_16x16x32_bf16 v[14:17], v[158:161], v[224:227], v[14:17]
	v_mfma_f32_16x16x32_bf16 v[50:53], v[162:165], v[186:189], v[50:53]
	v_mfma_f32_16x16x32_bf16 v[42:45], v[178:181], v[186:189], v[42:45]
	v_mfma_f32_16x16x32_bf16 v[34:37], v[162:165], v[194:197], v[34:37]
	v_mfma_f32_16x16x32_bf16 v[26:29], v[178:181], v[194:197], v[26:29]
	v_mfma_f32_16x16x32_bf16 v[18:21], v[162:165], v[212:215], v[18:21]
	v_mfma_f32_16x16x32_bf16 v[10:13], v[178:181], v[212:215], v[10:13]
	v_mfma_f32_16x16x32_bf16 v[6:9], v[162:165], v[220:223], v[6:9]
	v_mfma_f32_16x16x32_bf16 v[2:5], v[178:181], v[220:223], v[2:5]
	v_mfma_f32_16x16x32_bf16 v[50:53], v[166:169], v[190:193], v[50:53]
	v_mfma_f32_16x16x32_bf16 v[42:45], v[182:185], v[190:193], v[42:45]
	v_mfma_f32_16x16x32_bf16 v[34:37], v[166:169], v[198:201], v[34:37]
	v_mfma_f32_16x16x32_bf16 v[26:29], v[182:185], v[198:201], v[26:29]
	v_mfma_f32_16x16x32_bf16 v[18:21], v[166:169], v[216:219], v[18:21]
	v_mfma_f32_16x16x32_bf16 v[10:13], v[182:185], v[216:219], v[10:13]
	v_mfma_f32_16x16x32_bf16 v[6:9], v[166:169], v[224:227], v[6:9]
	v_mfma_f32_16x16x32_bf16 v[2:5], v[182:185], v[224:227], v[2:5]
	s_setprio 0
	s_barrier
	s_add_i32 s50, s50, 2
	s_add_u32 s48, s48, 0x100
	s_addc_u32 s49, s49, 0
	s_add_u32 s28, s28, 0x100
	s_addc_u32 s29, s29, 0
	s_cmp_gt_u32 s50, 29
	s_cbranch_scc0 .LBB0_861
	s_and_b64 vcc, exec, s[12:13]
	s_cbranch_vccz .LBB0_864
	s_barrier
